# speedup vs baseline: 1.0024x; 1.0024x over previous
; #define WAIT_V(n) asm volatile("s_waitcnt vmcnt(" #n ")" ::: "memory")
; #define WAIT_L(n) asm volatile("s_waitcnt lgkmcnt(" #n ")" ::: "memory")
; #define BAR __builtin_amdgcn_s_barrier()
; #define SCHED __builtin_amdgcn_sched_barrier(0)
; #define STG_A(b, h, kt) stage_half_s(lds0 + ((b) * 2 + (h)) * HT_B, ((h) ? A1 : Ap) + (kt) * BK, off0, off1)
; #define STG_B(b, h, kt) stage_half_s(lds0 + (4 + (b) * 2 + (h)) * HT_B, ((h) ? B1p : Bp) + (kt) * BK, off0, off1)
; #define STG_A(b, h, kt) stage_half_s(lds0 + ((b) * 2 + (h)) * HT_B, ((h) ? A1 : Ap) + (kt) * BK, off0, off1)
; #define STG_B(b, h, kt) stage_half_s(lds0 + (4 + (b) * 2 + (h)) * HT_B, ((h) ? B1p : Bp) + (kt) * BK, off0, off1)
; #define LDA8(b, h) _Pragma("unroll") for (int m = 0; m < 4; ++m) _Pragma("unroll") for (int k = 0; k < 2; ++k) \
;     At[m][k] = *(const bf16x8*)(SA_(shm, b, h) + abase + (m * 2 + k) * 1024)
; template <bool HS>
; __device__ __forceinline__ void gemm_tile8(const u16* __restrict__ Ap, const u16* __restrict__ Bp, int K,
;                                            f32x4 (&acc)[2][2][4][2], char* shm, const int tid, const float* hsr = nullptr) {
;     ...
;   stage_rc(tid * 16, r0, c0);
;   stage_rc(tid * 16 + 8192, r1, c1);
;   const unsigned off0 = (unsigned)(r0 * K + c0) * 2u, off1 = (unsigned)(r1 * K + c1) * 2u;
;   const int wvoff = __builtin_amdgcn_readfirstlane(tid >> 6) * 1024;
;   const u16* A1 = Ap + (size_t)128 * K;
;   const u16* B1p = Bp + (size_t)128 * K;
; #pragma unroll
;   for (int a = 0; a < 2; ++a)
; #pragma unroll
;     for (int b = 0; b < 2; ++b)
; #pragma unroll
;       for (int m = 0; m < 4; ++m)
; #pragma unroll
;         for (int n = 0; n < 2; ++n) acc[a][b][m][n] = f32x4{0.f, 0.f, 0.f, 0.f};
;   const int abase = lds_byte(wr * 64 + fr, fq * 8), bbase = lds_byte(wc * 32 + fr, fq * 8);
;   bf16x8 At[4][2], B0[2][2], B1[2][2];
;   const unsigned lds0 = (unsigned)(size_t)(__attribute__((address_space(3))) char*)shm + (unsigned)wvoff;
;     ...
;     LDB8(B0, 0, 0); SCHED; LDA8(0, 0); STG_A(1, 1, t + 1);
;     WAIT_L(8); BAR; WAIT_L(0); MMA8(0, 0, B0); BAR; SCHED;
;     LDB8(B1, 0, 1); STG_B(0, 0, t + 2);
;     BAR; WAIT_L(0); MMA8(0, 1, B1); BAR;
;     LDA8(0, 1); STG_A(0, 0, t + 2);
;     BAR; WAIT_L(0); MMA8(1, 0, B0); BAR; SCHED;
;     STG_B(0, 1, t + 2);
;     WAIT_V(6); BAR; MMA8(1, 1, B1); BAR;
.LBB0_98:
	s_or_b64 exec, exec, s[2:3]
	v_mov_b32_e32 v4, s14
	v_bfe_i32 v4, v4, 0, 8
	v_ashrrev_i32_e32 v5, 31, v4
	v_lshlrev_b64 v[4:5], 19, v[4:5]
	v_bfe_i32 v6, v0, 27, 1
	v_lshl_add_u64 v[130:131], s[0:1], 0, v[4:5]
	v_lshlrev_b32_e32 v4, 4, v0
	v_lshrrev_b32_e32 v6, 22, v6
	v_add_u32_e32 v6, v4, v6
	v_and_b32_e32 v6, 0xfffffc00, v6
	v_ashrrev_i32_e32 v5, 31, v0
	v_sub_u32_e32 v6, v4, v6
	v_lshrrev_b32_e32 v5, 26, v5
	v_lshrrev_b32_e32 v7, 4, v6
	v_add_u32_e32 v5, v0, v5
	v_bitop3_b32 v7, v7, v6, 32 bitop3:0x6c
	v_ashrrev_i32_e32 v6, 31, v6
	v_ashrrev_i32_e32 v5, 6, v5
	v_lshrrev_b32_e32 v6, 26, v6
	v_lshlrev_b32_e32 v8, 3, v5
	v_add_u32_e32 v6, v7, v6
	v_and_b32_e32 v8, 0x1ffff0, v8
	v_ashrrev_i32_e32 v6, 6, v6
	v_add_u32_e32 v8, v6, v8
	v_mul_i32_i24_e32 v6, 64, v6
	v_add_u32_e32 v4, 0x2000, v4
	v_sub_u32_e32 v6, v7, v6
	v_ashrrev_i32_e32 v7, 31, v4
	v_lshrrev_b32_e32 v7, 22, v7
	v_add_u32_e32 v7, v4, v7
	v_ashrrev_i32_e32 v7, 10, v7
	v_mul_i32_i24_e32 v9, 0x400, v7
	v_sub_u32_e32 v4, v4, v9
	v_lshrrev_b32_e32 v9, 4, v4
	v_bitop3_b32 v4, v9, v4, 32 bitop3:0x6c
	v_ashrrev_i32_e32 v10, 31, v4
	v_lshrrev_b32_e32 v10, 26, v10
	v_add_u32_e32 v10, v4, v10
	v_lshlrev_b32_e32 v9, 3, v7
	v_lshrrev_b32_e32 v11, 6, v10
	v_and_b32_e32 v10, 0xc0, v10
	s_ashr_i32 s5, s4, 31
	v_and_b32_e32 v9, 0x1ffff0, v9
	v_lshlrev_b32_e32 v7, 5, v7
	v_sub_u32_e32 v4, v4, v10
	s_lshl_b64 s[10:11], s[4:5], 11
	v_readlane_b32 s2, v253, 63
	v_lshlrev_b32_e32 v5, 5, v5
	v_add_u32_e32 v9, v11, v9
	v_and_b32_e32 v7, 32, v7
	v_ashrrev_i16_sdwa v4, v178, sext(v4) dst_sel:DWORD dst_unused:UNUSED_PAD src0_sel:DWORD src1_sel:BYTE_0
	v_readlane_b32 s3, v254, 0
	s_add_u32 s9, s2, s10
	v_and_b32_e32 v5, 32, v5
	v_ashrrev_i16_sdwa v6, v178, sext(v6) dst_sel:DWORD dst_unused:UNUSED_PAD src0_sel:DWORD src1_sel:BYTE_0
	v_bfe_i32 v4, v4, 0, 16
	v_lshl_or_b32 v7, v9, 10, v7
	s_addc_u32 s12, s3, s11
	v_bfe_i32 v6, v6, 0, 16
	v_lshl_or_b32 v5, v8, 10, v5
	v_and_b32_e32 v8, 15, v0
	v_add_lshl_u32 v135, v7, v4, 1
	s_lshl_b32 s13, s13, 10
	v_lshlrev_b32_e32 v7, 2, v0
	v_add_lshl_u32 v136, v5, v6, 1
	s_mov_b64 s[2:3], 0x40000
	v_and_b32_e32 v4, 48, v0
	v_lshlrev_b32_e32 v5, 6, v8
	v_and_b32_e32 v7, 32, v7
	s_add_i32 s14, s13, 0
	v_lshl_add_u64 v[132:133], v[130:131], 0, s[2:3]
	v_or_b32_e32 v6, v5, v4
	v_bitop3_b32 v4, v5, v7, v4 bitop3:0x36
	v_lshlrev_b32_e32 v2, 12, v2
	s_movk_i32 s2, 0x3000
	s_add_u32 s15, s9, 0x40100
	v_lshlrev_b32_e32 v3, 13, v3
	v_and_or_b32 v137, v2, s2, v4
	s_addc_u32 s16, s12, 0
	v_readlane_b32 s2, v254, 32
	v_bitop3_b32 v3, v6, v3, v7 bitop3:0xde
	s_add_u32 s17, s2, s10
	v_readlane_b32 s2, v254, 33
	v_mov_b32_e32 v2, 0
	s_addc_u32 s18, s2, s11
	s_mov_b32 s19, -2
	s_mov_b64 s[2:3], 0
	v_add_u32_e32 v134, 0, v3
	s_waitcnt lgkmcnt(0)
	v_readfirstlane_b32 s24, v130
	v_readfirstlane_b32 s25, v131
	v_readfirstlane_b32 s26, v132
	v_readfirstlane_b32 s27, v133
	s_barrier
	s_barrier
	v_add_u32_e32 v158, 0x10000, v137
	ds_read_b128 v[138:141], v158
	ds_read_b128 v[142:145], v158 offset:1024
	ds_read_b128 v[154:157], v158 offset:2048
	ds_read_b128 v[158:161], v158 offset:3072
	ds_read_b128 v[162:165], v134
	ds_read_b128 v[166:169], v134 offset:1024
	ds_read_b128 v[170:173], v134 offset:2048
	ds_read_b128 v[174:177], v134 offset:3072
	ds_read_b128 v[180:183], v134 offset:4096
	ds_read_b128 v[184:187], v134 offset:5120
	ds_read_b128 v[188:191], v134 offset:6144
	ds_read_b128 v[192:195], v134 offset:7168
	v_add_u32_e32 v208, 0x14000, v137
	ds_read_b128 v[196:199], v208
	ds_read_b128 v[200:203], v208 offset:1024
	ds_read_b128 v[204:207], v208 offset:2048
	ds_read_b128 v[208:211], v208 offset:3072
	s_add_u32 s22, s17, s2
	s_addc_u32 s23, s18, s3
	s_add_u32 s22, s22, 0x80
	s_addc_u32 s23, s23, 0
	s_add_i32 s36, s14, 0xc000
	s_mov_b32 m0, s36
	s_nop 0
	global_load_lds_dwordx4 v136, s[22:23]
	s_add_i32 s36, s14, 0xe000
	s_mov_b32 m0, s36
	s_nop 0
	global_load_lds_dwordx4 v135, s[22:23]
	s_waitcnt vmcnt(8) lgkmcnt(0)
	s_setprio 1
	s_barrier
	v_mfma_f32_16x16x32_bf16 v[126:129], v[162:165], v[138:141], 0
	v_mfma_f32_16x16x32_bf16 v[122:125], v[162:165], v[154:157], 0
	v_mfma_f32_16x16x32_bf16 v[114:117], v[170:173], v[154:157], 0
	v_mfma_f32_16x16x32_bf16 v[118:121], v[170:173], v[138:141], 0
	v_mfma_f32_16x16x32_bf16 v[110:113], v[180:183], v[138:141], 0
	v_mfma_f32_16x16x32_bf16 v[106:109], v[180:183], v[154:157], 0
	v_mfma_f32_16x16x32_bf16 v[98:101], v[188:191], v[154:157], 0
	v_mfma_f32_16x16x32_bf16 v[102:105], v[188:191], v[138:141], 0
	v_mfma_f32_16x16x32_bf16 v[126:129], v[166:169], v[142:145], v[126:129]
	v_mfma_f32_16x16x32_bf16 v[122:125], v[166:169], v[158:161], v[122:125]
	v_mfma_f32_16x16x32_bf16 v[114:117], v[174:177], v[158:161], v[114:117]
	v_mfma_f32_16x16x32_bf16 v[118:121], v[174:177], v[142:145], v[118:121]
	v_mfma_f32_16x16x32_bf16 v[110:113], v[184:187], v[142:145], v[110:113]
	v_mfma_f32_16x16x32_bf16 v[106:109], v[184:187], v[158:161], v[106:109]
	v_mfma_f32_16x16x32_bf16 v[98:101], v[192:195], v[158:161], v[98:101]
	v_mfma_f32_16x16x32_bf16 v[102:105], v[192:195], v[142:145], v[102:105]
	v_mfma_f32_16x16x32_bf16 v[94:97], v[162:165], v[196:199], 0
	v_mfma_f32_16x16x32_bf16 v[90:93], v[162:165], v[204:207], 0
	v_mfma_f32_16x16x32_bf16 v[82:85], v[170:173], v[204:207], 0
	v_mfma_f32_16x16x32_bf16 v[86:89], v[170:173], v[196:199], 0
	v_mfma_f32_16x16x32_bf16 v[78:81], v[180:183], v[196:199], 0
	v_mfma_f32_16x16x32_bf16 v[74:77], v[180:183], v[204:207], 0
	v_mfma_f32_16x16x32_bf16 v[66:69], v[188:191], v[204:207], 0
	v_mfma_f32_16x16x32_bf16 v[70:73], v[188:191], v[196:199], 0
	v_mfma_f32_16x16x32_bf16 v[94:97], v[166:169], v[200:203], v[94:97]
	v_mfma_f32_16x16x32_bf16 v[90:93], v[166:169], v[208:211], v[90:93]
	v_mfma_f32_16x16x32_bf16 v[82:85], v[174:177], v[208:211], v[82:85]
	v_mfma_f32_16x16x32_bf16 v[86:89], v[174:177], v[200:203], v[86:89]
	v_mfma_f32_16x16x32_bf16 v[78:81], v[184:187], v[200:203], v[78:81]
	v_mfma_f32_16x16x32_bf16 v[74:77], v[184:187], v[208:211], v[74:77]
	v_mfma_f32_16x16x32_bf16 v[66:69], v[192:195], v[208:211], v[66:69]
	v_mfma_f32_16x16x32_bf16 v[70:73], v[192:195], v[200:203], v[70:73]
	s_barrier
; #define WAIT_V(n) asm volatile("s_waitcnt vmcnt(" #n ")" ::: "memory")
; #define WAIT_L(n) asm volatile("s_waitcnt lgkmcnt(" #n ")" ::: "memory")
; #define BAR __builtin_amdgcn_s_barrier()
; #define SCHED __builtin_amdgcn_sched_barrier(0)
; #define STG_A(b, h, kt) stage_half_s(lds0 + ((b) * 2 + (h)) * HT_B, ((h) ? A1 : Ap) + (kt) * BK, off0, off1)
; #define STG_B(b, h, kt) stage_half_s(lds0 + (4 + (b) * 2 + (h)) * HT_B, ((h) ? B1p : Bp) + (kt) * BK, off0, off1)
; #define STG_A(b, h, kt) stage_half_s(lds0 + ((b) * 2 + (h)) * HT_B, ((h) ? A1 : Ap) + (kt) * BK, off0, off1)
; #define STG_B(b, h, kt) stage_half_s(lds0 + (4 + (b) * 2 + (h)) * HT_B, ((h) ? B1p : Bp) + (kt) * BK, off0, off1)
; #define LDA8(b, h) _Pragma("unroll") for (int m = 0; m < 4; ++m) _Pragma("unroll") for (int k = 0; k < 2; ++k) \
;     At[m][k] = *(const bf16x8*)(SA_(shm, b, h) + abase + (m * 2 + k) * 1024)
; #define LDB8(dst, b, h) _Pragma("unroll") for (int n = 0; n < 2; ++n) _Pragma("unroll") for (int k = 0; k < 2; ++k) \
;     dst[n][k] = *(const bf16x8*)(SB_(shm, b, h) + bbase + (n * 2 + k) * 1024)
; #define MMA8(ai, bj, Bx) do { __builtin_amdgcn_s_setprio(1); \
;     _Pragma("unroll") for (int m = 0; m < 4; ++m) _Pragma("unroll") for (int n = 0; n < 2; ++n) _Pragma("unroll") for (int k = 0; k < 2; ++k) \
;       acc[ai][bj][m][n] = __builtin_amdgcn_mfma_f32_16x16x32_bf16(At[m][k], Bx[n][k], acc[ai][bj][m][n], 0, 0, 0); \
;     __builtin_amdgcn_s_setprio(0); } while (0)
; template <bool HS>
; __device__ __forceinline__ void gemm_tile8(const u16* __restrict__ Ap, const u16* __restrict__ Bp, int K,
;                                            f32x4 (&acc)[2][2][4][2], char* shm, const int tid, const float* hsr = nullptr) {
;     ...
;     LDA8(0, 1); STG_A(0, 0, t + 2);
;     BAR; WAIT_L(0); MMA8(1, 0, B0); BAR; SCHED;
;     STG_B(0, 1, t + 2);
;     WAIT_V(6); BAR; MMA8(1, 1, B1); BAR;
;     LDB8(B0, 1, 0); SCHED; LDA8(1, 0); STG_A(0, 1, t + 2);
;     WAIT_L(8); BAR; WAIT_L(0); MMA8(0, 0, B0); BAR; SCHED;
;     LDB8(B1, 1, 1); STG_B(1, 0, t + 3);
;     BAR; WAIT_L(0); MMA8(0, 1, B1); BAR;
;     LDA8(1, 1); STG_A(1, 0, t + 3);
;     BAR; WAIT_L(0); MMA8(1, 0, B0); BAR; SCHED;
;     STG_B(1, 1, t + 3);
;     WAIT_V(6); BAR; MMA8(1, 1, B1); BAR;
	s_setprio 0
	ds_read_b128 v[162:165], v134 offset:16384
	ds_read_b128 v[166:169], v134 offset:17408
	ds_read_b128 v[170:173], v134 offset:18432
	ds_read_b128 v[174:177], v134 offset:19456
	ds_read_b128 v[180:183], v134 offset:20480
	ds_read_b128 v[184:187], v134 offset:21504
	ds_read_b128 v[188:191], v134 offset:22528
	ds_read_b128 v[192:195], v134 offset:23552
	s_add_u32 s22, s24, s2
	s_addc_u32 s23, s25, s3
	s_add_u32 s22, s22, 0x100
	s_addc_u32 s23, s23, 0
	s_add_i32 s36, s14, 0x10000
	s_mov_b32 m0, s36
	s_nop 0
	global_load_lds_dwordx4 v136, s[22:23]
	s_add_i32 s36, s14, 0x12000
	s_mov_b32 m0, s36
	s_nop 0
	global_load_lds_dwordx4 v135, s[22:23]
	s_add_u32 s22, s9, s2
	s_addc_u32 s23, s12, s3
	s_add_u32 s22, s22, 0x100
	s_addc_u32 s23, s23, 0
	s_mov_b32 m0, s14
	s_nop 0
	global_load_lds_dwordx4 v136, s[22:23]
	s_add_i32 s36, s14, 0x2000
	s_mov_b32 m0, s36
	s_nop 0
	global_load_lds_dwordx4 v135, s[22:23]
	s_add_u32 s22, s26, s2
	s_addc_u32 s23, s27, s3
	s_add_u32 s22, s22, 0x100
	s_addc_u32 s23, s23, 0
	s_add_i32 s36, s14, 0x14000
	s_mov_b32 m0, s36
	s_nop 0
	global_load_lds_dwordx4 v136, s[22:23]
	s_add_i32 s36, s14, 0x16000
	s_mov_b32 m0, s36
	s_nop 0
	global_load_lds_dwordx4 v135, s[22:23]
	s_waitcnt vmcnt(8) lgkmcnt(0)
	s_setprio 1
	s_barrier
	v_mfma_f32_16x16x32_bf16 v[62:65], v[162:165], v[138:141], 0
	v_mfma_f32_16x16x32_bf16 v[58:61], v[162:165], v[154:157], 0
	v_mfma_f32_16x16x32_bf16 v[50:53], v[170:173], v[154:157], 0
	v_mfma_f32_16x16x32_bf16 v[54:57], v[170:173], v[138:141], 0
	v_mfma_f32_16x16x32_bf16 v[46:49], v[180:183], v[138:141], 0
	v_mfma_f32_16x16x32_bf16 v[42:45], v[180:183], v[154:157], 0
	v_mfma_f32_16x16x32_bf16 v[34:37], v[188:191], v[154:157], 0
	v_mfma_f32_16x16x32_bf16 v[38:41], v[188:191], v[138:141], 0
	v_mfma_f32_16x16x32_bf16 v[62:65], v[166:169], v[142:145], v[62:65]
	v_mfma_f32_16x16x32_bf16 v[58:61], v[166:169], v[158:161], v[58:61]
	v_mfma_f32_16x16x32_bf16 v[50:53], v[174:177], v[158:161], v[50:53]
	v_mfma_f32_16x16x32_bf16 v[54:57], v[174:177], v[142:145], v[54:57]
	v_mfma_f32_16x16x32_bf16 v[46:49], v[184:187], v[142:145], v[46:49]
	v_mfma_f32_16x16x32_bf16 v[42:45], v[184:187], v[158:161], v[42:45]
	v_mfma_f32_16x16x32_bf16 v[34:37], v[192:195], v[158:161], v[34:37]
	v_mfma_f32_16x16x32_bf16 v[38:41], v[192:195], v[142:145], v[38:41]
	v_mfma_f32_16x16x32_bf16 v[30:33], v[162:165], v[196:199], 0
	v_mfma_f32_16x16x32_bf16 v[26:29], v[162:165], v[204:207], 0
	v_mfma_f32_16x16x32_bf16 v[18:21], v[170:173], v[204:207], 0
	v_mfma_f32_16x16x32_bf16 v[22:25], v[170:173], v[196:199], 0
	v_mfma_f32_16x16x32_bf16 v[14:17], v[180:183], v[196:199], 0
	v_mfma_f32_16x16x32_bf16 v[10:13], v[180:183], v[204:207], 0
	v_mfma_f32_16x16x32_bf16 v[2:5], v[188:191], v[204:207], 0
	v_mfma_f32_16x16x32_bf16 v[6:9], v[188:191], v[196:199], 0
	v_mfma_f32_16x16x32_bf16 v[30:33], v[166:169], v[200:203], v[30:33]
	v_mfma_f32_16x16x32_bf16 v[26:29], v[166:169], v[208:211], v[26:29]
	v_mfma_f32_16x16x32_bf16 v[18:21], v[174:177], v[208:211], v[18:21]
	v_mfma_f32_16x16x32_bf16 v[22:25], v[174:177], v[200:203], v[22:25]
	v_mfma_f32_16x16x32_bf16 v[14:17], v[184:187], v[200:203], v[14:17]
	v_mfma_f32_16x16x32_bf16 v[10:13], v[184:187], v[208:211], v[10:13]
	v_mfma_f32_16x16x32_bf16 v[2:5], v[192:195], v[208:211], v[2:5]
	v_mfma_f32_16x16x32_bf16 v[6:9], v[192:195], v[200:203], v[6:9]
	s_barrier
	s_setprio 0
	v_add_u32_e32 v158, 0x18000, v137
	ds_read_b128 v[138:141], v158
	ds_read_b128 v[142:145], v158 offset:1024
	ds_read_b128 v[154:157], v158 offset:2048
	ds_read_b128 v[158:161], v158 offset:3072
	ds_read_b128 v[162:165], v134 offset:32768
	ds_read_b128 v[166:169], v134 offset:33792
	ds_read_b128 v[170:173], v134 offset:34816
	ds_read_b128 v[174:177], v134 offset:35840
	ds_read_b128 v[180:183], v134 offset:36864
	ds_read_b128 v[184:187], v134 offset:37888
	ds_read_b128 v[188:191], v134 offset:38912
	ds_read_b128 v[192:195], v134 offset:39936
	v_add_u32_e32 v208, 0x1c000, v137
	ds_read_b128 v[196:199], v208
	ds_read_b128 v[200:203], v208 offset:1024
	ds_read_b128 v[204:207], v208 offset:2048
	ds_read_b128 v[208:211], v208 offset:3072
	s_add_u32 s22, s17, s2
	s_addc_u32 s23, s18, s3
	s_add_u32 s22, s22, 0x100
	s_addc_u32 s23, s23, 0
	s_add_i32 s36, s14, 0x4000
	s_mov_b32 m0, s36
	s_nop 0
	global_load_lds_dwordx4 v136, s[22:23]
	s_add_i32 s36, s14, 0x6000
	s_mov_b32 m0, s36
	s_nop 0
	global_load_lds_dwordx4 v135, s[22:23]
	s_waitcnt vmcnt(8) lgkmcnt(0)
	s_setprio 1
	s_barrier
	v_mfma_f32_16x16x32_bf16 v[126:129], v[162:165], v[138:141], v[126:129]
	v_mfma_f32_16x16x32_bf16 v[122:125], v[162:165], v[154:157], v[122:125]
	v_mfma_f32_16x16x32_bf16 v[114:117], v[170:173], v[154:157], v[114:117]
	v_mfma_f32_16x16x32_bf16 v[118:121], v[170:173], v[138:141], v[118:121]
	v_mfma_f32_16x16x32_bf16 v[110:113], v[180:183], v[138:141], v[110:113]
	v_mfma_f32_16x16x32_bf16 v[106:109], v[180:183], v[154:157], v[106:109]
	v_mfma_f32_16x16x32_bf16 v[98:101], v[188:191], v[154:157], v[98:101]
	v_mfma_f32_16x16x32_bf16 v[102:105], v[188:191], v[138:141], v[102:105]
	v_mfma_f32_16x16x32_bf16 v[126:129], v[166:169], v[142:145], v[126:129]
	v_mfma_f32_16x16x32_bf16 v[122:125], v[166:169], v[158:161], v[122:125]
	v_mfma_f32_16x16x32_bf16 v[114:117], v[174:177], v[158:161], v[114:117]
	v_mfma_f32_16x16x32_bf16 v[118:121], v[174:177], v[142:145], v[118:121]
	v_mfma_f32_16x16x32_bf16 v[110:113], v[184:187], v[142:145], v[110:113]
	v_mfma_f32_16x16x32_bf16 v[106:109], v[184:187], v[158:161], v[106:109]
	v_mfma_f32_16x16x32_bf16 v[98:101], v[192:195], v[158:161], v[98:101]
	v_mfma_f32_16x16x32_bf16 v[102:105], v[192:195], v[142:145], v[102:105]
	v_mfma_f32_16x16x32_bf16 v[94:97], v[162:165], v[196:199], v[94:97]
	v_mfma_f32_16x16x32_bf16 v[90:93], v[162:165], v[204:207], v[90:93]
	v_mfma_f32_16x16x32_bf16 v[82:85], v[170:173], v[204:207], v[82:85]
	v_mfma_f32_16x16x32_bf16 v[86:89], v[170:173], v[196:199], v[86:89]
	v_mfma_f32_16x16x32_bf16 v[78:81], v[180:183], v[196:199], v[78:81]
	v_mfma_f32_16x16x32_bf16 v[74:77], v[180:183], v[204:207], v[74:77]
	v_mfma_f32_16x16x32_bf16 v[66:69], v[188:191], v[204:207], v[66:69]
	v_mfma_f32_16x16x32_bf16 v[70:73], v[188:191], v[196:199], v[70:73]
	v_mfma_f32_16x16x32_bf16 v[94:97], v[166:169], v[200:203], v[94:97]
	v_mfma_f32_16x16x32_bf16 v[90:93], v[166:169], v[208:211], v[90:93]
	v_mfma_f32_16x16x32_bf16 v[82:85], v[174:177], v[208:211], v[82:85]
	v_mfma_f32_16x16x32_bf16 v[86:89], v[174:177], v[200:203], v[86:89]
	v_mfma_f32_16x16x32_bf16 v[78:81], v[184:187], v[200:203], v[78:81]
	v_mfma_f32_16x16x32_bf16 v[74:77], v[184:187], v[208:211], v[74:77]
	v_mfma_f32_16x16x32_bf16 v[66:69], v[192:195], v[208:211], v[66:69]
	v_mfma_f32_16x16x32_bf16 v[70:73], v[192:195], v[200:203], v[70:73]
	s_barrier
; #define WAIT_V(n) asm volatile("s_waitcnt vmcnt(" #n ")" ::: "memory")
; #define WAIT_L(n) asm volatile("s_waitcnt lgkmcnt(" #n ")" ::: "memory")
; #define BAR __builtin_amdgcn_s_barrier()
; #define SCHED __builtin_amdgcn_sched_barrier(0)
; #define STG_A(b, h, kt) stage_half_s(lds0 + ((b) * 2 + (h)) * HT_B, ((h) ? A1 : Ap) + (kt) * BK, off0, off1)
; #define STG_B(b, h, kt) stage_half_s(lds0 + (4 + (b) * 2 + (h)) * HT_B, ((h) ? B1p : Bp) + (kt) * BK, off0, off1)
; #define STG_A(b, h, kt) stage_half_s(lds0 + ((b) * 2 + (h)) * HT_B, ((h) ? A1 : Ap) + (kt) * BK, off0, off1)
; #define STG_B(b, h, kt) stage_half_s(lds0 + (4 + (b) * 2 + (h)) * HT_B, ((h) ? B1p : Bp) + (kt) * BK, off0, off1)
; #define LDA8(b, h) _Pragma("unroll") for (int m = 0; m < 4; ++m) _Pragma("unroll") for (int k = 0; k < 2; ++k) \
;     At[m][k] = *(const bf16x8*)(SA_(shm, b, h) + abase + (m * 2 + k) * 1024)
; #define LDB8(dst, b, h) _Pragma("unroll") for (int n = 0; n < 2; ++n) _Pragma("unroll") for (int k = 0; k < 2; ++k) \
;     dst[n][k] = *(const bf16x8*)(SB_(shm, b, h) + bbase + (n * 2 + k) * 1024)
; #define MMA8(ai, bj, Bx) do { __builtin_amdgcn_s_setprio(1); \
;     _Pragma("unroll") for (int m = 0; m < 4; ++m) _Pragma("unroll") for (int n = 0; n < 2; ++n) _Pragma("unroll") for (int k = 0; k < 2; ++k) \
;       acc[ai][bj][m][n] = __builtin_amdgcn_mfma_f32_16x16x32_bf16(At[m][k], Bx[n][k], acc[ai][bj][m][n], 0, 0, 0); \
;     __builtin_amdgcn_s_setprio(0); } while (0)
; template <bool HS>
; __device__ __forceinline__ void gemm_tile8(const u16* __restrict__ Ap, const u16* __restrict__ Bp, int K,
;                                            f32x4 (&acc)[2][2][4][2], char* shm, const int tid, const float* hsr = nullptr) {
;     ...
;     LDB8(B0, 0, 0); SCHED; LDA8(0, 0); STG_A(1, 1, t + 1);
;     WAIT_L(8); BAR; WAIT_L(0); MMA8(0, 0, B0); BAR; SCHED;
;     ...
;     LDB8(B0, 1, 0); SCHED; LDA8(1, 0); STG_A(0, 1, t + 2);
;     WAIT_L(8); BAR; WAIT_L(0); MMA8(0, 0, B0); BAR; SCHED;
;     LDB8(B1, 1, 1); STG_B(1, 0, t + 3);
;     BAR; WAIT_L(0); MMA8(0, 1, B1); BAR;
;     LDA8(1, 1); STG_A(1, 0, t + 3);
;     BAR; WAIT_L(0); MMA8(1, 0, B0); BAR; SCHED;
;     STG_B(1, 1, t + 3);
;     WAIT_V(6); BAR; MMA8(1, 1, B1); BAR;
	s_setprio 0
	ds_read_b128 v[162:165], v134 offset:49152
	ds_read_b128 v[166:169], v134 offset:50176
	ds_read_b128 v[170:173], v134 offset:51200
	ds_read_b128 v[174:177], v134 offset:52224
	ds_read_b128 v[180:183], v134 offset:53248
	ds_read_b128 v[184:187], v134 offset:54272
	ds_read_b128 v[188:191], v134 offset:55296
	ds_read_b128 v[192:195], v134 offset:56320
	s_add_u32 s22, s24, s2
	s_addc_u32 s23, s25, s3
	s_add_u32 s22, s22, 0x180
	s_addc_u32 s23, s23, 0
	s_add_i32 s36, s14, 0x18000
	s_mov_b32 m0, s36
	s_nop 0
	global_load_lds_dwordx4 v136, s[22:23]
	s_add_i32 s36, s14, 0x1a000
	s_mov_b32 m0, s36
	s_nop 0
	global_load_lds_dwordx4 v135, s[22:23]
	s_add_u32 s22, s9, s2
	s_addc_u32 s23, s12, s3
	s_add_u32 s22, s22, 0x180
	s_addc_u32 s23, s23, 0
	s_add_i32 s36, s14, 0x8000
	s_mov_b32 m0, s36
	s_nop 0
	global_load_lds_dwordx4 v136, s[22:23]
	s_add_i32 s36, s14, 0xa000
	s_mov_b32 m0, s36
	s_nop 0
	global_load_lds_dwordx4 v135, s[22:23]
	s_add_u32 s22, s26, s2
	s_addc_u32 s23, s27, s3
	s_add_u32 s22, s22, 0x180
	s_addc_u32 s23, s23, 0
	s_add_i32 s36, s14, 0x1c000
	s_mov_b32 m0, s36
	s_nop 0
	global_load_lds_dwordx4 v136, s[22:23]
	s_add_i32 s36, s14, 0x1e000
	s_mov_b32 m0, s36
	s_nop 0
	global_load_lds_dwordx4 v135, s[22:23]
	s_waitcnt vmcnt(8) lgkmcnt(0)
	s_setprio 1
	s_barrier
	v_mfma_f32_16x16x32_bf16 v[62:65], v[162:165], v[138:141], v[62:65]
	v_mfma_f32_16x16x32_bf16 v[58:61], v[162:165], v[154:157], v[58:61]
	v_mfma_f32_16x16x32_bf16 v[50:53], v[170:173], v[154:157], v[50:53]
	v_mfma_f32_16x16x32_bf16 v[54:57], v[170:173], v[138:141], v[54:57]
	v_mfma_f32_16x16x32_bf16 v[46:49], v[180:183], v[138:141], v[46:49]
	v_mfma_f32_16x16x32_bf16 v[42:45], v[180:183], v[154:157], v[42:45]
	v_mfma_f32_16x16x32_bf16 v[34:37], v[188:191], v[154:157], v[34:37]
	v_mfma_f32_16x16x32_bf16 v[38:41], v[188:191], v[138:141], v[38:41]
	v_mfma_f32_16x16x32_bf16 v[62:65], v[166:169], v[142:145], v[62:65]
	v_mfma_f32_16x16x32_bf16 v[58:61], v[166:169], v[158:161], v[58:61]
	v_mfma_f32_16x16x32_bf16 v[50:53], v[174:177], v[158:161], v[50:53]
	v_mfma_f32_16x16x32_bf16 v[54:57], v[174:177], v[142:145], v[54:57]
	v_mfma_f32_16x16x32_bf16 v[46:49], v[184:187], v[142:145], v[46:49]
	v_mfma_f32_16x16x32_bf16 v[42:45], v[184:187], v[158:161], v[42:45]
	v_mfma_f32_16x16x32_bf16 v[34:37], v[192:195], v[158:161], v[34:37]
	v_mfma_f32_16x16x32_bf16 v[38:41], v[192:195], v[142:145], v[38:41]
	v_mfma_f32_16x16x32_bf16 v[30:33], v[162:165], v[196:199], v[30:33]
	v_mfma_f32_16x16x32_bf16 v[26:29], v[162:165], v[204:207], v[26:29]
	v_mfma_f32_16x16x32_bf16 v[18:21], v[170:173], v[204:207], v[18:21]
	v_mfma_f32_16x16x32_bf16 v[22:25], v[170:173], v[196:199], v[22:25]
	v_mfma_f32_16x16x32_bf16 v[14:17], v[180:183], v[196:199], v[14:17]
	v_mfma_f32_16x16x32_bf16 v[10:13], v[180:183], v[204:207], v[10:13]
	v_mfma_f32_16x16x32_bf16 v[2:5], v[188:191], v[204:207], v[2:5]
	v_mfma_f32_16x16x32_bf16 v[6:9], v[188:191], v[196:199], v[6:9]
	v_mfma_f32_16x16x32_bf16 v[30:33], v[166:169], v[200:203], v[30:33]
	v_mfma_f32_16x16x32_bf16 v[26:29], v[166:169], v[208:211], v[26:29]
	v_mfma_f32_16x16x32_bf16 v[18:21], v[174:177], v[208:211], v[18:21]
	v_mfma_f32_16x16x32_bf16 v[22:25], v[174:177], v[200:203], v[22:25]
	v_mfma_f32_16x16x32_bf16 v[14:17], v[184:187], v[200:203], v[14:17]
	v_mfma_f32_16x16x32_bf16 v[10:13], v[184:187], v[208:211], v[10:13]
	v_mfma_f32_16x16x32_bf16 v[2:5], v[192:195], v[208:211], v[2:5]
	v_mfma_f32_16x16x32_bf16 v[6:9], v[192:195], v[200:203], v[6:9]
	s_barrier
	s_setprio 0
	s_add_i32 s19, s19, 2
	s_add_u32 s2, s2, 0x100
	s_addc_u32 s3, s3, 0
	s_cmp_lt_u32 s19, 12
	s_cbranch_scc0 .Lk_conv_out_exit
.Lk_conv_out:
	v_add_u32_e32 v158, 0x10000, v137
	ds_read_b128 v[138:141], v158
	ds_read_b128 v[142:145], v158 offset:1024
	ds_read_b128 v[154:157], v158 offset:2048
	ds_read_b128 v[158:161], v158 offset:3072
	ds_read_b128 v[162:165], v134
	ds_read_b128 v[166:169], v134 offset:1024
	ds_read_b128 v[170:173], v134 offset:2048
	ds_read_b128 v[174:177], v134 offset:3072
	ds_read_b128 v[180:183], v134 offset:4096
	ds_read_b128 v[184:187], v134 offset:5120
	ds_read_b128 v[188:191], v134 offset:6144
	ds_read_b128 v[192:195], v134 offset:7168
	v_add_u32_e32 v208, 0x14000, v137
	ds_read_b128 v[196:199], v208
	ds_read_b128 v[200:203], v208 offset:1024
	ds_read_b128 v[204:207], v208 offset:2048
	ds_read_b128 v[208:211], v208 offset:3072
	s_add_u32 s22, s17, s2
	s_addc_u32 s23, s18, s3
	s_add_u32 s22, s22, 0x80
	s_addc_u32 s23, s23, 0
	s_add_i32 s36, s14, 0xc000
	s_mov_b32 m0, s36
	s_nop 0
	global_load_lds_dwordx4 v136, s[22:23]
	s_add_i32 s36, s14, 0xe000
	s_mov_b32 m0, s36
	s_nop 0
	global_load_lds_dwordx4 v135, s[22:23]
	s_waitcnt vmcnt(8) lgkmcnt(0)
	s_setprio 1
	s_barrier
; #define WAIT_V(n) asm volatile("s_waitcnt vmcnt(" #n ")" ::: "memory")
; #define WAIT_L(n) asm volatile("s_waitcnt lgkmcnt(" #n ")" ::: "memory")
; #define BAR __builtin_amdgcn_s_barrier()
; #define SCHED __builtin_amdgcn_sched_barrier(0)
; #define STG_A(b, h, kt) stage_half_s(lds0 + ((b) * 2 + (h)) * HT_B, ((h) ? A1 : Ap) + (kt) * BK, off0, off1)
; #define STG_B(b, h, kt) stage_half_s(lds0 + (4 + (b) * 2 + (h)) * HT_B, ((h) ? B1p : Bp) + (kt) * BK, off0, off1)
; #define STG_A(b, h, kt) stage_half_s(lds0 + ((b) * 2 + (h)) * HT_B, ((h) ? A1 : Ap) + (kt) * BK, off0, off1)
; #define STG_B(b, h, kt) stage_half_s(lds0 + (4 + (b) * 2 + (h)) * HT_B, ((h) ? B1p : Bp) + (kt) * BK, off0, off1)
; #define LDA8(b, h) _Pragma("unroll") for (int m = 0; m < 4; ++m) _Pragma("unroll") for (int k = 0; k < 2; ++k) \
;     At[m][k] = *(const bf16x8*)(SA_(shm, b, h) + abase + (m * 2 + k) * 1024)
; #define LDB8(dst, b, h) _Pragma("unroll") for (int n = 0; n < 2; ++n) _Pragma("unroll") for (int k = 0; k < 2; ++k) \
;     dst[n][k] = *(const bf16x8*)(SB_(shm, b, h) + bbase + (n * 2 + k) * 1024)
; #define MMA8(ai, bj, Bx) do { __builtin_amdgcn_s_setprio(1); \
;     _Pragma("unroll") for (int m = 0; m < 4; ++m) _Pragma("unroll") for (int n = 0; n < 2; ++n) _Pragma("unroll") for (int k = 0; k < 2; ++k) \
;       acc[ai][bj][m][n] = __builtin_amdgcn_mfma_f32_16x16x32_bf16(At[m][k], Bx[n][k], acc[ai][bj][m][n], 0, 0, 0); \
;     __builtin_amdgcn_s_setprio(0); } while (0)
; template <bool HS>
; __device__ __forceinline__ void gemm_tile8(const u16* __restrict__ Ap, const u16* __restrict__ Bp, int K,
;                                            f32x4 (&acc)[2][2][4][2], char* shm, const int tid, const float* hsr = nullptr) {
;     ...
;     LDB8(B0, 0, 0); SCHED; LDA8(0, 0); STG_A(1, 1, t + 1);
;     WAIT_L(8); BAR; WAIT_L(0); MMA8(0, 0, B0); BAR; SCHED;
;     LDB8(B1, 0, 1); STG_B(0, 0, t + 2);
;     BAR; WAIT_L(0); MMA8(0, 1, B1); BAR;
;     LDA8(0, 1); STG_A(0, 0, t + 2);
;     BAR; WAIT_L(0); MMA8(1, 0, B0); BAR; SCHED;
;     STG_B(0, 1, t + 2);
;     WAIT_V(6); BAR; MMA8(1, 1, B1); BAR;
	v_mfma_f32_16x16x32_bf16 v[126:129], v[162:165], v[138:141], v[126:129]
	v_mfma_f32_16x16x32_bf16 v[122:125], v[162:165], v[154:157], v[122:125]
	v_mfma_f32_16x16x32_bf16 v[114:117], v[170:173], v[154:157], v[114:117]
	v_mfma_f32_16x16x32_bf16 v[118:121], v[170:173], v[138:141], v[118:121]
	v_mfma_f32_16x16x32_bf16 v[110:113], v[180:183], v[138:141], v[110:113]
	v_mfma_f32_16x16x32_bf16 v[106:109], v[180:183], v[154:157], v[106:109]
	v_mfma_f32_16x16x32_bf16 v[98:101], v[188:191], v[154:157], v[98:101]
	v_mfma_f32_16x16x32_bf16 v[102:105], v[188:191], v[138:141], v[102:105]
	v_mfma_f32_16x16x32_bf16 v[126:129], v[166:169], v[142:145], v[126:129]
	v_mfma_f32_16x16x32_bf16 v[122:125], v[166:169], v[158:161], v[122:125]
	v_mfma_f32_16x16x32_bf16 v[114:117], v[174:177], v[158:161], v[114:117]
	v_mfma_f32_16x16x32_bf16 v[118:121], v[174:177], v[142:145], v[118:121]
	v_mfma_f32_16x16x32_bf16 v[110:113], v[184:187], v[142:145], v[110:113]
	v_mfma_f32_16x16x32_bf16 v[106:109], v[184:187], v[158:161], v[106:109]
	v_mfma_f32_16x16x32_bf16 v[98:101], v[192:195], v[158:161], v[98:101]
	v_mfma_f32_16x16x32_bf16 v[102:105], v[192:195], v[142:145], v[102:105]
	v_mfma_f32_16x16x32_bf16 v[94:97], v[162:165], v[196:199], v[94:97]
	v_mfma_f32_16x16x32_bf16 v[90:93], v[162:165], v[204:207], v[90:93]
	v_mfma_f32_16x16x32_bf16 v[82:85], v[170:173], v[204:207], v[82:85]
	v_mfma_f32_16x16x32_bf16 v[86:89], v[170:173], v[196:199], v[86:89]
	v_mfma_f32_16x16x32_bf16 v[78:81], v[180:183], v[196:199], v[78:81]
	v_mfma_f32_16x16x32_bf16 v[74:77], v[180:183], v[204:207], v[74:77]
	v_mfma_f32_16x16x32_bf16 v[66:69], v[188:191], v[204:207], v[66:69]
	v_mfma_f32_16x16x32_bf16 v[70:73], v[188:191], v[196:199], v[70:73]
	v_mfma_f32_16x16x32_bf16 v[94:97], v[166:169], v[200:203], v[94:97]
	v_mfma_f32_16x16x32_bf16 v[90:93], v[166:169], v[208:211], v[90:93]
	v_mfma_f32_16x16x32_bf16 v[82:85], v[174:177], v[208:211], v[82:85]
	v_mfma_f32_16x16x32_bf16 v[86:89], v[174:177], v[200:203], v[86:89]
	v_mfma_f32_16x16x32_bf16 v[78:81], v[184:187], v[200:203], v[78:81]
	v_mfma_f32_16x16x32_bf16 v[74:77], v[184:187], v[208:211], v[74:77]
	v_mfma_f32_16x16x32_bf16 v[66:69], v[192:195], v[208:211], v[66:69]
	v_mfma_f32_16x16x32_bf16 v[70:73], v[192:195], v[200:203], v[70:73]
	s_barrier
	s_setprio 0
	ds_read_b128 v[162:165], v134 offset:16384
	ds_read_b128 v[166:169], v134 offset:17408
	ds_read_b128 v[170:173], v134 offset:18432
	ds_read_b128 v[174:177], v134 offset:19456
	ds_read_b128 v[180:183], v134 offset:20480
	ds_read_b128 v[184:187], v134 offset:21504
	ds_read_b128 v[188:191], v134 offset:22528
	ds_read_b128 v[192:195], v134 offset:23552
	s_add_u32 s22, s24, s2
	s_addc_u32 s23, s25, s3
	s_add_u32 s22, s22, 0x100
	s_addc_u32 s23, s23, 0
	s_add_i32 s36, s14, 0x10000
	s_mov_b32 m0, s36
	s_nop 0
	global_load_lds_dwordx4 v136, s[22:23]
	s_add_i32 s36, s14, 0x12000
	s_mov_b32 m0, s36
	s_nop 0
	global_load_lds_dwordx4 v135, s[22:23]
	s_add_u32 s22, s9, s2
	s_addc_u32 s23, s12, s3
	s_add_u32 s22, s22, 0x100
	s_addc_u32 s23, s23, 0
	s_mov_b32 m0, s14
	s_nop 0
	global_load_lds_dwordx4 v136, s[22:23]
	s_add_i32 s36, s14, 0x2000
	s_mov_b32 m0, s36
	s_nop 0
	global_load_lds_dwordx4 v135, s[22:23]
	s_add_u32 s22, s26, s2
	s_addc_u32 s23, s27, s3
	s_add_u32 s22, s22, 0x100
	s_addc_u32 s23, s23, 0
	s_add_i32 s36, s14, 0x14000
	s_mov_b32 m0, s36
	s_nop 0
	global_load_lds_dwordx4 v136, s[22:23]
	s_add_i32 s36, s14, 0x16000
	s_mov_b32 m0, s36
	s_nop 0
	global_load_lds_dwordx4 v135, s[22:23]
	s_waitcnt vmcnt(8) lgkmcnt(0)
	s_setprio 1
	s_barrier
	v_mfma_f32_16x16x32_bf16 v[62:65], v[162:165], v[138:141], v[62:65]
	v_mfma_f32_16x16x32_bf16 v[58:61], v[162:165], v[154:157], v[58:61]
	v_mfma_f32_16x16x32_bf16 v[50:53], v[170:173], v[154:157], v[50:53]
	v_mfma_f32_16x16x32_bf16 v[54:57], v[170:173], v[138:141], v[54:57]
	v_mfma_f32_16x16x32_bf16 v[46:49], v[180:183], v[138:141], v[46:49]
	v_mfma_f32_16x16x32_bf16 v[42:45], v[180:183], v[154:157], v[42:45]
	v_mfma_f32_16x16x32_bf16 v[34:37], v[188:191], v[154:157], v[34:37]
	v_mfma_f32_16x16x32_bf16 v[38:41], v[188:191], v[138:141], v[38:41]
	v_mfma_f32_16x16x32_bf16 v[62:65], v[166:169], v[142:145], v[62:65]
	v_mfma_f32_16x16x32_bf16 v[58:61], v[166:169], v[158:161], v[58:61]
	v_mfma_f32_16x16x32_bf16 v[50:53], v[174:177], v[158:161], v[50:53]
	v_mfma_f32_16x16x32_bf16 v[54:57], v[174:177], v[142:145], v[54:57]
	v_mfma_f32_16x16x32_bf16 v[46:49], v[184:187], v[142:145], v[46:49]
	v_mfma_f32_16x16x32_bf16 v[42:45], v[184:187], v[158:161], v[42:45]
	v_mfma_f32_16x16x32_bf16 v[34:37], v[192:195], v[158:161], v[34:37]
	v_mfma_f32_16x16x32_bf16 v[38:41], v[192:195], v[142:145], v[38:41]
	v_mfma_f32_16x16x32_bf16 v[30:33], v[162:165], v[196:199], v[30:33]
	v_mfma_f32_16x16x32_bf16 v[26:29], v[162:165], v[204:207], v[26:29]
	v_mfma_f32_16x16x32_bf16 v[18:21], v[170:173], v[204:207], v[18:21]
	v_mfma_f32_16x16x32_bf16 v[22:25], v[170:173], v[196:199], v[22:25]
	v_mfma_f32_16x16x32_bf16 v[14:17], v[180:183], v[196:199], v[14:17]
	v_mfma_f32_16x16x32_bf16 v[10:13], v[180:183], v[204:207], v[10:13]
	v_mfma_f32_16x16x32_bf16 v[2:5], v[188:191], v[204:207], v[2:5]
	v_mfma_f32_16x16x32_bf16 v[6:9], v[188:191], v[196:199], v[6:9]
	v_mfma_f32_16x16x32_bf16 v[30:33], v[166:169], v[200:203], v[30:33]
	v_mfma_f32_16x16x32_bf16 v[26:29], v[166:169], v[208:211], v[26:29]
	v_mfma_f32_16x16x32_bf16 v[18:21], v[174:177], v[208:211], v[18:21]
	v_mfma_f32_16x16x32_bf16 v[22:25], v[174:177], v[200:203], v[22:25]
	v_mfma_f32_16x16x32_bf16 v[14:17], v[184:187], v[200:203], v[14:17]
	v_mfma_f32_16x16x32_bf16 v[10:13], v[184:187], v[208:211], v[10:13]
	v_mfma_f32_16x16x32_bf16 v[2:5], v[192:195], v[208:211], v[2:5]
	v_mfma_f32_16x16x32_bf16 v[6:9], v[192:195], v[200:203], v[6:9]
	s_barrier
; #define WAIT_V(n) asm volatile("s_waitcnt vmcnt(" #n ")" ::: "memory")
; #define WAIT_L(n) asm volatile("s_waitcnt lgkmcnt(" #n ")" ::: "memory")
; #define BAR __builtin_amdgcn_s_barrier()
; #define SCHED __builtin_amdgcn_sched_barrier(0)
; #define STG_A(b, h, kt) stage_half_s(lds0 + ((b) * 2 + (h)) * HT_B, ((h) ? A1 : Ap) + (kt) * BK, off0, off1)
; #define STG_B(b, h, kt) stage_half_s(lds0 + (4 + (b) * 2 + (h)) * HT_B, ((h) ? B1p : Bp) + (kt) * BK, off0, off1)
; #define STG_A(b, h, kt) stage_half_s(lds0 + ((b) * 2 + (h)) * HT_B, ((h) ? A1 : Ap) + (kt) * BK, off0, off1)
; #define STG_B(b, h, kt) stage_half_s(lds0 + (4 + (b) * 2 + (h)) * HT_B, ((h) ? B1p : Bp) + (kt) * BK, off0, off1)
; #define LDA8(b, h) _Pragma("unroll") for (int m = 0; m < 4; ++m) _Pragma("unroll") for (int k = 0; k < 2; ++k) \
;     At[m][k] = *(const bf16x8*)(SA_(shm, b, h) + abase + (m * 2 + k) * 1024)
; #define LDB8(dst, b, h) _Pragma("unroll") for (int n = 0; n < 2; ++n) _Pragma("unroll") for (int k = 0; k < 2; ++k) \
;     dst[n][k] = *(const bf16x8*)(SB_(shm, b, h) + bbase + (n * 2 + k) * 1024)
; #define MMA8(ai, bj, Bx) do { __builtin_amdgcn_s_setprio(1); \
;     _Pragma("unroll") for (int m = 0; m < 4; ++m) _Pragma("unroll") for (int n = 0; n < 2; ++n) _Pragma("unroll") for (int k = 0; k < 2; ++k) \
;       acc[ai][bj][m][n] = __builtin_amdgcn_mfma_f32_16x16x32_bf16(At[m][k], Bx[n][k], acc[ai][bj][m][n], 0, 0, 0); \
;     __builtin_amdgcn_s_setprio(0); } while (0)
; template <bool HS>
; __device__ __forceinline__ void gemm_tile8(const u16* __restrict__ Ap, const u16* __restrict__ Bp, int K,
;                                            f32x4 (&acc)[2][2][4][2], char* shm, const int tid, const float* hsr = nullptr) {
;     ...
;     LDA8(0, 1); STG_A(0, 0, t + 2);
;     BAR; WAIT_L(0); MMA8(1, 0, B0); BAR; SCHED;
;     STG_B(0, 1, t + 2);
;     WAIT_V(6); BAR; MMA8(1, 1, B1); BAR;
;     LDB8(B0, 1, 0); SCHED; LDA8(1, 0); STG_A(0, 1, t + 2);
;     WAIT_L(8); BAR; WAIT_L(0); MMA8(0, 0, B0); BAR; SCHED;
;     LDB8(B1, 1, 1); STG_B(1, 0, t + 3);
;     BAR; WAIT_L(0); MMA8(0, 1, B1); BAR;
;     LDA8(1, 1); STG_A(1, 0, t + 3);
;     BAR; WAIT_L(0); MMA8(1, 0, B0); BAR; SCHED;
;     STG_B(1, 1, t + 3);
;     WAIT_V(6); BAR; MMA8(1, 1, B1); BAR;
	s_setprio 0
	v_add_u32_e32 v158, 0x18000, v137
	ds_read_b128 v[138:141], v158
	ds_read_b128 v[142:145], v158 offset:1024
	ds_read_b128 v[154:157], v158 offset:2048
	ds_read_b128 v[158:161], v158 offset:3072
	ds_read_b128 v[162:165], v134 offset:32768
	ds_read_b128 v[166:169], v134 offset:33792
	ds_read_b128 v[170:173], v134 offset:34816
	ds_read_b128 v[174:177], v134 offset:35840
	ds_read_b128 v[180:183], v134 offset:36864
	ds_read_b128 v[184:187], v134 offset:37888
	ds_read_b128 v[188:191], v134 offset:38912
	ds_read_b128 v[192:195], v134 offset:39936
	v_add_u32_e32 v208, 0x1c000, v137
	ds_read_b128 v[196:199], v208
	ds_read_b128 v[200:203], v208 offset:1024
	ds_read_b128 v[204:207], v208 offset:2048
	ds_read_b128 v[208:211], v208 offset:3072
	s_add_u32 s22, s17, s2
	s_addc_u32 s23, s18, s3
	s_add_u32 s22, s22, 0x100
	s_addc_u32 s23, s23, 0
	s_add_i32 s36, s14, 0x4000
	s_mov_b32 m0, s36
	s_nop 0
	global_load_lds_dwordx4 v136, s[22:23]
	s_add_i32 s36, s14, 0x6000
	s_mov_b32 m0, s36
	s_nop 0
	global_load_lds_dwordx4 v135, s[22:23]
	s_waitcnt vmcnt(8) lgkmcnt(0)
	s_setprio 1
	s_barrier
	v_mfma_f32_16x16x32_bf16 v[126:129], v[162:165], v[138:141], v[126:129]
	v_mfma_f32_16x16x32_bf16 v[122:125], v[162:165], v[154:157], v[122:125]
	v_mfma_f32_16x16x32_bf16 v[114:117], v[170:173], v[154:157], v[114:117]
	v_mfma_f32_16x16x32_bf16 v[118:121], v[170:173], v[138:141], v[118:121]
	v_mfma_f32_16x16x32_bf16 v[110:113], v[180:183], v[138:141], v[110:113]
	v_mfma_f32_16x16x32_bf16 v[106:109], v[180:183], v[154:157], v[106:109]
	v_mfma_f32_16x16x32_bf16 v[98:101], v[188:191], v[154:157], v[98:101]
	v_mfma_f32_16x16x32_bf16 v[102:105], v[188:191], v[138:141], v[102:105]
	v_mfma_f32_16x16x32_bf16 v[126:129], v[166:169], v[142:145], v[126:129]
	v_mfma_f32_16x16x32_bf16 v[122:125], v[166:169], v[158:161], v[122:125]
	v_mfma_f32_16x16x32_bf16 v[114:117], v[174:177], v[158:161], v[114:117]
	v_mfma_f32_16x16x32_bf16 v[118:121], v[174:177], v[142:145], v[118:121]
	v_mfma_f32_16x16x32_bf16 v[110:113], v[184:187], v[142:145], v[110:113]
	v_mfma_f32_16x16x32_bf16 v[106:109], v[184:187], v[158:161], v[106:109]
	v_mfma_f32_16x16x32_bf16 v[98:101], v[192:195], v[158:161], v[98:101]
	v_mfma_f32_16x16x32_bf16 v[102:105], v[192:195], v[142:145], v[102:105]
	v_mfma_f32_16x16x32_bf16 v[94:97], v[162:165], v[196:199], v[94:97]
	v_mfma_f32_16x16x32_bf16 v[90:93], v[162:165], v[204:207], v[90:93]
	v_mfma_f32_16x16x32_bf16 v[82:85], v[170:173], v[204:207], v[82:85]
	v_mfma_f32_16x16x32_bf16 v[86:89], v[170:173], v[196:199], v[86:89]
	v_mfma_f32_16x16x32_bf16 v[78:81], v[180:183], v[196:199], v[78:81]
	v_mfma_f32_16x16x32_bf16 v[74:77], v[180:183], v[204:207], v[74:77]
	v_mfma_f32_16x16x32_bf16 v[66:69], v[188:191], v[204:207], v[66:69]
	v_mfma_f32_16x16x32_bf16 v[70:73], v[188:191], v[196:199], v[70:73]
	v_mfma_f32_16x16x32_bf16 v[94:97], v[166:169], v[200:203], v[94:97]
	v_mfma_f32_16x16x32_bf16 v[90:93], v[166:169], v[208:211], v[90:93]
	v_mfma_f32_16x16x32_bf16 v[82:85], v[174:177], v[208:211], v[82:85]
	v_mfma_f32_16x16x32_bf16 v[86:89], v[174:177], v[200:203], v[86:89]
	v_mfma_f32_16x16x32_bf16 v[78:81], v[184:187], v[200:203], v[78:81]
	v_mfma_f32_16x16x32_bf16 v[74:77], v[184:187], v[208:211], v[74:77]
	v_mfma_f32_16x16x32_bf16 v[66:69], v[192:195], v[208:211], v[66:69]
	v_mfma_f32_16x16x32_bf16 v[70:73], v[192:195], v[200:203], v[70:73]
	s_barrier
	s_setprio 0
	ds_read_b128 v[162:165], v134 offset:49152
	ds_read_b128 v[166:169], v134 offset:50176
	ds_read_b128 v[170:173], v134 offset:51200
	ds_read_b128 v[174:177], v134 offset:52224
	ds_read_b128 v[180:183], v134 offset:53248
	ds_read_b128 v[184:187], v134 offset:54272
	ds_read_b128 v[188:191], v134 offset:55296
	ds_read_b128 v[192:195], v134 offset:56320
	s_add_u32 s22, s24, s2
	s_addc_u32 s23, s25, s3
	s_add_u32 s22, s22, 0x180
	s_addc_u32 s23, s23, 0
	s_add_i32 s36, s14, 0x18000
	s_mov_b32 m0, s36
	s_nop 0
	global_load_lds_dwordx4 v136, s[22:23]
	s_add_i32 s36, s14, 0x1a000
	s_mov_b32 m0, s36
	s_nop 0
	global_load_lds_dwordx4 v135, s[22:23]
	s_add_u32 s22, s9, s2
	s_addc_u32 s23, s12, s3
	s_add_u32 s22, s22, 0x180
	s_addc_u32 s23, s23, 0
	s_add_i32 s36, s14, 0x8000
	s_mov_b32 m0, s36
	s_nop 0
	global_load_lds_dwordx4 v136, s[22:23]
	s_add_i32 s36, s14, 0xa000
	s_mov_b32 m0, s36
	s_nop 0
	global_load_lds_dwordx4 v135, s[22:23]
	s_add_u32 s22, s26, s2
	s_addc_u32 s23, s27, s3
	s_add_u32 s22, s22, 0x180
	s_addc_u32 s23, s23, 0
	s_add_i32 s36, s14, 0x1c000
	s_mov_b32 m0, s36
	s_nop 0
	global_load_lds_dwordx4 v136, s[22:23]
	s_add_i32 s36, s14, 0x1e000
	s_mov_b32 m0, s36
	s_nop 0
	global_load_lds_dwordx4 v135, s[22:23]
	s_waitcnt vmcnt(8) lgkmcnt(0)
	s_setprio 1
	s_barrier
	v_mfma_f32_16x16x32_bf16 v[62:65], v[162:165], v[138:141], v[62:65]
	v_mfma_f32_16x16x32_bf16 v[58:61], v[162:165], v[154:157], v[58:61]
	v_mfma_f32_16x16x32_bf16 v[50:53], v[170:173], v[154:157], v[50:53]
	v_mfma_f32_16x16x32_bf16 v[54:57], v[170:173], v[138:141], v[54:57]
	v_mfma_f32_16x16x32_bf16 v[46:49], v[180:183], v[138:141], v[46:49]
	v_mfma_f32_16x16x32_bf16 v[42:45], v[180:183], v[154:157], v[42:45]
	v_mfma_f32_16x16x32_bf16 v[34:37], v[188:191], v[154:157], v[34:37]
	v_mfma_f32_16x16x32_bf16 v[38:41], v[188:191], v[138:141], v[38:41]
	v_mfma_f32_16x16x32_bf16 v[62:65], v[166:169], v[142:145], v[62:65]
	v_mfma_f32_16x16x32_bf16 v[58:61], v[166:169], v[158:161], v[58:61]
	v_mfma_f32_16x16x32_bf16 v[50:53], v[174:177], v[158:161], v[50:53]
	v_mfma_f32_16x16x32_bf16 v[54:57], v[174:177], v[142:145], v[54:57]
	v_mfma_f32_16x16x32_bf16 v[46:49], v[184:187], v[142:145], v[46:49]
	v_mfma_f32_16x16x32_bf16 v[42:45], v[184:187], v[158:161], v[42:45]
	v_mfma_f32_16x16x32_bf16 v[34:37], v[192:195], v[158:161], v[34:37]
	v_mfma_f32_16x16x32_bf16 v[38:41], v[192:195], v[142:145], v[38:41]
	v_mfma_f32_16x16x32_bf16 v[30:33], v[162:165], v[196:199], v[30:33]
	v_mfma_f32_16x16x32_bf16 v[26:29], v[162:165], v[204:207], v[26:29]
	v_mfma_f32_16x16x32_bf16 v[18:21], v[170:173], v[204:207], v[18:21]
	v_mfma_f32_16x16x32_bf16 v[22:25], v[170:173], v[196:199], v[22:25]
	v_mfma_f32_16x16x32_bf16 v[14:17], v[180:183], v[196:199], v[14:17]
	v_mfma_f32_16x16x32_bf16 v[10:13], v[180:183], v[204:207], v[10:13]
	v_mfma_f32_16x16x32_bf16 v[2:5], v[188:191], v[204:207], v[2:5]
	v_mfma_f32_16x16x32_bf16 v[6:9], v[188:191], v[196:199], v[6:9]
	v_mfma_f32_16x16x32_bf16 v[30:33], v[166:169], v[200:203], v[30:33]
	v_mfma_f32_16x16x32_bf16 v[26:29], v[166:169], v[208:211], v[26:29]
	v_mfma_f32_16x16x32_bf16 v[18:21], v[174:177], v[208:211], v[18:21]
	v_mfma_f32_16x16x32_bf16 v[22:25], v[174:177], v[200:203], v[22:25]
	v_mfma_f32_16x16x32_bf16 v[14:17], v[184:187], v[200:203], v[14:17]
	v_mfma_f32_16x16x32_bf16 v[10:13], v[184:187], v[208:211], v[10:13]
	v_mfma_f32_16x16x32_bf16 v[2:5], v[192:195], v[208:211], v[2:5]
	v_mfma_f32_16x16x32_bf16 v[6:9], v[192:195], v[200:203], v[6:9]
	s_barrier
	s_setprio 0
	s_add_i32 s19, s19, 2
	s_add_u32 s2, s2, 0x100
	s_addc_u32 s3, s3, 0
	s_cmp_lt_u32 s19, 12
	s_cbranch_scc1 .Lk_conv_out

; #define WAIT_L(n) asm volatile("s_waitcnt lgkmcnt(" #n ")" ::: "memory")
; #define BAR __builtin_amdgcn_s_barrier()
; #define SCHED __builtin_amdgcn_sched_barrier(0)
; #define STG_A(b, h, kt) stage_half_s(lds0 + ((b) * 2 + (h)) * HT_B, ((h) ? A1 : Ap) + (kt) * BK, off0, off1)
; #define STG_B(b, h, kt) stage_half_s(lds0 + (4 + (b) * 2 + (h)) * HT_B, ((h) ? B1p : Bp) + (kt) * BK, off0, off1)
; #define STG_A(b, h, kt) stage_half_s(lds0 + ((b) * 2 + (h)) * HT_B, ((h) ? A1 : Ap) + (kt) * BK, off0, off1)
; #define STG_B(b, h, kt) stage_half_s(lds0 + (4 + (b) * 2 + (h)) * HT_B, ((h) ? B1p : Bp) + (kt) * BK, off0, off1)
; #define LDA8(b, h) _Pragma("unroll") for (int m = 0; m < 4; ++m) _Pragma("unroll") for (int k = 0; k < 2; ++k) \
;     At[m][k] = *(const bf16x8*)(SA_(shm, b, h) + abase + (m * 2 + k) * 1024)
; #define LDB8(dst, b, h) _Pragma("unroll") for (int n = 0; n < 2; ++n) _Pragma("unroll") for (int k = 0; k < 2; ++k) \
;     dst[n][k] = *(const bf16x8*)(SB_(shm, b, h) + bbase + (n * 2 + k) * 1024)
; template <bool HS>
; __device__ __forceinline__ void gemm_tile8(const u16* __restrict__ Ap, const u16* __restrict__ Bp, int K,
;                                            f32x4 (&acc)[2][2][4][2], char* shm, const int tid, const float* hsr = nullptr) {
;     ...
;   stage_rc(tid * 16, r0, c0);
;   stage_rc(tid * 16 + 8192, r1, c1);
;   const unsigned off0 = (unsigned)(r0 * K + c0) * 2u, off1 = (unsigned)(r1 * K + c1) * 2u;
;   const int wvoff = __builtin_amdgcn_readfirstlane(tid >> 6) * 1024;
;   const u16* A1 = Ap + (size_t)128 * K;
;   const u16* B1p = Bp + (size_t)128 * K;
; #pragma unroll
;   for (int a = 0; a < 2; ++a)
; #pragma unroll
;     for (int b = 0; b < 2; ++b)
; #pragma unroll
;       for (int m = 0; m < 4; ++m)
; #pragma unroll
;         for (int n = 0; n < 2; ++n) acc[a][b][m][n] = f32x4{0.f, 0.f, 0.f, 0.f};
;   const int abase = lds_byte(wr * 64 + fr, fq * 8), bbase = lds_byte(wc * 32 + fr, fq * 8);
;   bf16x8 At[4][2], B0[2][2], B1[2][2];
;   const unsigned lds0 = (unsigned)(size_t)(__attribute__((address_space(3))) char*)shm + (unsigned)wvoff;
;     ...
;     LDB8(B0, 0, 0); SCHED; LDA8(0, 0); STG_A(1, 1, t + 1);
;     WAIT_L(8); BAR; WAIT_L(0); MMA8(0, 0, B0); BAR; SCHED;
;     LDB8(B1, 0, 1); STG_B(0, 0, t + 2);
;     BAR; WAIT_L(0); MMA8(0, 1, B1); BAR;
.LBB0_317:
	s_or_b64 exec, exec, s[6:7]
	v_mov_b32_e32 v4, s11
	v_bfe_i32 v4, v4, 0, 8
	v_ashrrev_i32_e32 v5, 31, v4
	v_lshlrev_b64 v[4:5], 19, v[4:5]
	v_bfe_i32 v6, v0, 27, 1
	v_lshl_add_u64 v[130:131], s[0:1], 0, v[4:5]
	v_lshlrev_b32_e32 v4, 4, v0
	v_lshrrev_b32_e32 v6, 22, v6
	v_add_u32_e32 v6, v4, v6
	v_and_b32_e32 v6, 0xfffffc00, v6
	v_ashrrev_i32_e32 v5, 31, v0
	v_sub_u32_e32 v6, v4, v6
	v_lshrrev_b32_e32 v5, 26, v5
	v_lshrrev_b32_e32 v7, 4, v6
	v_add_u32_e32 v5, v0, v5
	v_bitop3_b32 v7, v7, v6, 32 bitop3:0x6c
	v_ashrrev_i32_e32 v6, 31, v6
	v_ashrrev_i32_e32 v5, 6, v5
	v_lshrrev_b32_e32 v6, 26, v6
	v_lshlrev_b32_e32 v8, 3, v5
	v_add_u32_e32 v6, v7, v6
	v_and_b32_e32 v8, 0x1ffff0, v8
	v_ashrrev_i32_e32 v6, 6, v6
	v_add_u32_e32 v8, v6, v8
	v_mul_i32_i24_e32 v6, 64, v6
	v_add_u32_e32 v4, 0x2000, v4
	v_sub_u32_e32 v6, v7, v6
	v_ashrrev_i32_e32 v7, 31, v4
	v_lshrrev_b32_e32 v7, 22, v7
	v_add_u32_e32 v7, v4, v7
	v_ashrrev_i32_e32 v7, 10, v7
	v_mul_i32_i24_e32 v9, 0x400, v7
	v_sub_u32_e32 v4, v4, v9
	v_lshrrev_b32_e32 v9, 4, v4
	v_bitop3_b32 v4, v9, v4, 32 bitop3:0x6c
	v_ashrrev_i32_e32 v10, 31, v4
	v_lshrrev_b32_e32 v10, 26, v10
	v_add_u32_e32 v10, v4, v10
	v_lshlrev_b32_e32 v9, 3, v7
	v_lshrrev_b32_e32 v11, 6, v10
	v_and_b32_e32 v10, 0xc0, v10
	s_ashr_i32 s5, s4, 31
	v_and_b32_e32 v9, 0x1ffff0, v9
	v_lshlrev_b32_e32 v7, 5, v7
	v_sub_u32_e32 v4, v4, v10
	s_lshl_b64 s[6:7], s[4:5], 11
	v_lshlrev_b32_e32 v5, 5, v5
	v_add_u32_e32 v9, v11, v9
	v_and_b32_e32 v7, 32, v7
	v_ashrrev_i16_sdwa v4, v178, sext(v4) dst_sel:DWORD dst_unused:UNUSED_PAD src0_sel:DWORD src1_sel:BYTE_0
	s_add_u32 s8, s88, s6
	v_and_b32_e32 v5, 32, v5
	v_ashrrev_i16_sdwa v6, v178, sext(v6) dst_sel:DWORD dst_unused:UNUSED_PAD src0_sel:DWORD src1_sel:BYTE_0
	v_bfe_i32 v4, v4, 0, 16
	v_lshl_or_b32 v7, v9, 10, v7
	s_addc_u32 s9, s89, s7
	v_bfe_i32 v6, v6, 0, 16
	v_lshl_or_b32 v5, v8, 10, v5
	v_and_b32_e32 v8, 15, v0
	v_add_lshl_u32 v139, v7, v4, 1
	s_lshl_b32 s10, s10, 10
	v_lshlrev_b32_e32 v7, 2, v0
	v_add_lshl_u32 v140, v5, v6, 1
	s_mov_b64 s[4:5], 0x40000
	v_and_b32_e32 v4, 48, v0
	v_lshlrev_b32_e32 v5, 6, v8
	v_and_b32_e32 v7, 32, v7
	s_add_i32 s11, s10, 0
	v_lshl_add_u64 v[132:133], v[130:131], 0, s[4:5]
	v_or_b32_e32 v6, v5, v4
	v_bitop3_b32 v4, v5, v7, v4 bitop3:0x36
	v_lshlrev_b32_e32 v2, 12, v2
	s_movk_i32 s4, 0x3000
	s_add_u32 s13, s8, 0x40100
	v_lshlrev_b32_e32 v3, 13, v3
	v_and_or_b32 v141, v2, s4, v4
	s_addc_u32 s14, s9, 0
	v_readlane_b32 s4, v254, 34
	v_bitop3_b32 v3, v6, v3, v7 bitop3:0xde
	s_add_u32 s15, s4, s6
	v_readlane_b32 s4, v254, 35
	v_mov_b32_e32 v2, 0
	s_addc_u32 s16, s4, s7
	s_mov_b32 s17, -2
	s_mov_b64 s[4:5], 0
	v_add_u32_e32 v138, 0, v3
	s_waitcnt lgkmcnt(0)
	v_readfirstlane_b32 s24, v130
	v_readfirstlane_b32 s25, v131
	v_readfirstlane_b32 s22, v132
	v_readfirstlane_b32 s23, v133
	s_barrier
	s_barrier
	v_add_u32_e32 v154, 0x10000, v141
	ds_read_b128 v[142:145], v154
	ds_read_b128 v[146:149], v154 offset:1024
	ds_read_b128 v[150:153], v154 offset:2048
	ds_read_b128 v[154:157], v154 offset:3072
	ds_read_b128 v[158:161], v138
	ds_read_b128 v[162:165], v138 offset:1024
	ds_read_b128 v[166:169], v138 offset:2048
	ds_read_b128 v[170:173], v138 offset:3072
	ds_read_b128 v[174:177], v138 offset:4096
	ds_read_b128 v[180:183], v138 offset:5120
	ds_read_b128 v[184:187], v138 offset:6144
	ds_read_b128 v[188:191], v138 offset:7168
	v_add_u32_e32 v204, 0x14000, v141
	ds_read_b128 v[192:195], v204
	ds_read_b128 v[196:199], v204 offset:1024
	ds_read_b128 v[200:203], v204 offset:2048
	ds_read_b128 v[204:207], v204 offset:3072
	s_add_u32 s20, s15, s4
	s_addc_u32 s21, s16, s5
	s_add_u32 s20, s20, 0x80
	s_addc_u32 s21, s21, 0
	s_add_i32 s18, s11, 0xc000
	s_mov_b32 m0, s18
	s_nop 0
	global_load_lds_dwordx4 v140, s[20:21]
	s_add_i32 s18, s11, 0xe000
	s_mov_b32 m0, s18
	s_nop 0
	global_load_lds_dwordx4 v139, s[20:21]
	s_waitcnt vmcnt(8) lgkmcnt(0)
	s_setprio 1
	s_barrier
	v_mfma_f32_16x16x32_bf16 v[126:129], v[158:161], v[142:145], 0
	v_mfma_f32_16x16x32_bf16 v[122:125], v[158:161], v[150:153], 0
	v_mfma_f32_16x16x32_bf16 v[114:117], v[166:169], v[150:153], 0
	v_mfma_f32_16x16x32_bf16 v[118:121], v[166:169], v[142:145], 0
	v_mfma_f32_16x16x32_bf16 v[110:113], v[174:177], v[142:145], 0
	v_mfma_f32_16x16x32_bf16 v[106:109], v[174:177], v[150:153], 0
	v_mfma_f32_16x16x32_bf16 v[98:101], v[184:187], v[150:153], 0
	v_mfma_f32_16x16x32_bf16 v[102:105], v[184:187], v[142:145], 0
	v_mfma_f32_16x16x32_bf16 v[126:129], v[162:165], v[146:149], v[126:129]
	v_mfma_f32_16x16x32_bf16 v[122:125], v[162:165], v[154:157], v[122:125]
	v_mfma_f32_16x16x32_bf16 v[114:117], v[170:173], v[154:157], v[114:117]
	v_mfma_f32_16x16x32_bf16 v[118:121], v[170:173], v[146:149], v[118:121]
	v_mfma_f32_16x16x32_bf16 v[110:113], v[180:183], v[146:149], v[110:113]
	v_mfma_f32_16x16x32_bf16 v[106:109], v[180:183], v[154:157], v[106:109]
	v_mfma_f32_16x16x32_bf16 v[98:101], v[188:191], v[154:157], v[98:101]
	v_mfma_f32_16x16x32_bf16 v[102:105], v[188:191], v[146:149], v[102:105]
	v_mfma_f32_16x16x32_bf16 v[94:97], v[158:161], v[192:195], 0
	v_mfma_f32_16x16x32_bf16 v[90:93], v[158:161], v[200:203], 0
	v_mfma_f32_16x16x32_bf16 v[82:85], v[166:169], v[200:203], 0
	v_mfma_f32_16x16x32_bf16 v[86:89], v[166:169], v[192:195], 0
	v_mfma_f32_16x16x32_bf16 v[78:81], v[174:177], v[192:195], 0
	v_mfma_f32_16x16x32_bf16 v[74:77], v[174:177], v[200:203], 0
	v_mfma_f32_16x16x32_bf16 v[66:69], v[184:187], v[200:203], 0
	v_mfma_f32_16x16x32_bf16 v[70:73], v[184:187], v[192:195], 0
	v_mfma_f32_16x16x32_bf16 v[94:97], v[162:165], v[196:199], v[94:97]
	v_mfma_f32_16x16x32_bf16 v[90:93], v[162:165], v[204:207], v[90:93]
	v_mfma_f32_16x16x32_bf16 v[82:85], v[170:173], v[204:207], v[82:85]
	v_mfma_f32_16x16x32_bf16 v[86:89], v[170:173], v[196:199], v[86:89]
	v_mfma_f32_16x16x32_bf16 v[78:81], v[180:183], v[196:199], v[78:81]
	v_mfma_f32_16x16x32_bf16 v[74:77], v[180:183], v[204:207], v[74:77]
	v_mfma_f32_16x16x32_bf16 v[66:69], v[188:191], v[204:207], v[66:69]
	v_mfma_f32_16x16x32_bf16 v[70:73], v[188:191], v[196:199], v[70:73]
	s_barrier
; #define WAIT_V(n) asm volatile("s_waitcnt vmcnt(" #n ")" ::: "memory")
; #define WAIT_L(n) asm volatile("s_waitcnt lgkmcnt(" #n ")" ::: "memory")
; #define BAR __builtin_amdgcn_s_barrier()
; #define SCHED __builtin_amdgcn_sched_barrier(0)
; #define STG_A(b, h, kt) stage_half_s(lds0 + ((b) * 2 + (h)) * HT_B, ((h) ? A1 : Ap) + (kt) * BK, off0, off1)
; #define STG_B(b, h, kt) stage_half_s(lds0 + (4 + (b) * 2 + (h)) * HT_B, ((h) ? B1p : Bp) + (kt) * BK, off0, off1)
; #define STG_A(b, h, kt) stage_half_s(lds0 + ((b) * 2 + (h)) * HT_B, ((h) ? A1 : Ap) + (kt) * BK, off0, off1)
; #define STG_B(b, h, kt) stage_half_s(lds0 + (4 + (b) * 2 + (h)) * HT_B, ((h) ? B1p : Bp) + (kt) * BK, off0, off1)
; #define LDA8(b, h) _Pragma("unroll") for (int m = 0; m < 4; ++m) _Pragma("unroll") for (int k = 0; k < 2; ++k) \
;     At[m][k] = *(const bf16x8*)(SA_(shm, b, h) + abase + (m * 2 + k) * 1024)
; #define LDB8(dst, b, h) _Pragma("unroll") for (int n = 0; n < 2; ++n) _Pragma("unroll") for (int k = 0; k < 2; ++k) \
;     dst[n][k] = *(const bf16x8*)(SB_(shm, b, h) + bbase + (n * 2 + k) * 1024)
; #define MMA8(ai, bj, Bx) do { __builtin_amdgcn_s_setprio(1); \
;     _Pragma("unroll") for (int m = 0; m < 4; ++m) _Pragma("unroll") for (int n = 0; n < 2; ++n) _Pragma("unroll") for (int k = 0; k < 2; ++k) \
;       acc[ai][bj][m][n] = __builtin_amdgcn_mfma_f32_16x16x32_bf16(At[m][k], Bx[n][k], acc[ai][bj][m][n], 0, 0, 0); \
;     __builtin_amdgcn_s_setprio(0); } while (0)
; template <bool HS>
; __device__ __forceinline__ void gemm_tile8(const u16* __restrict__ Ap, const u16* __restrict__ Bp, int K,
;                                            f32x4 (&acc)[2][2][4][2], char* shm, const int tid, const float* hsr = nullptr) {
;     ...
;     LDA8(0, 1); STG_A(0, 0, t + 2);
;     BAR; WAIT_L(0); MMA8(1, 0, B0); BAR; SCHED;
;     STG_B(0, 1, t + 2);
;     WAIT_V(6); BAR; MMA8(1, 1, B1); BAR;
;     LDB8(B0, 1, 0); SCHED; LDA8(1, 0); STG_A(0, 1, t + 2);
;     WAIT_L(8); BAR; WAIT_L(0); MMA8(0, 0, B0); BAR; SCHED;
;     LDB8(B1, 1, 1); STG_B(1, 0, t + 3);
;     BAR; WAIT_L(0); MMA8(0, 1, B1); BAR;
	s_setprio 0
	ds_read_b128 v[158:161], v138 offset:16384
	ds_read_b128 v[162:165], v138 offset:17408
	ds_read_b128 v[166:169], v138 offset:18432
	ds_read_b128 v[170:173], v138 offset:19456
	ds_read_b128 v[174:177], v138 offset:20480
	ds_read_b128 v[180:183], v138 offset:21504
	ds_read_b128 v[184:187], v138 offset:22528
	ds_read_b128 v[188:191], v138 offset:23552
	s_add_u32 s20, s24, s4
	s_addc_u32 s21, s25, s5
	s_add_u32 s20, s20, 0x100
	s_addc_u32 s21, s21, 0
	s_add_i32 s18, s11, 0x10000
	s_mov_b32 m0, s18
	s_nop 0
	global_load_lds_dwordx4 v140, s[20:21]
	s_add_i32 s18, s11, 0x12000
	s_mov_b32 m0, s18
	s_nop 0
	global_load_lds_dwordx4 v139, s[20:21]
	s_add_u32 s20, s8, s4
	s_addc_u32 s21, s9, s5
	s_add_u32 s20, s20, 0x100
	s_addc_u32 s21, s21, 0
	s_mov_b32 m0, s11
	s_nop 0
	global_load_lds_dwordx4 v140, s[20:21]
	s_add_i32 s18, s11, 0x2000
	s_mov_b32 m0, s18
	s_nop 0
	global_load_lds_dwordx4 v139, s[20:21]
	s_add_u32 s20, s22, s4
	s_addc_u32 s21, s23, s5
	s_add_u32 s20, s20, 0x100
	s_addc_u32 s21, s21, 0
	s_add_i32 s18, s11, 0x14000
	s_mov_b32 m0, s18
	s_nop 0
	global_load_lds_dwordx4 v140, s[20:21]
	s_add_i32 s18, s11, 0x16000
	s_mov_b32 m0, s18
	s_nop 0
	global_load_lds_dwordx4 v139, s[20:21]
	s_waitcnt vmcnt(8) lgkmcnt(0)
	s_setprio 1
	s_barrier
	v_mfma_f32_16x16x32_bf16 v[62:65], v[158:161], v[142:145], 0
	v_mfma_f32_16x16x32_bf16 v[58:61], v[158:161], v[150:153], 0
	v_mfma_f32_16x16x32_bf16 v[50:53], v[166:169], v[150:153], 0
	v_mfma_f32_16x16x32_bf16 v[54:57], v[166:169], v[142:145], 0
	v_mfma_f32_16x16x32_bf16 v[46:49], v[174:177], v[142:145], 0
	v_mfma_f32_16x16x32_bf16 v[42:45], v[174:177], v[150:153], 0
	v_mfma_f32_16x16x32_bf16 v[34:37], v[184:187], v[150:153], 0
	v_mfma_f32_16x16x32_bf16 v[38:41], v[184:187], v[142:145], 0
	v_mfma_f32_16x16x32_bf16 v[62:65], v[162:165], v[146:149], v[62:65]
	v_mfma_f32_16x16x32_bf16 v[58:61], v[162:165], v[154:157], v[58:61]
	v_mfma_f32_16x16x32_bf16 v[50:53], v[170:173], v[154:157], v[50:53]
	v_mfma_f32_16x16x32_bf16 v[54:57], v[170:173], v[146:149], v[54:57]
	v_mfma_f32_16x16x32_bf16 v[46:49], v[180:183], v[146:149], v[46:49]
	v_mfma_f32_16x16x32_bf16 v[42:45], v[180:183], v[154:157], v[42:45]
	v_mfma_f32_16x16x32_bf16 v[34:37], v[188:191], v[154:157], v[34:37]
	v_mfma_f32_16x16x32_bf16 v[38:41], v[188:191], v[146:149], v[38:41]
	v_mfma_f32_16x16x32_bf16 v[30:33], v[158:161], v[192:195], 0
	v_mfma_f32_16x16x32_bf16 v[26:29], v[158:161], v[200:203], 0
	v_mfma_f32_16x16x32_bf16 v[18:21], v[166:169], v[200:203], 0
	v_mfma_f32_16x16x32_bf16 v[22:25], v[166:169], v[192:195], 0
	v_mfma_f32_16x16x32_bf16 v[14:17], v[174:177], v[192:195], 0
	v_mfma_f32_16x16x32_bf16 v[10:13], v[174:177], v[200:203], 0
	v_mfma_f32_16x16x32_bf16 v[2:5], v[184:187], v[200:203], 0
	v_mfma_f32_16x16x32_bf16 v[6:9], v[184:187], v[192:195], 0
	v_mfma_f32_16x16x32_bf16 v[30:33], v[162:165], v[196:199], v[30:33]
	v_mfma_f32_16x16x32_bf16 v[26:29], v[162:165], v[204:207], v[26:29]
	v_mfma_f32_16x16x32_bf16 v[18:21], v[170:173], v[204:207], v[18:21]
	v_mfma_f32_16x16x32_bf16 v[22:25], v[170:173], v[196:199], v[22:25]
	v_mfma_f32_16x16x32_bf16 v[14:17], v[180:183], v[196:199], v[14:17]
	v_mfma_f32_16x16x32_bf16 v[10:13], v[180:183], v[204:207], v[10:13]
	v_mfma_f32_16x16x32_bf16 v[2:5], v[188:191], v[204:207], v[2:5]
	v_mfma_f32_16x16x32_bf16 v[6:9], v[188:191], v[196:199], v[6:9]
	s_barrier
	s_setprio 0
	v_add_u32_e32 v154, 0x18000, v141
	ds_read_b128 v[142:145], v154
	ds_read_b128 v[146:149], v154 offset:1024
	ds_read_b128 v[150:153], v154 offset:2048
	ds_read_b128 v[154:157], v154 offset:3072
	ds_read_b128 v[158:161], v138 offset:32768
	ds_read_b128 v[162:165], v138 offset:33792
	ds_read_b128 v[166:169], v138 offset:34816
	ds_read_b128 v[170:173], v138 offset:35840
	ds_read_b128 v[174:177], v138 offset:36864
	ds_read_b128 v[180:183], v138 offset:37888
	ds_read_b128 v[184:187], v138 offset:38912
	ds_read_b128 v[188:191], v138 offset:39936
	v_add_u32_e32 v204, 0x1c000, v141
	ds_read_b128 v[192:195], v204
	ds_read_b128 v[196:199], v204 offset:1024
	ds_read_b128 v[200:203], v204 offset:2048
	ds_read_b128 v[204:207], v204 offset:3072
	s_add_u32 s20, s15, s4
	s_addc_u32 s21, s16, s5
	s_add_u32 s20, s20, 0x100
	s_addc_u32 s21, s21, 0
	s_add_i32 s18, s11, 0x4000
	s_mov_b32 m0, s18
	s_nop 0
	global_load_lds_dwordx4 v140, s[20:21]
	s_add_i32 s18, s11, 0x6000
	s_mov_b32 m0, s18
	s_nop 0
	global_load_lds_dwordx4 v139, s[20:21]
	s_waitcnt vmcnt(8) lgkmcnt(0)
	s_setprio 1
	s_barrier
	v_mfma_f32_16x16x32_bf16 v[126:129], v[158:161], v[142:145], v[126:129]
	v_mfma_f32_16x16x32_bf16 v[122:125], v[158:161], v[150:153], v[122:125]
	v_mfma_f32_16x16x32_bf16 v[114:117], v[166:169], v[150:153], v[114:117]
	v_mfma_f32_16x16x32_bf16 v[118:121], v[166:169], v[142:145], v[118:121]
	v_mfma_f32_16x16x32_bf16 v[110:113], v[174:177], v[142:145], v[110:113]
	v_mfma_f32_16x16x32_bf16 v[106:109], v[174:177], v[150:153], v[106:109]
	v_mfma_f32_16x16x32_bf16 v[98:101], v[184:187], v[150:153], v[98:101]
	v_mfma_f32_16x16x32_bf16 v[102:105], v[184:187], v[142:145], v[102:105]
	v_mfma_f32_16x16x32_bf16 v[126:129], v[162:165], v[146:149], v[126:129]
	v_mfma_f32_16x16x32_bf16 v[122:125], v[162:165], v[154:157], v[122:125]
	v_mfma_f32_16x16x32_bf16 v[114:117], v[170:173], v[154:157], v[114:117]
	v_mfma_f32_16x16x32_bf16 v[118:121], v[170:173], v[146:149], v[118:121]
	v_mfma_f32_16x16x32_bf16 v[110:113], v[180:183], v[146:149], v[110:113]
	v_mfma_f32_16x16x32_bf16 v[106:109], v[180:183], v[154:157], v[106:109]
	v_mfma_f32_16x16x32_bf16 v[98:101], v[188:191], v[154:157], v[98:101]
	v_mfma_f32_16x16x32_bf16 v[102:105], v[188:191], v[146:149], v[102:105]
	v_mfma_f32_16x16x32_bf16 v[94:97], v[158:161], v[192:195], v[94:97]
	v_mfma_f32_16x16x32_bf16 v[90:93], v[158:161], v[200:203], v[90:93]
	v_mfma_f32_16x16x32_bf16 v[82:85], v[166:169], v[200:203], v[82:85]
	v_mfma_f32_16x16x32_bf16 v[86:89], v[166:169], v[192:195], v[86:89]
	v_mfma_f32_16x16x32_bf16 v[78:81], v[174:177], v[192:195], v[78:81]
	v_mfma_f32_16x16x32_bf16 v[74:77], v[174:177], v[200:203], v[74:77]
	v_mfma_f32_16x16x32_bf16 v[66:69], v[184:187], v[200:203], v[66:69]
	v_mfma_f32_16x16x32_bf16 v[70:73], v[184:187], v[192:195], v[70:73]
	v_mfma_f32_16x16x32_bf16 v[94:97], v[162:165], v[196:199], v[94:97]
	v_mfma_f32_16x16x32_bf16 v[90:93], v[162:165], v[204:207], v[90:93]
	v_mfma_f32_16x16x32_bf16 v[82:85], v[170:173], v[204:207], v[82:85]
	v_mfma_f32_16x16x32_bf16 v[86:89], v[170:173], v[196:199], v[86:89]
	v_mfma_f32_16x16x32_bf16 v[78:81], v[180:183], v[196:199], v[78:81]
	v_mfma_f32_16x16x32_bf16 v[74:77], v[180:183], v[204:207], v[74:77]
	v_mfma_f32_16x16x32_bf16 v[66:69], v[188:191], v[204:207], v[66:69]
	v_mfma_f32_16x16x32_bf16 v[70:73], v[188:191], v[196:199], v[70:73]
	s_barrier
; #define WAIT_V(n) asm volatile("s_waitcnt vmcnt(" #n ")" ::: "memory")
; #define WAIT_L(n) asm volatile("s_waitcnt lgkmcnt(" #n ")" ::: "memory")
; #define BAR __builtin_amdgcn_s_barrier()
; #define SCHED __builtin_amdgcn_sched_barrier(0)
; #define STG_A(b, h, kt) stage_half_s(lds0 + ((b) * 2 + (h)) * HT_B, ((h) ? A1 : Ap) + (kt) * BK, off0, off1)
; #define STG_B(b, h, kt) stage_half_s(lds0 + (4 + (b) * 2 + (h)) * HT_B, ((h) ? B1p : Bp) + (kt) * BK, off0, off1)
; #define STG_A(b, h, kt) stage_half_s(lds0 + ((b) * 2 + (h)) * HT_B, ((h) ? A1 : Ap) + (kt) * BK, off0, off1)
; #define STG_B(b, h, kt) stage_half_s(lds0 + (4 + (b) * 2 + (h)) * HT_B, ((h) ? B1p : Bp) + (kt) * BK, off0, off1)
; #define LDA8(b, h) _Pragma("unroll") for (int m = 0; m < 4; ++m) _Pragma("unroll") for (int k = 0; k < 2; ++k) \
;     At[m][k] = *(const bf16x8*)(SA_(shm, b, h) + abase + (m * 2 + k) * 1024)
; #define LDB8(dst, b, h) _Pragma("unroll") for (int n = 0; n < 2; ++n) _Pragma("unroll") for (int k = 0; k < 2; ++k) \
;     dst[n][k] = *(const bf16x8*)(SB_(shm, b, h) + bbase + (n * 2 + k) * 1024)
; #define MMA8(ai, bj, Bx) do { __builtin_amdgcn_s_setprio(1); \
;     _Pragma("unroll") for (int m = 0; m < 4; ++m) _Pragma("unroll") for (int n = 0; n < 2; ++n) _Pragma("unroll") for (int k = 0; k < 2; ++k) \
;       acc[ai][bj][m][n] = __builtin_amdgcn_mfma_f32_16x16x32_bf16(At[m][k], Bx[n][k], acc[ai][bj][m][n], 0, 0, 0); \
;     __builtin_amdgcn_s_setprio(0); } while (0)
; template <bool HS>
; __device__ __forceinline__ void gemm_tile8(const u16* __restrict__ Ap, const u16* __restrict__ Bp, int K,
;                                            f32x4 (&acc)[2][2][4][2], char* shm, const int tid, const float* hsr = nullptr) {
;     ...
;     LDB8(B0, 0, 0); SCHED; LDA8(0, 0); STG_A(1, 1, t + 1);
;     WAIT_L(8); BAR; WAIT_L(0); MMA8(0, 0, B0); BAR; SCHED;
;     ...
;     LDA8(1, 1); STG_A(1, 0, t + 3);
;     BAR; WAIT_L(0); MMA8(1, 0, B0); BAR; SCHED;
;     STG_B(1, 1, t + 3);
;     WAIT_V(6); BAR; MMA8(1, 1, B1); BAR;
	s_setprio 0
	ds_read_b128 v[158:161], v138 offset:49152
	ds_read_b128 v[162:165], v138 offset:50176
	ds_read_b128 v[166:169], v138 offset:51200
	ds_read_b128 v[170:173], v138 offset:52224
	ds_read_b128 v[174:177], v138 offset:53248
	ds_read_b128 v[180:183], v138 offset:54272
	ds_read_b128 v[184:187], v138 offset:55296
	ds_read_b128 v[188:191], v138 offset:56320
	s_add_u32 s20, s24, s4
	s_addc_u32 s21, s25, s5
	s_add_u32 s20, s20, 0x180
	s_addc_u32 s21, s21, 0
	s_add_i32 s18, s11, 0x18000
	s_mov_b32 m0, s18
	s_nop 0
	global_load_lds_dwordx4 v140, s[20:21]
	s_add_i32 s18, s11, 0x1a000
	s_mov_b32 m0, s18
	s_nop 0
	global_load_lds_dwordx4 v139, s[20:21]
	s_add_u32 s20, s8, s4
	s_addc_u32 s21, s9, s5
	s_add_u32 s20, s20, 0x180
	s_addc_u32 s21, s21, 0
	s_add_i32 s18, s11, 0x8000
	s_mov_b32 m0, s18
	s_nop 0
	global_load_lds_dwordx4 v140, s[20:21]
	s_add_i32 s18, s11, 0xa000
	s_mov_b32 m0, s18
	s_nop 0
	global_load_lds_dwordx4 v139, s[20:21]
	s_add_u32 s20, s22, s4
	s_addc_u32 s21, s23, s5
	s_add_u32 s20, s20, 0x180
	s_addc_u32 s21, s21, 0
	s_add_i32 s18, s11, 0x1c000
	s_mov_b32 m0, s18
	s_nop 0
	global_load_lds_dwordx4 v140, s[20:21]
	s_add_i32 s18, s11, 0x1e000
	s_mov_b32 m0, s18
	s_nop 0
	global_load_lds_dwordx4 v139, s[20:21]
	s_waitcnt vmcnt(8) lgkmcnt(0)
	s_setprio 1
	s_barrier
	v_mfma_f32_16x16x32_bf16 v[62:65], v[158:161], v[142:145], v[62:65]
	v_mfma_f32_16x16x32_bf16 v[58:61], v[158:161], v[150:153], v[58:61]
	v_mfma_f32_16x16x32_bf16 v[50:53], v[166:169], v[150:153], v[50:53]
	v_mfma_f32_16x16x32_bf16 v[54:57], v[166:169], v[142:145], v[54:57]
	v_mfma_f32_16x16x32_bf16 v[46:49], v[174:177], v[142:145], v[46:49]
	v_mfma_f32_16x16x32_bf16 v[42:45], v[174:177], v[150:153], v[42:45]
	v_mfma_f32_16x16x32_bf16 v[34:37], v[184:187], v[150:153], v[34:37]
	v_mfma_f32_16x16x32_bf16 v[38:41], v[184:187], v[142:145], v[38:41]
	v_mfma_f32_16x16x32_bf16 v[62:65], v[162:165], v[146:149], v[62:65]
	v_mfma_f32_16x16x32_bf16 v[58:61], v[162:165], v[154:157], v[58:61]
	v_mfma_f32_16x16x32_bf16 v[50:53], v[170:173], v[154:157], v[50:53]
	v_mfma_f32_16x16x32_bf16 v[54:57], v[170:173], v[146:149], v[54:57]
	v_mfma_f32_16x16x32_bf16 v[46:49], v[180:183], v[146:149], v[46:49]
	v_mfma_f32_16x16x32_bf16 v[42:45], v[180:183], v[154:157], v[42:45]
	v_mfma_f32_16x16x32_bf16 v[34:37], v[188:191], v[154:157], v[34:37]
	v_mfma_f32_16x16x32_bf16 v[38:41], v[188:191], v[146:149], v[38:41]
	v_mfma_f32_16x16x32_bf16 v[30:33], v[158:161], v[192:195], v[30:33]
	v_mfma_f32_16x16x32_bf16 v[26:29], v[158:161], v[200:203], v[26:29]
	v_mfma_f32_16x16x32_bf16 v[18:21], v[166:169], v[200:203], v[18:21]
	v_mfma_f32_16x16x32_bf16 v[22:25], v[166:169], v[192:195], v[22:25]
	v_mfma_f32_16x16x32_bf16 v[14:17], v[174:177], v[192:195], v[14:17]
	v_mfma_f32_16x16x32_bf16 v[10:13], v[174:177], v[200:203], v[10:13]
	v_mfma_f32_16x16x32_bf16 v[2:5], v[184:187], v[200:203], v[2:5]
	v_mfma_f32_16x16x32_bf16 v[6:9], v[184:187], v[192:195], v[6:9]
	v_mfma_f32_16x16x32_bf16 v[30:33], v[162:165], v[196:199], v[30:33]
	v_mfma_f32_16x16x32_bf16 v[26:29], v[162:165], v[204:207], v[26:29]
	v_mfma_f32_16x16x32_bf16 v[18:21], v[170:173], v[204:207], v[18:21]
	v_mfma_f32_16x16x32_bf16 v[22:25], v[170:173], v[196:199], v[22:25]
	v_mfma_f32_16x16x32_bf16 v[14:17], v[180:183], v[196:199], v[14:17]
	v_mfma_f32_16x16x32_bf16 v[10:13], v[180:183], v[204:207], v[10:13]
	v_mfma_f32_16x16x32_bf16 v[2:5], v[188:191], v[204:207], v[2:5]
	v_mfma_f32_16x16x32_bf16 v[6:9], v[188:191], v[196:199], v[6:9]
	s_barrier
	s_setprio 0
	s_add_i32 s17, s17, 2
	s_add_u32 s4, s4, 0x100
	s_addc_u32 s5, s5, 0
	s_cmp_lt_u32 s17, 12
	s_cbranch_scc0 .Lk_conv_in_exit
.Lk_conv_in:
	v_add_u32_e32 v154, 0x10000, v141
	ds_read_b128 v[142:145], v154
	ds_read_b128 v[146:149], v154 offset:1024
	ds_read_b128 v[150:153], v154 offset:2048
	ds_read_b128 v[154:157], v154 offset:3072
	ds_read_b128 v[158:161], v138
	ds_read_b128 v[162:165], v138 offset:1024
	ds_read_b128 v[166:169], v138 offset:2048
	ds_read_b128 v[170:173], v138 offset:3072
	ds_read_b128 v[174:177], v138 offset:4096
	ds_read_b128 v[180:183], v138 offset:5120
	ds_read_b128 v[184:187], v138 offset:6144
	ds_read_b128 v[188:191], v138 offset:7168
	v_add_u32_e32 v204, 0x14000, v141
	ds_read_b128 v[192:195], v204
	ds_read_b128 v[196:199], v204 offset:1024
	ds_read_b128 v[200:203], v204 offset:2048
	ds_read_b128 v[204:207], v204 offset:3072
	s_add_u32 s20, s15, s4
	s_addc_u32 s21, s16, s5
	s_add_u32 s20, s20, 0x80
	s_addc_u32 s21, s21, 0
	s_add_i32 s18, s11, 0xc000
	s_mov_b32 m0, s18
	s_nop 0
	global_load_lds_dwordx4 v140, s[20:21]
	s_add_i32 s18, s11, 0xe000
	s_mov_b32 m0, s18
	s_nop 0
	global_load_lds_dwordx4 v139, s[20:21]
	s_waitcnt vmcnt(8) lgkmcnt(0)
	s_setprio 1
	s_barrier
; #define WAIT_V(n) asm volatile("s_waitcnt vmcnt(" #n ")" ::: "memory")
; #define WAIT_L(n) asm volatile("s_waitcnt lgkmcnt(" #n ")" ::: "memory")
; #define BAR __builtin_amdgcn_s_barrier()
; #define SCHED __builtin_amdgcn_sched_barrier(0)
; #define STG_A(b, h, kt) stage_half_s(lds0 + ((b) * 2 + (h)) * HT_B, ((h) ? A1 : Ap) + (kt) * BK, off0, off1)
; #define STG_B(b, h, kt) stage_half_s(lds0 + (4 + (b) * 2 + (h)) * HT_B, ((h) ? B1p : Bp) + (kt) * BK, off0, off1)
; #define STG_A(b, h, kt) stage_half_s(lds0 + ((b) * 2 + (h)) * HT_B, ((h) ? A1 : Ap) + (kt) * BK, off0, off1)
; #define STG_B(b, h, kt) stage_half_s(lds0 + (4 + (b) * 2 + (h)) * HT_B, ((h) ? B1p : Bp) + (kt) * BK, off0, off1)
; #define LDA8(b, h) _Pragma("unroll") for (int m = 0; m < 4; ++m) _Pragma("unroll") for (int k = 0; k < 2; ++k) \
;     At[m][k] = *(const bf16x8*)(SA_(shm, b, h) + abase + (m * 2 + k) * 1024)
; #define LDB8(dst, b, h) _Pragma("unroll") for (int n = 0; n < 2; ++n) _Pragma("unroll") for (int k = 0; k < 2; ++k) \
;     dst[n][k] = *(const bf16x8*)(SB_(shm, b, h) + bbase + (n * 2 + k) * 1024)
; template <bool HS>
; __device__ __forceinline__ void gemm_tile8(const u16* __restrict__ Ap, const u16* __restrict__ Bp, int K,
;                                            f32x4 (&acc)[2][2][4][2], char* shm, const int tid, const float* hsr = nullptr) {
;     ...
;     LDB8(B0, 0, 0); SCHED; LDA8(0, 0); STG_A(1, 1, t + 1);
;     WAIT_L(8); BAR; WAIT_L(0); MMA8(0, 0, B0); BAR; SCHED;
;     LDB8(B1, 0, 1); STG_B(0, 0, t + 2);
;     BAR; WAIT_L(0); MMA8(0, 1, B1); BAR;
;     LDA8(0, 1); STG_A(0, 0, t + 2);
;     BAR; WAIT_L(0); MMA8(1, 0, B0); BAR; SCHED;
;     STG_B(0, 1, t + 2);
;     WAIT_V(6); BAR; MMA8(1, 1, B1); BAR;
;     LDB8(B0, 1, 0); SCHED; LDA8(1, 0); STG_A(0, 1, t + 2);
;     WAIT_L(8); BAR; WAIT_L(0); MMA8(0, 0, B0); BAR; SCHED;
;     LDB8(B1, 1, 1); STG_B(1, 0, t + 3);
;     BAR; WAIT_L(0); MMA8(0, 1, B1); BAR;
;     LDA8(1, 1); STG_A(1, 0, t + 3);
;     BAR; WAIT_L(0); MMA8(1, 0, B0); BAR; SCHED;
;     STG_B(1, 1, t + 3);
;     WAIT_V(6); BAR; MMA8(1, 1, B1); BAR;
	v_mfma_f32_16x16x32_bf16 v[126:129], v[158:161], v[142:145], v[126:129]
	v_mfma_f32_16x16x32_bf16 v[122:125], v[158:161], v[150:153], v[122:125]
	v_mfma_f32_16x16x32_bf16 v[114:117], v[166:169], v[150:153], v[114:117]
	v_mfma_f32_16x16x32_bf16 v[118:121], v[166:169], v[142:145], v[118:121]
	v_mfma_f32_16x16x32_bf16 v[110:113], v[174:177], v[142:145], v[110:113]
	v_mfma_f32_16x16x32_bf16 v[106:109], v[174:177], v[150:153], v[106:109]
	v_mfma_f32_16x16x32_bf16 v[98:101], v[184:187], v[150:153], v[98:101]
	v_mfma_f32_16x16x32_bf16 v[102:105], v[184:187], v[142:145], v[102:105]
	v_mfma_f32_16x16x32_bf16 v[126:129], v[162:165], v[146:149], v[126:129]
	v_mfma_f32_16x16x32_bf16 v[122:125], v[162:165], v[154:157], v[122:125]
	v_mfma_f32_16x16x32_bf16 v[114:117], v[170:173], v[154:157], v[114:117]
	v_mfma_f32_16x16x32_bf16 v[118:121], v[170:173], v[146:149], v[118:121]
	v_mfma_f32_16x16x32_bf16 v[110:113], v[180:183], v[146:149], v[110:113]
	v_mfma_f32_16x16x32_bf16 v[106:109], v[180:183], v[154:157], v[106:109]
	v_mfma_f32_16x16x32_bf16 v[98:101], v[188:191], v[154:157], v[98:101]
	v_mfma_f32_16x16x32_bf16 v[102:105], v[188:191], v[146:149], v[102:105]
	v_mfma_f32_16x16x32_bf16 v[94:97], v[158:161], v[192:195], v[94:97]
	v_mfma_f32_16x16x32_bf16 v[90:93], v[158:161], v[200:203], v[90:93]
	v_mfma_f32_16x16x32_bf16 v[82:85], v[166:169], v[200:203], v[82:85]
	v_mfma_f32_16x16x32_bf16 v[86:89], v[166:169], v[192:195], v[86:89]
	v_mfma_f32_16x16x32_bf16 v[78:81], v[174:177], v[192:195], v[78:81]
	v_mfma_f32_16x16x32_bf16 v[74:77], v[174:177], v[200:203], v[74:77]
	v_mfma_f32_16x16x32_bf16 v[66:69], v[184:187], v[200:203], v[66:69]
	v_mfma_f32_16x16x32_bf16 v[70:73], v[184:187], v[192:195], v[70:73]
	v_mfma_f32_16x16x32_bf16 v[94:97], v[162:165], v[196:199], v[94:97]
	v_mfma_f32_16x16x32_bf16 v[90:93], v[162:165], v[204:207], v[90:93]
	v_mfma_f32_16x16x32_bf16 v[82:85], v[170:173], v[204:207], v[82:85]
	v_mfma_f32_16x16x32_bf16 v[86:89], v[170:173], v[196:199], v[86:89]
	v_mfma_f32_16x16x32_bf16 v[78:81], v[180:183], v[196:199], v[78:81]
	v_mfma_f32_16x16x32_bf16 v[74:77], v[180:183], v[204:207], v[74:77]
	v_mfma_f32_16x16x32_bf16 v[66:69], v[188:191], v[204:207], v[66:69]
	v_mfma_f32_16x16x32_bf16 v[70:73], v[188:191], v[196:199], v[70:73]
	s_barrier
	s_setprio 0
	ds_read_b128 v[158:161], v138 offset:16384
	ds_read_b128 v[162:165], v138 offset:17408
	ds_read_b128 v[166:169], v138 offset:18432
	ds_read_b128 v[170:173], v138 offset:19456
	ds_read_b128 v[174:177], v138 offset:20480
	ds_read_b128 v[180:183], v138 offset:21504
	ds_read_b128 v[184:187], v138 offset:22528
	ds_read_b128 v[188:191], v138 offset:23552
	s_add_u32 s20, s24, s4
	s_addc_u32 s21, s25, s5
	s_add_u32 s20, s20, 0x100
	s_addc_u32 s21, s21, 0
	s_add_i32 s18, s11, 0x10000
	s_mov_b32 m0, s18
	s_nop 0
	global_load_lds_dwordx4 v140, s[20:21]
	s_add_i32 s18, s11, 0x12000
	s_mov_b32 m0, s18
	s_nop 0
	global_load_lds_dwordx4 v139, s[20:21]
	s_add_u32 s20, s8, s4
	s_addc_u32 s21, s9, s5
	s_add_u32 s20, s20, 0x100
	s_addc_u32 s21, s21, 0
	s_mov_b32 m0, s11
	s_nop 0
	global_load_lds_dwordx4 v140, s[20:21]
	s_add_i32 s18, s11, 0x2000
	s_mov_b32 m0, s18
	s_nop 0
	global_load_lds_dwordx4 v139, s[20:21]
	s_add_u32 s20, s22, s4
	s_addc_u32 s21, s23, s5
	s_add_u32 s20, s20, 0x100
	s_addc_u32 s21, s21, 0
	s_add_i32 s18, s11, 0x14000
	s_mov_b32 m0, s18
	s_nop 0
	global_load_lds_dwordx4 v140, s[20:21]
	s_add_i32 s18, s11, 0x16000
	s_mov_b32 m0, s18
	s_nop 0
	global_load_lds_dwordx4 v139, s[20:21]
	s_waitcnt vmcnt(8) lgkmcnt(0)
	s_setprio 1
	s_barrier
	v_mfma_f32_16x16x32_bf16 v[62:65], v[158:161], v[142:145], v[62:65]
	v_mfma_f32_16x16x32_bf16 v[58:61], v[158:161], v[150:153], v[58:61]
	v_mfma_f32_16x16x32_bf16 v[50:53], v[166:169], v[150:153], v[50:53]
	v_mfma_f32_16x16x32_bf16 v[54:57], v[166:169], v[142:145], v[54:57]
	v_mfma_f32_16x16x32_bf16 v[46:49], v[174:177], v[142:145], v[46:49]
	v_mfma_f32_16x16x32_bf16 v[42:45], v[174:177], v[150:153], v[42:45]
	v_mfma_f32_16x16x32_bf16 v[34:37], v[184:187], v[150:153], v[34:37]
	v_mfma_f32_16x16x32_bf16 v[38:41], v[184:187], v[142:145], v[38:41]
	v_mfma_f32_16x16x32_bf16 v[62:65], v[162:165], v[146:149], v[62:65]
	v_mfma_f32_16x16x32_bf16 v[58:61], v[162:165], v[154:157], v[58:61]
	v_mfma_f32_16x16x32_bf16 v[50:53], v[170:173], v[154:157], v[50:53]
	v_mfma_f32_16x16x32_bf16 v[54:57], v[170:173], v[146:149], v[54:57]
	v_mfma_f32_16x16x32_bf16 v[46:49], v[180:183], v[146:149], v[46:49]
	v_mfma_f32_16x16x32_bf16 v[42:45], v[180:183], v[154:157], v[42:45]
	v_mfma_f32_16x16x32_bf16 v[34:37], v[188:191], v[154:157], v[34:37]
	v_mfma_f32_16x16x32_bf16 v[38:41], v[188:191], v[146:149], v[38:41]
	v_mfma_f32_16x16x32_bf16 v[30:33], v[158:161], v[192:195], v[30:33]
	v_mfma_f32_16x16x32_bf16 v[26:29], v[158:161], v[200:203], v[26:29]
	v_mfma_f32_16x16x32_bf16 v[18:21], v[166:169], v[200:203], v[18:21]
	v_mfma_f32_16x16x32_bf16 v[22:25], v[166:169], v[192:195], v[22:25]
	v_mfma_f32_16x16x32_bf16 v[14:17], v[174:177], v[192:195], v[14:17]
	v_mfma_f32_16x16x32_bf16 v[10:13], v[174:177], v[200:203], v[10:13]
	v_mfma_f32_16x16x32_bf16 v[2:5], v[184:187], v[200:203], v[2:5]
	v_mfma_f32_16x16x32_bf16 v[6:9], v[184:187], v[192:195], v[6:9]
	v_mfma_f32_16x16x32_bf16 v[30:33], v[162:165], v[196:199], v[30:33]
	v_mfma_f32_16x16x32_bf16 v[26:29], v[162:165], v[204:207], v[26:29]
	v_mfma_f32_16x16x32_bf16 v[18:21], v[170:173], v[204:207], v[18:21]
	v_mfma_f32_16x16x32_bf16 v[22:25], v[170:173], v[196:199], v[22:25]
	v_mfma_f32_16x16x32_bf16 v[14:17], v[180:183], v[196:199], v[14:17]
	v_mfma_f32_16x16x32_bf16 v[10:13], v[180:183], v[204:207], v[10:13]
	v_mfma_f32_16x16x32_bf16 v[2:5], v[188:191], v[204:207], v[2:5]
	v_mfma_f32_16x16x32_bf16 v[6:9], v[188:191], v[196:199], v[6:9]
	s_barrier
; #define WAIT_V(n) asm volatile("s_waitcnt vmcnt(" #n ")" ::: "memory")
; #define WAIT_L(n) asm volatile("s_waitcnt lgkmcnt(" #n ")" ::: "memory")
; #define BAR __builtin_amdgcn_s_barrier()
; #define SCHED __builtin_amdgcn_sched_barrier(0)
; #define STG_A(b, h, kt) stage_half_s(lds0 + ((b) * 2 + (h)) * HT_B, ((h) ? A1 : Ap) + (kt) * BK, off0, off1)
; #define STG_B(b, h, kt) stage_half_s(lds0 + (4 + (b) * 2 + (h)) * HT_B, ((h) ? B1p : Bp) + (kt) * BK, off0, off1)
; #define STG_A(b, h, kt) stage_half_s(lds0 + ((b) * 2 + (h)) * HT_B, ((h) ? A1 : Ap) + (kt) * BK, off0, off1)
; #define STG_B(b, h, kt) stage_half_s(lds0 + (4 + (b) * 2 + (h)) * HT_B, ((h) ? B1p : Bp) + (kt) * BK, off0, off1)
; #define LDA8(b, h) _Pragma("unroll") for (int m = 0; m < 4; ++m) _Pragma("unroll") for (int k = 0; k < 2; ++k) \
;     At[m][k] = *(const bf16x8*)(SA_(shm, b, h) + abase + (m * 2 + k) * 1024)
; #define LDB8(dst, b, h) _Pragma("unroll") for (int n = 0; n < 2; ++n) _Pragma("unroll") for (int k = 0; k < 2; ++k) \
;     dst[n][k] = *(const bf16x8*)(SB_(shm, b, h) + bbase + (n * 2 + k) * 1024)
; template <bool HS>
; __device__ __forceinline__ void gemm_tile8(const u16* __restrict__ Ap, const u16* __restrict__ Bp, int K,
;                                            f32x4 (&acc)[2][2][4][2], char* shm, const int tid, const float* hsr = nullptr) {
;     ...
;     LDB8(B0, 0, 0); SCHED; LDA8(0, 0); STG_A(1, 1, t + 1);
;     WAIT_L(8); BAR; WAIT_L(0); MMA8(0, 0, B0); BAR; SCHED;
;     LDB8(B1, 0, 1); STG_B(0, 0, t + 2);
;     BAR; WAIT_L(0); MMA8(0, 1, B1); BAR;
;     LDA8(0, 1); STG_A(0, 0, t + 2);
;     BAR; WAIT_L(0); MMA8(1, 0, B0); BAR; SCHED;
;     STG_B(0, 1, t + 2);
;     WAIT_V(6); BAR; MMA8(1, 1, B1); BAR;
;     LDB8(B0, 1, 0); SCHED; LDA8(1, 0); STG_A(0, 1, t + 2);
;     WAIT_L(8); BAR; WAIT_L(0); MMA8(0, 0, B0); BAR; SCHED;
;     LDB8(B1, 1, 1); STG_B(1, 0, t + 3);
;     BAR; WAIT_L(0); MMA8(0, 1, B1); BAR;
;     LDA8(1, 1); STG_A(1, 0, t + 3);
;     BAR; WAIT_L(0); MMA8(1, 0, B0); BAR; SCHED;
;     STG_B(1, 1, t + 3);
;     WAIT_V(6); BAR; MMA8(1, 1, B1); BAR;
	s_setprio 0
	v_add_u32_e32 v154, 0x18000, v141
	ds_read_b128 v[142:145], v154
	ds_read_b128 v[146:149], v154 offset:1024
	ds_read_b128 v[150:153], v154 offset:2048
	ds_read_b128 v[154:157], v154 offset:3072
	ds_read_b128 v[158:161], v138 offset:32768
	ds_read_b128 v[162:165], v138 offset:33792
	ds_read_b128 v[166:169], v138 offset:34816
	ds_read_b128 v[170:173], v138 offset:35840
	ds_read_b128 v[174:177], v138 offset:36864
	ds_read_b128 v[180:183], v138 offset:37888
	ds_read_b128 v[184:187], v138 offset:38912
	ds_read_b128 v[188:191], v138 offset:39936
	v_add_u32_e32 v204, 0x1c000, v141
	ds_read_b128 v[192:195], v204
	ds_read_b128 v[196:199], v204 offset:1024
	ds_read_b128 v[200:203], v204 offset:2048
	ds_read_b128 v[204:207], v204 offset:3072
	s_add_u32 s20, s15, s4
	s_addc_u32 s21, s16, s5
	s_add_u32 s20, s20, 0x100
	s_addc_u32 s21, s21, 0
	s_add_i32 s18, s11, 0x4000
	s_mov_b32 m0, s18
	s_nop 0
	global_load_lds_dwordx4 v140, s[20:21]
	s_add_i32 s18, s11, 0x6000
	s_mov_b32 m0, s18
	s_nop 0
	global_load_lds_dwordx4 v139, s[20:21]
	s_waitcnt vmcnt(8) lgkmcnt(0)
	s_setprio 1
	s_barrier
	v_mfma_f32_16x16x32_bf16 v[126:129], v[158:161], v[142:145], v[126:129]
	v_mfma_f32_16x16x32_bf16 v[122:125], v[158:161], v[150:153], v[122:125]
	v_mfma_f32_16x16x32_bf16 v[114:117], v[166:169], v[150:153], v[114:117]
	v_mfma_f32_16x16x32_bf16 v[118:121], v[166:169], v[142:145], v[118:121]
	v_mfma_f32_16x16x32_bf16 v[110:113], v[174:177], v[142:145], v[110:113]
	v_mfma_f32_16x16x32_bf16 v[106:109], v[174:177], v[150:153], v[106:109]
	v_mfma_f32_16x16x32_bf16 v[98:101], v[184:187], v[150:153], v[98:101]
	v_mfma_f32_16x16x32_bf16 v[102:105], v[184:187], v[142:145], v[102:105]
	v_mfma_f32_16x16x32_bf16 v[126:129], v[162:165], v[146:149], v[126:129]
	v_mfma_f32_16x16x32_bf16 v[122:125], v[162:165], v[154:157], v[122:125]
	v_mfma_f32_16x16x32_bf16 v[114:117], v[170:173], v[154:157], v[114:117]
	v_mfma_f32_16x16x32_bf16 v[118:121], v[170:173], v[146:149], v[118:121]
	v_mfma_f32_16x16x32_bf16 v[110:113], v[180:183], v[146:149], v[110:113]
	v_mfma_f32_16x16x32_bf16 v[106:109], v[180:183], v[154:157], v[106:109]
	v_mfma_f32_16x16x32_bf16 v[98:101], v[188:191], v[154:157], v[98:101]
	v_mfma_f32_16x16x32_bf16 v[102:105], v[188:191], v[146:149], v[102:105]
	v_mfma_f32_16x16x32_bf16 v[94:97], v[158:161], v[192:195], v[94:97]
	v_mfma_f32_16x16x32_bf16 v[90:93], v[158:161], v[200:203], v[90:93]
	v_mfma_f32_16x16x32_bf16 v[82:85], v[166:169], v[200:203], v[82:85]
	v_mfma_f32_16x16x32_bf16 v[86:89], v[166:169], v[192:195], v[86:89]
	v_mfma_f32_16x16x32_bf16 v[78:81], v[174:177], v[192:195], v[78:81]
	v_mfma_f32_16x16x32_bf16 v[74:77], v[174:177], v[200:203], v[74:77]
	v_mfma_f32_16x16x32_bf16 v[66:69], v[184:187], v[200:203], v[66:69]
	v_mfma_f32_16x16x32_bf16 v[70:73], v[184:187], v[192:195], v[70:73]
	v_mfma_f32_16x16x32_bf16 v[94:97], v[162:165], v[196:199], v[94:97]
	v_mfma_f32_16x16x32_bf16 v[90:93], v[162:165], v[204:207], v[90:93]
	v_mfma_f32_16x16x32_bf16 v[82:85], v[170:173], v[204:207], v[82:85]
	v_mfma_f32_16x16x32_bf16 v[86:89], v[170:173], v[196:199], v[86:89]
	v_mfma_f32_16x16x32_bf16 v[78:81], v[180:183], v[196:199], v[78:81]
	v_mfma_f32_16x16x32_bf16 v[74:77], v[180:183], v[204:207], v[74:77]
	v_mfma_f32_16x16x32_bf16 v[66:69], v[188:191], v[204:207], v[66:69]
	v_mfma_f32_16x16x32_bf16 v[70:73], v[188:191], v[196:199], v[70:73]
	s_barrier
	s_setprio 0
	ds_read_b128 v[158:161], v138 offset:49152
	ds_read_b128 v[162:165], v138 offset:50176
	ds_read_b128 v[166:169], v138 offset:51200
	ds_read_b128 v[170:173], v138 offset:52224
	ds_read_b128 v[174:177], v138 offset:53248
	ds_read_b128 v[180:183], v138 offset:54272
	ds_read_b128 v[184:187], v138 offset:55296
	ds_read_b128 v[188:191], v138 offset:56320
	s_add_u32 s20, s24, s4
	s_addc_u32 s21, s25, s5
	s_add_u32 s20, s20, 0x180
	s_addc_u32 s21, s21, 0
	s_add_i32 s18, s11, 0x18000
	s_mov_b32 m0, s18
	s_nop 0
	global_load_lds_dwordx4 v140, s[20:21]
	s_add_i32 s18, s11, 0x1a000
	s_mov_b32 m0, s18
	s_nop 0
	global_load_lds_dwordx4 v139, s[20:21]
	s_add_u32 s20, s8, s4
	s_addc_u32 s21, s9, s5
	s_add_u32 s20, s20, 0x180
	s_addc_u32 s21, s21, 0
	s_add_i32 s18, s11, 0x8000
	s_mov_b32 m0, s18
	s_nop 0
	global_load_lds_dwordx4 v140, s[20:21]
	s_add_i32 s18, s11, 0xa000
	s_mov_b32 m0, s18
	s_nop 0
	global_load_lds_dwordx4 v139, s[20:21]
	s_add_u32 s20, s22, s4
	s_addc_u32 s21, s23, s5
	s_add_u32 s20, s20, 0x180
	s_addc_u32 s21, s21, 0
	s_add_i32 s18, s11, 0x1c000
	s_mov_b32 m0, s18
	s_nop 0
	global_load_lds_dwordx4 v140, s[20:21]
	s_add_i32 s18, s11, 0x1e000
	s_mov_b32 m0, s18
	s_nop 0
	global_load_lds_dwordx4 v139, s[20:21]
	s_waitcnt vmcnt(8) lgkmcnt(0)
	s_setprio 1
	s_barrier
	v_mfma_f32_16x16x32_bf16 v[62:65], v[158:161], v[142:145], v[62:65]
	v_mfma_f32_16x16x32_bf16 v[58:61], v[158:161], v[150:153], v[58:61]
	v_mfma_f32_16x16x32_bf16 v[50:53], v[166:169], v[150:153], v[50:53]
	v_mfma_f32_16x16x32_bf16 v[54:57], v[166:169], v[142:145], v[54:57]
	v_mfma_f32_16x16x32_bf16 v[46:49], v[174:177], v[142:145], v[46:49]
	v_mfma_f32_16x16x32_bf16 v[42:45], v[174:177], v[150:153], v[42:45]
	v_mfma_f32_16x16x32_bf16 v[34:37], v[184:187], v[150:153], v[34:37]
	v_mfma_f32_16x16x32_bf16 v[38:41], v[184:187], v[142:145], v[38:41]
	v_mfma_f32_16x16x32_bf16 v[62:65], v[162:165], v[146:149], v[62:65]
	v_mfma_f32_16x16x32_bf16 v[58:61], v[162:165], v[154:157], v[58:61]
	v_mfma_f32_16x16x32_bf16 v[50:53], v[170:173], v[154:157], v[50:53]
	v_mfma_f32_16x16x32_bf16 v[54:57], v[170:173], v[146:149], v[54:57]
	v_mfma_f32_16x16x32_bf16 v[46:49], v[180:183], v[146:149], v[46:49]
	v_mfma_f32_16x16x32_bf16 v[42:45], v[180:183], v[154:157], v[42:45]
	v_mfma_f32_16x16x32_bf16 v[34:37], v[188:191], v[154:157], v[34:37]
	v_mfma_f32_16x16x32_bf16 v[38:41], v[188:191], v[146:149], v[38:41]
	v_mfma_f32_16x16x32_bf16 v[30:33], v[158:161], v[192:195], v[30:33]
	v_mfma_f32_16x16x32_bf16 v[26:29], v[158:161], v[200:203], v[26:29]
	v_mfma_f32_16x16x32_bf16 v[18:21], v[166:169], v[200:203], v[18:21]
	v_mfma_f32_16x16x32_bf16 v[22:25], v[166:169], v[192:195], v[22:25]
	v_mfma_f32_16x16x32_bf16 v[14:17], v[174:177], v[192:195], v[14:17]
	v_mfma_f32_16x16x32_bf16 v[10:13], v[174:177], v[200:203], v[10:13]
	v_mfma_f32_16x16x32_bf16 v[2:5], v[184:187], v[200:203], v[2:5]
	v_mfma_f32_16x16x32_bf16 v[6:9], v[184:187], v[192:195], v[6:9]
	v_mfma_f32_16x16x32_bf16 v[30:33], v[162:165], v[196:199], v[30:33]
	v_mfma_f32_16x16x32_bf16 v[26:29], v[162:165], v[204:207], v[26:29]
	v_mfma_f32_16x16x32_bf16 v[18:21], v[170:173], v[204:207], v[18:21]
	v_mfma_f32_16x16x32_bf16 v[22:25], v[170:173], v[196:199], v[22:25]
	v_mfma_f32_16x16x32_bf16 v[14:17], v[180:183], v[196:199], v[14:17]
	v_mfma_f32_16x16x32_bf16 v[10:13], v[180:183], v[204:207], v[10:13]
	v_mfma_f32_16x16x32_bf16 v[2:5], v[188:191], v[204:207], v[2:5]
	v_mfma_f32_16x16x32_bf16 v[6:9], v[188:191], v[196:199], v[6:9]
	s_barrier
	s_setprio 0
	s_add_i32 s17, s17, 2
	s_add_u32 s4, s4, 0x100
	s_addc_u32 s5, s5, 0
	s_cmp_lt_u32 s17, 12
	s_cbranch_scc1 .Lk_conv_in

; #define WAIT_V(n) asm volatile("s_waitcnt vmcnt(" #n ")" ::: "memory")
; #define WAIT_L(n) asm volatile("s_waitcnt lgkmcnt(" #n ")" ::: "memory")
; #define BAR __builtin_amdgcn_s_barrier()
; #define SCHED __builtin_amdgcn_sched_barrier(0)
; #define STG_A(b, h, kt) stage_half_s(lds0 + ((b) * 2 + (h)) * HT_B, ((h) ? A1 : Ap) + (kt) * BK, off0, off1)
; #define STG_B(b, h, kt) stage_half_s(lds0 + (4 + (b) * 2 + (h)) * HT_B, ((h) ? B1p : Bp) + (kt) * BK, off0, off1)
; #define STG_A(b, h, kt) stage_half_s(lds0 + ((b) * 2 + (h)) * HT_B, ((h) ? A1 : Ap) + (kt) * BK, off0, off1)
; #define STG_B(b, h, kt) stage_half_s(lds0 + (4 + (b) * 2 + (h)) * HT_B, ((h) ? B1p : Bp) + (kt) * BK, off0, off1)
; template <bool HS>
; __device__ __forceinline__ void gemm_tile8(const u16* __restrict__ Ap, const u16* __restrict__ Bp, int K,
;                                            f32x4 (&acc)[2][2][4][2], char* shm, const int tid, const float* hsr = nullptr) {
;     ...
;   stage_rc(tid * 16, r0, c0);
;   stage_rc(tid * 16 + 8192, r1, c1);
;   const unsigned off0 = (unsigned)(r0 * K + c0) * 2u, off1 = (unsigned)(r1 * K + c1) * 2u;
;   const int wvoff = __builtin_amdgcn_readfirstlane(tid >> 6) * 1024;
;   const u16* A1 = Ap + (size_t)128 * K;
;   const u16* B1p = Bp + (size_t)128 * K;
; #pragma unroll
;   for (int a = 0; a < 2; ++a)
; #pragma unroll
;     for (int b = 0; b < 2; ++b)
; #pragma unroll
;       for (int m = 0; m < 4; ++m)
; #pragma unroll
;         for (int n = 0; n < 2; ++n) acc[a][b][m][n] = f32x4{0.f, 0.f, 0.f, 0.f};
;   const int abase = lds_byte(wr * 64 + fr, fq * 8), bbase = lds_byte(wc * 32 + fr, fq * 8);
;   bf16x8 At[4][2], B0[2][2], B1[2][2];
;   const unsigned lds0 = (unsigned)(size_t)(__attribute__((address_space(3))) char*)shm + (unsigned)wvoff;
;     ...
;   const int nt = K / BK;
;   WAIT_V(0);
;   if (wr == 1) BAR;
;   BAR;
;   BAR;
;     ...
;     LDB8(B0, 0, 0); SCHED; LDA8(0, 0); STG_A(1, 1, t + 1);
;     WAIT_L(8); BAR; WAIT_L(0); MMA8(0, 0, B0); BAR; SCHED;
;     LDB8(B1, 0, 1); STG_B(0, 0, t + 2);
;     BAR; WAIT_L(0); MMA8(0, 1, B1); BAR;
;     LDA8(0, 1); STG_A(0, 0, t + 2);
;     BAR; WAIT_L(0); MMA8(1, 0, B0); BAR; SCHED;
;     STG_B(0, 1, t + 2);
;     WAIT_V(6); BAR; MMA8(1, 1, B1); BAR;
.LBB0_582:
	s_or_b64 exec, exec, s[8:9]
	v_bfe_i32 v6, v0, 27, 1
	v_lshlrev_b32_e32 v4, 4, v0
	v_lshrrev_b32_e32 v6, 22, v6
	v_add_u32_e32 v6, v4, v6
	v_and_b32_e32 v6, 0xfffffc00, v6
	v_ashrrev_i32_e32 v5, 31, v0
	v_sub_u32_e32 v6, v4, v6
	v_lshrrev_b32_e32 v5, 26, v5
	v_lshrrev_b32_e32 v7, 4, v6
	v_add_u32_e32 v5, v0, v5
	v_bitop3_b32 v7, v7, v6, 32 bitop3:0x6c
	v_ashrrev_i32_e32 v6, 31, v6
	v_ashrrev_i32_e32 v5, 6, v5
	v_lshrrev_b32_e32 v6, 26, v6
	v_lshlrev_b32_e32 v8, 3, v5
	v_add_u32_e32 v6, v7, v6
	v_and_b32_e32 v8, 0x1ffff0, v8
	v_ashrrev_i32_e32 v6, 6, v6
	v_add_u32_e32 v8, v6, v8
	v_mul_i32_i24_e32 v6, 64, v6
	v_add_u32_e32 v4, 0x2000, v4
	v_sub_u32_e32 v6, v7, v6
	v_ashrrev_i32_e32 v7, 31, v4
	v_lshrrev_b32_e32 v7, 22, v7
	v_add_u32_e32 v7, v4, v7
	v_ashrrev_i32_e32 v7, 10, v7
	v_mul_i32_i24_e32 v9, 0x400, v7
	v_sub_u32_e32 v4, v4, v9
	v_lshrrev_b32_e32 v9, 4, v4
	v_bitop3_b32 v4, v9, v4, 32 bitop3:0x6c
	s_ashr_i32 s7, s6, 31
	v_ashrrev_i32_e32 v10, 31, v4
	s_lshl_b64 s[6:7], s[6:7], 11
	v_readlane_b32 s20, v254, 47
	v_lshrrev_b32_e32 v10, 26, v10
	v_readlane_b32 s21, v254, 48
	s_add_u32 s8, s20, s6
	v_add_u32_e32 v10, v4, v10
	s_addc_u32 s9, s21, s7
	s_ashr_i32 s3, s2, 31
	v_lshlrev_b32_e32 v9, 3, v7
	v_lshrrev_b32_e32 v11, 6, v10
	v_and_b32_e32 v10, 0xc0, v10
	s_lshl_b64 s[6:7], s[2:3], 19
	v_readlane_b32 s3, v255, 7
	v_and_b32_e32 v9, 0x1ffff0, v9
	v_lshlrev_b32_e32 v7, 5, v7
	v_sub_u32_e32 v4, v4, v10
	s_add_u32 s3, s3, s6
	v_readlane_b32 s6, v255, 8
	v_lshlrev_b32_e32 v5, 5, v5
	v_add_u32_e32 v9, v11, v9
	v_and_b32_e32 v7, 32, v7
	v_ashrrev_i16_sdwa v4, v178, sext(v4) dst_sel:DWORD dst_unused:UNUSED_PAD src0_sel:DWORD src1_sel:BYTE_0
	s_addc_u32 s10, s6, s7
	v_and_b32_e32 v5, 32, v5
	v_ashrrev_i16_sdwa v6, v178, sext(v6) dst_sel:DWORD dst_unused:UNUSED_PAD src0_sel:DWORD src1_sel:BYTE_0
	v_bfe_i32 v4, v4, 0, 16
	v_lshl_or_b32 v7, v9, 10, v7
	s_lshl_b32 s11, s11, 10
	v_bfe_i32 v6, v6, 0, 16
	v_lshl_or_b32 v5, v8, 10, v5
	v_and_b32_e32 v8, 15, v0
	v_add_lshl_u32 v131, v7, v4, 1
	s_add_u32 s13, s3, 0x40000
	v_lshlrev_b32_e32 v7, 2, v0
	v_add_lshl_u32 v132, v5, v6, 1
	s_addc_u32 s14, s10, 0
	v_and_b32_e32 v4, 48, v0
	v_lshlrev_b32_e32 v5, 6, v8
	v_and_b32_e32 v7, 32, v7
	s_add_i32 s15, s11, 0
	v_or_b32_e32 v6, v5, v4
	v_bitop3_b32 v4, v5, v7, v4 bitop3:0x36
	v_lshlrev_b32_e32 v2, 12, v2
	s_movk_i32 s6, 0x3000
	s_add_u32 s16, s8, 0x40100
	v_and_or_b32 v133, v2, s6, v4
	s_addc_u32 s17, s9, 0
	s_add_i32 s6, s18, s19
	s_ashr_i32 s7, s6, 31
	v_lshlrev_b32_e32 v3, 13, v3
	s_lshl_b64 s[6:7], s[6:7], 11
	v_readlane_b32 s18, v254, 34
	v_bitop3_b32 v3, v6, v3, v7 bitop3:0xde
	s_add_u32 s18, s18, s6
	v_readlane_b32 s6, v254, 35
	v_mov_b32_e32 v2, 0
	s_addc_u32 s19, s6, s7
	s_mov_b32 s20, -2
	s_mov_b64 s[6:7], 0
	v_add_u32_e32 v130, 0, v3
	s_waitcnt lgkmcnt(0)
	v_readlane_b32 s22, v254, 49
	v_readlane_b32 s23, v254, 50
	s_barrier
	s_barrier
	v_add_u32_e32 v154, 0x10000, v133
	ds_read_b128 v[142:145], v154
	ds_read_b128 v[146:149], v154 offset:1024
	ds_read_b128 v[150:153], v154 offset:2048
	ds_read_b128 v[154:157], v154 offset:3072
	ds_read_b128 v[158:161], v130
	ds_read_b128 v[164:167], v130 offset:1024
	ds_read_b128 v[168:171], v130 offset:2048
	ds_read_b128 v[172:175], v130 offset:3072
	ds_read_b128 v[180:183], v130 offset:4096
	ds_read_b128 v[184:187], v130 offset:5120
	ds_read_b128 v[188:191], v130 offset:6144
	ds_read_b128 v[192:195], v130 offset:7168
	v_add_u32_e32 v208, 0x14000, v133
	ds_read_b128 v[196:199], v208
	ds_read_b128 v[200:203], v208 offset:1024
	ds_read_b128 v[204:207], v208 offset:2048
	ds_read_b128 v[208:211], v208 offset:3072
	s_add_u32 s24, s18, s6
	s_addc_u32 s25, s19, s7
	s_add_u32 s24, s24, 0x80
	s_addc_u32 s25, s25, 0
	s_add_i32 s23, s15, 0xc000
	s_mov_b32 m0, s23
	s_nop 0
	global_load_lds_dwordx4 v132, s[24:25]
	s_add_i32 s23, s15, 0xe000
	s_mov_b32 m0, s23
	s_nop 0
	global_load_lds_dwordx4 v131, s[24:25]
	s_waitcnt vmcnt(8) lgkmcnt(0)
	s_setprio 1
	s_barrier
	v_mfma_f32_16x16x32_bf16 v[126:129], v[158:161], v[142:145], 0
	v_mfma_f32_16x16x32_bf16 v[122:125], v[158:161], v[150:153], 0
	v_mfma_f32_16x16x32_bf16 v[114:117], v[168:171], v[150:153], 0
	v_mfma_f32_16x16x32_bf16 v[118:121], v[168:171], v[142:145], 0
	v_mfma_f32_16x16x32_bf16 v[110:113], v[180:183], v[142:145], 0
	v_mfma_f32_16x16x32_bf16 v[106:109], v[180:183], v[150:153], 0
	v_mfma_f32_16x16x32_bf16 v[98:101], v[188:191], v[150:153], 0
	v_mfma_f32_16x16x32_bf16 v[102:105], v[188:191], v[142:145], 0
	v_mfma_f32_16x16x32_bf16 v[126:129], v[164:167], v[146:149], v[126:129]
	v_mfma_f32_16x16x32_bf16 v[122:125], v[164:167], v[154:157], v[122:125]
	v_mfma_f32_16x16x32_bf16 v[114:117], v[172:175], v[154:157], v[114:117]
	v_mfma_f32_16x16x32_bf16 v[118:121], v[172:175], v[146:149], v[118:121]
	v_mfma_f32_16x16x32_bf16 v[110:113], v[184:187], v[146:149], v[110:113]
	v_mfma_f32_16x16x32_bf16 v[106:109], v[184:187], v[154:157], v[106:109]
	v_mfma_f32_16x16x32_bf16 v[98:101], v[192:195], v[154:157], v[98:101]
	v_mfma_f32_16x16x32_bf16 v[102:105], v[192:195], v[146:149], v[102:105]
	v_mfma_f32_16x16x32_bf16 v[94:97], v[158:161], v[196:199], 0
	v_mfma_f32_16x16x32_bf16 v[90:93], v[158:161], v[204:207], 0
	v_mfma_f32_16x16x32_bf16 v[82:85], v[168:171], v[204:207], 0
	v_mfma_f32_16x16x32_bf16 v[86:89], v[168:171], v[196:199], 0
	v_mfma_f32_16x16x32_bf16 v[78:81], v[180:183], v[196:199], 0
	v_mfma_f32_16x16x32_bf16 v[74:77], v[180:183], v[204:207], 0
	v_mfma_f32_16x16x32_bf16 v[66:69], v[188:191], v[204:207], 0
	v_mfma_f32_16x16x32_bf16 v[70:73], v[188:191], v[196:199], 0
	v_mfma_f32_16x16x32_bf16 v[94:97], v[164:167], v[200:203], v[94:97]
	v_mfma_f32_16x16x32_bf16 v[90:93], v[164:167], v[208:211], v[90:93]
	v_mfma_f32_16x16x32_bf16 v[82:85], v[172:175], v[208:211], v[82:85]
	v_mfma_f32_16x16x32_bf16 v[86:89], v[172:175], v[200:203], v[86:89]
	v_mfma_f32_16x16x32_bf16 v[78:81], v[184:187], v[200:203], v[78:81]
	v_mfma_f32_16x16x32_bf16 v[74:77], v[184:187], v[208:211], v[74:77]
	v_mfma_f32_16x16x32_bf16 v[66:69], v[192:195], v[208:211], v[66:69]
	v_mfma_f32_16x16x32_bf16 v[70:73], v[192:195], v[200:203], v[70:73]
	s_barrier
; #define WAIT_V(n) asm volatile("s_waitcnt vmcnt(" #n ")" ::: "memory")
; #define WAIT_L(n) asm volatile("s_waitcnt lgkmcnt(" #n ")" ::: "memory")
; #define BAR __builtin_amdgcn_s_barrier()
; #define SCHED __builtin_amdgcn_sched_barrier(0)
; #define STG_A(b, h, kt) stage_half_s(lds0 + ((b) * 2 + (h)) * HT_B, ((h) ? A1 : Ap) + (kt) * BK, off0, off1)
; #define STG_B(b, h, kt) stage_half_s(lds0 + (4 + (b) * 2 + (h)) * HT_B, ((h) ? B1p : Bp) + (kt) * BK, off0, off1)
; #define STG_A(b, h, kt) stage_half_s(lds0 + ((b) * 2 + (h)) * HT_B, ((h) ? A1 : Ap) + (kt) * BK, off0, off1)
; #define STG_B(b, h, kt) stage_half_s(lds0 + (4 + (b) * 2 + (h)) * HT_B, ((h) ? B1p : Bp) + (kt) * BK, off0, off1)
; #define LDA8(b, h) _Pragma("unroll") for (int m = 0; m < 4; ++m) _Pragma("unroll") for (int k = 0; k < 2; ++k) \
;     At[m][k] = *(const bf16x8*)(SA_(shm, b, h) + abase + (m * 2 + k) * 1024)
; #define LDB8(dst, b, h) _Pragma("unroll") for (int n = 0; n < 2; ++n) _Pragma("unroll") for (int k = 0; k < 2; ++k) \
;     dst[n][k] = *(const bf16x8*)(SB_(shm, b, h) + bbase + (n * 2 + k) * 1024)
; template <bool HS>
; __device__ __forceinline__ void gemm_tile8(const u16* __restrict__ Ap, const u16* __restrict__ Bp, int K,
;                                            f32x4 (&acc)[2][2][4][2], char* shm, const int tid, const float* hsr = nullptr) {
;     ...
;     LDB8(B0, 0, 0); SCHED; LDA8(0, 0); STG_A(1, 1, t + 1);
;     WAIT_L(8); BAR; WAIT_L(0); MMA8(0, 0, B0); BAR; SCHED;
;     LDB8(B1, 0, 1); STG_B(0, 0, t + 2);
;     BAR; WAIT_L(0); MMA8(0, 1, B1); BAR;
;     LDA8(0, 1); STG_A(0, 0, t + 2);
;     BAR; WAIT_L(0); MMA8(1, 0, B0); BAR; SCHED;
;     STG_B(0, 1, t + 2);
;     WAIT_V(6); BAR; MMA8(1, 1, B1); BAR;
;     LDB8(B0, 1, 0); SCHED; LDA8(1, 0); STG_A(0, 1, t + 2);
;     WAIT_L(8); BAR; WAIT_L(0); MMA8(0, 0, B0); BAR; SCHED;
;     LDB8(B1, 1, 1); STG_B(1, 0, t + 3);
;     BAR; WAIT_L(0); MMA8(0, 1, B1); BAR;
;     LDA8(1, 1); STG_A(1, 0, t + 3);
;     BAR; WAIT_L(0); MMA8(1, 0, B0); BAR; SCHED;
;     STG_B(1, 1, t + 3);
;     WAIT_V(6); BAR; MMA8(1, 1, B1); BAR;
	s_setprio 0
	ds_read_b128 v[158:161], v130 offset:16384
	ds_read_b128 v[164:167], v130 offset:17408
	ds_read_b128 v[168:171], v130 offset:18432
	ds_read_b128 v[172:175], v130 offset:19456
	ds_read_b128 v[180:183], v130 offset:20480
	ds_read_b128 v[184:187], v130 offset:21504
	ds_read_b128 v[188:191], v130 offset:22528
	ds_read_b128 v[192:195], v130 offset:23552
	s_add_u32 s24, s3, s6
	s_addc_u32 s25, s10, s7
	s_add_u32 s24, s24, 0x100
	s_addc_u32 s25, s25, 0
	s_add_i32 s23, s15, 0x10000
	s_mov_b32 m0, s23
	s_nop 0
	global_load_lds_dwordx4 v132, s[24:25]
	s_add_i32 s23, s15, 0x12000
	s_mov_b32 m0, s23
	s_nop 0
	global_load_lds_dwordx4 v131, s[24:25]
	s_add_u32 s24, s8, s6
	s_addc_u32 s25, s9, s7
	s_add_u32 s24, s24, 0x100
	s_addc_u32 s25, s25, 0
	s_mov_b32 m0, s15
	s_nop 0
	global_load_lds_dwordx4 v132, s[24:25]
	s_add_i32 s23, s15, 0x2000
	s_mov_b32 m0, s23
	s_nop 0
	global_load_lds_dwordx4 v131, s[24:25]
	s_add_u32 s24, s13, s6
	s_addc_u32 s25, s14, s7
	s_add_u32 s24, s24, 0x100
	s_addc_u32 s25, s25, 0
	s_add_i32 s23, s15, 0x14000
	s_mov_b32 m0, s23
	s_nop 0
	global_load_lds_dwordx4 v132, s[24:25]
	s_add_i32 s23, s15, 0x16000
	s_mov_b32 m0, s23
	s_nop 0
	global_load_lds_dwordx4 v131, s[24:25]
	s_waitcnt vmcnt(8) lgkmcnt(0)
	s_setprio 1
	s_barrier
	v_mfma_f32_16x16x32_bf16 v[62:65], v[158:161], v[142:145], 0
	v_mfma_f32_16x16x32_bf16 v[58:61], v[158:161], v[150:153], 0
	v_mfma_f32_16x16x32_bf16 v[50:53], v[168:171], v[150:153], 0
	v_mfma_f32_16x16x32_bf16 v[54:57], v[168:171], v[142:145], 0
	v_mfma_f32_16x16x32_bf16 v[46:49], v[180:183], v[142:145], 0
	v_mfma_f32_16x16x32_bf16 v[42:45], v[180:183], v[150:153], 0
	v_mfma_f32_16x16x32_bf16 v[34:37], v[188:191], v[150:153], 0
	v_mfma_f32_16x16x32_bf16 v[38:41], v[188:191], v[142:145], 0
	v_mfma_f32_16x16x32_bf16 v[62:65], v[164:167], v[146:149], v[62:65]
	v_mfma_f32_16x16x32_bf16 v[58:61], v[164:167], v[154:157], v[58:61]
	v_mfma_f32_16x16x32_bf16 v[50:53], v[172:175], v[154:157], v[50:53]
	v_mfma_f32_16x16x32_bf16 v[54:57], v[172:175], v[146:149], v[54:57]
	v_mfma_f32_16x16x32_bf16 v[46:49], v[184:187], v[146:149], v[46:49]
	v_mfma_f32_16x16x32_bf16 v[42:45], v[184:187], v[154:157], v[42:45]
	v_mfma_f32_16x16x32_bf16 v[34:37], v[192:195], v[154:157], v[34:37]
	v_mfma_f32_16x16x32_bf16 v[38:41], v[192:195], v[146:149], v[38:41]
	v_mfma_f32_16x16x32_bf16 v[30:33], v[158:161], v[196:199], 0
	v_mfma_f32_16x16x32_bf16 v[26:29], v[158:161], v[204:207], 0
	v_mfma_f32_16x16x32_bf16 v[18:21], v[168:171], v[204:207], 0
	v_mfma_f32_16x16x32_bf16 v[22:25], v[168:171], v[196:199], 0
	v_mfma_f32_16x16x32_bf16 v[14:17], v[180:183], v[196:199], 0
	v_mfma_f32_16x16x32_bf16 v[10:13], v[180:183], v[204:207], 0
	v_mfma_f32_16x16x32_bf16 v[2:5], v[188:191], v[204:207], 0
	v_mfma_f32_16x16x32_bf16 v[6:9], v[188:191], v[196:199], 0
	v_mfma_f32_16x16x32_bf16 v[30:33], v[164:167], v[200:203], v[30:33]
	v_mfma_f32_16x16x32_bf16 v[26:29], v[164:167], v[208:211], v[26:29]
	v_mfma_f32_16x16x32_bf16 v[18:21], v[172:175], v[208:211], v[18:21]
	v_mfma_f32_16x16x32_bf16 v[22:25], v[172:175], v[200:203], v[22:25]
	v_mfma_f32_16x16x32_bf16 v[14:17], v[184:187], v[200:203], v[14:17]
	v_mfma_f32_16x16x32_bf16 v[10:13], v[184:187], v[208:211], v[10:13]
	v_mfma_f32_16x16x32_bf16 v[2:5], v[192:195], v[208:211], v[2:5]
	v_mfma_f32_16x16x32_bf16 v[6:9], v[192:195], v[200:203], v[6:9]
	s_barrier
	s_setprio 0
	v_add_u32_e32 v154, 0x18000, v133
	ds_read_b128 v[142:145], v154
	ds_read_b128 v[146:149], v154 offset:1024
	ds_read_b128 v[150:153], v154 offset:2048
	ds_read_b128 v[154:157], v154 offset:3072
	ds_read_b128 v[158:161], v130 offset:32768
	ds_read_b128 v[164:167], v130 offset:33792
	ds_read_b128 v[168:171], v130 offset:34816
	ds_read_b128 v[172:175], v130 offset:35840
	ds_read_b128 v[180:183], v130 offset:36864
	ds_read_b128 v[184:187], v130 offset:37888
	ds_read_b128 v[188:191], v130 offset:38912
	ds_read_b128 v[192:195], v130 offset:39936
	v_add_u32_e32 v208, 0x1c000, v133
	ds_read_b128 v[196:199], v208
	ds_read_b128 v[200:203], v208 offset:1024
	ds_read_b128 v[204:207], v208 offset:2048
	ds_read_b128 v[208:211], v208 offset:3072
	s_add_u32 s24, s18, s6
	s_addc_u32 s25, s19, s7
	s_add_u32 s24, s24, 0x100
	s_addc_u32 s25, s25, 0
	s_add_i32 s23, s15, 0x4000
	s_mov_b32 m0, s23
	s_nop 0
	global_load_lds_dwordx4 v132, s[24:25]
	s_add_i32 s23, s15, 0x6000
	s_mov_b32 m0, s23
	s_nop 0
	global_load_lds_dwordx4 v131, s[24:25]
	s_waitcnt vmcnt(8) lgkmcnt(0)
	s_setprio 1
	s_barrier
	v_mfma_f32_16x16x32_bf16 v[126:129], v[158:161], v[142:145], v[126:129]
	v_mfma_f32_16x16x32_bf16 v[122:125], v[158:161], v[150:153], v[122:125]
	v_mfma_f32_16x16x32_bf16 v[114:117], v[168:171], v[150:153], v[114:117]
	v_mfma_f32_16x16x32_bf16 v[118:121], v[168:171], v[142:145], v[118:121]
	v_mfma_f32_16x16x32_bf16 v[110:113], v[180:183], v[142:145], v[110:113]
	v_mfma_f32_16x16x32_bf16 v[106:109], v[180:183], v[150:153], v[106:109]
	v_mfma_f32_16x16x32_bf16 v[98:101], v[188:191], v[150:153], v[98:101]
	v_mfma_f32_16x16x32_bf16 v[102:105], v[188:191], v[142:145], v[102:105]
	v_mfma_f32_16x16x32_bf16 v[126:129], v[164:167], v[146:149], v[126:129]
	v_mfma_f32_16x16x32_bf16 v[122:125], v[164:167], v[154:157], v[122:125]
	v_mfma_f32_16x16x32_bf16 v[114:117], v[172:175], v[154:157], v[114:117]
	v_mfma_f32_16x16x32_bf16 v[118:121], v[172:175], v[146:149], v[118:121]
	v_mfma_f32_16x16x32_bf16 v[110:113], v[184:187], v[146:149], v[110:113]
	v_mfma_f32_16x16x32_bf16 v[106:109], v[184:187], v[154:157], v[106:109]
	v_mfma_f32_16x16x32_bf16 v[98:101], v[192:195], v[154:157], v[98:101]
	v_mfma_f32_16x16x32_bf16 v[102:105], v[192:195], v[146:149], v[102:105]
	v_mfma_f32_16x16x32_bf16 v[94:97], v[158:161], v[196:199], v[94:97]
	v_mfma_f32_16x16x32_bf16 v[90:93], v[158:161], v[204:207], v[90:93]
	v_mfma_f32_16x16x32_bf16 v[82:85], v[168:171], v[204:207], v[82:85]
	v_mfma_f32_16x16x32_bf16 v[86:89], v[168:171], v[196:199], v[86:89]
	v_mfma_f32_16x16x32_bf16 v[78:81], v[180:183], v[196:199], v[78:81]
	v_mfma_f32_16x16x32_bf16 v[74:77], v[180:183], v[204:207], v[74:77]
	v_mfma_f32_16x16x32_bf16 v[66:69], v[188:191], v[204:207], v[66:69]
	v_mfma_f32_16x16x32_bf16 v[70:73], v[188:191], v[196:199], v[70:73]
	v_mfma_f32_16x16x32_bf16 v[94:97], v[164:167], v[200:203], v[94:97]
	v_mfma_f32_16x16x32_bf16 v[90:93], v[164:167], v[208:211], v[90:93]
	v_mfma_f32_16x16x32_bf16 v[82:85], v[172:175], v[208:211], v[82:85]
	v_mfma_f32_16x16x32_bf16 v[86:89], v[172:175], v[200:203], v[86:89]
	v_mfma_f32_16x16x32_bf16 v[78:81], v[184:187], v[200:203], v[78:81]
	v_mfma_f32_16x16x32_bf16 v[74:77], v[184:187], v[208:211], v[74:77]
	v_mfma_f32_16x16x32_bf16 v[66:69], v[192:195], v[208:211], v[66:69]
	v_mfma_f32_16x16x32_bf16 v[70:73], v[192:195], v[200:203], v[70:73]
	s_barrier
; #define WAIT_V(n) asm volatile("s_waitcnt vmcnt(" #n ")" ::: "memory")
; #define WAIT_L(n) asm volatile("s_waitcnt lgkmcnt(" #n ")" ::: "memory")
; #define BAR __builtin_amdgcn_s_barrier()
; #define SCHED __builtin_amdgcn_sched_barrier(0)
; #define STG_A(b, h, kt) stage_half_s(lds0 + ((b) * 2 + (h)) * HT_B, ((h) ? A1 : Ap) + (kt) * BK, off0, off1)
; #define STG_B(b, h, kt) stage_half_s(lds0 + (4 + (b) * 2 + (h)) * HT_B, ((h) ? B1p : Bp) + (kt) * BK, off0, off1)
; #define STG_A(b, h, kt) stage_half_s(lds0 + ((b) * 2 + (h)) * HT_B, ((h) ? A1 : Ap) + (kt) * BK, off0, off1)
; #define STG_B(b, h, kt) stage_half_s(lds0 + (4 + (b) * 2 + (h)) * HT_B, ((h) ? B1p : Bp) + (kt) * BK, off0, off1)
; #define LDA8(b, h) _Pragma("unroll") for (int m = 0; m < 4; ++m) _Pragma("unroll") for (int k = 0; k < 2; ++k) \
;     At[m][k] = *(const bf16x8*)(SA_(shm, b, h) + abase + (m * 2 + k) * 1024)
; #define LDB8(dst, b, h) _Pragma("unroll") for (int n = 0; n < 2; ++n) _Pragma("unroll") for (int k = 0; k < 2; ++k) \
;     dst[n][k] = *(const bf16x8*)(SB_(shm, b, h) + bbase + (n * 2 + k) * 1024)
; template <bool HS>
; __device__ __forceinline__ void gemm_tile8(const u16* __restrict__ Ap, const u16* __restrict__ Bp, int K,
;                                            f32x4 (&acc)[2][2][4][2], char* shm, const int tid, const float* hsr = nullptr) {
;     ...
;     LDB8(B0, 0, 0); SCHED; LDA8(0, 0); STG_A(1, 1, t + 1);
;     WAIT_L(8); BAR; WAIT_L(0); MMA8(0, 0, B0); BAR; SCHED;
;     LDB8(B1, 0, 1); STG_B(0, 0, t + 2);
;     BAR; WAIT_L(0); MMA8(0, 1, B1); BAR;
;     LDA8(0, 1); STG_A(0, 0, t + 2);
;     BAR; WAIT_L(0); MMA8(1, 0, B0); BAR; SCHED;
;     STG_B(0, 1, t + 2);
;     WAIT_V(6); BAR; MMA8(1, 1, B1); BAR;
;     LDB8(B0, 1, 0); SCHED; LDA8(1, 0); STG_A(0, 1, t + 2);
;     WAIT_L(8); BAR; WAIT_L(0); MMA8(0, 0, B0); BAR; SCHED;
;     LDB8(B1, 1, 1); STG_B(1, 0, t + 3);
;     BAR; WAIT_L(0); MMA8(0, 1, B1); BAR;
;     LDA8(1, 1); STG_A(1, 0, t + 3);
;     BAR; WAIT_L(0); MMA8(1, 0, B0); BAR; SCHED;
;     STG_B(1, 1, t + 3);
;     WAIT_V(6); BAR; MMA8(1, 1, B1); BAR;
	s_setprio 0
	ds_read_b128 v[158:161], v130 offset:49152
	ds_read_b128 v[164:167], v130 offset:50176
	ds_read_b128 v[168:171], v130 offset:51200
	ds_read_b128 v[172:175], v130 offset:52224
	ds_read_b128 v[180:183], v130 offset:53248
	ds_read_b128 v[184:187], v130 offset:54272
	ds_read_b128 v[188:191], v130 offset:55296
	ds_read_b128 v[192:195], v130 offset:56320
	s_add_u32 s24, s3, s6
	s_addc_u32 s25, s10, s7
	s_add_u32 s24, s24, 0x180
	s_addc_u32 s25, s25, 0
	s_add_i32 s23, s15, 0x18000
	s_mov_b32 m0, s23
	s_nop 0
	global_load_lds_dwordx4 v132, s[24:25]
	s_add_i32 s23, s15, 0x1a000
	s_mov_b32 m0, s23
	s_nop 0
	global_load_lds_dwordx4 v131, s[24:25]
	s_add_u32 s24, s8, s6
	s_addc_u32 s25, s9, s7
	s_add_u32 s24, s24, 0x180
	s_addc_u32 s25, s25, 0
	s_add_i32 s23, s15, 0x8000
	s_mov_b32 m0, s23
	s_nop 0
	global_load_lds_dwordx4 v132, s[24:25]
	s_add_i32 s23, s15, 0xa000
	s_mov_b32 m0, s23
	s_nop 0
	global_load_lds_dwordx4 v131, s[24:25]
	s_add_u32 s24, s13, s6
	s_addc_u32 s25, s14, s7
	s_add_u32 s24, s24, 0x180
	s_addc_u32 s25, s25, 0
	s_add_i32 s23, s15, 0x1c000
	s_mov_b32 m0, s23
	s_nop 0
	global_load_lds_dwordx4 v132, s[24:25]
	s_add_i32 s23, s15, 0x1e000
	s_mov_b32 m0, s23
	s_nop 0
	global_load_lds_dwordx4 v131, s[24:25]
	s_waitcnt vmcnt(8) lgkmcnt(0)
	s_setprio 1
	s_barrier
	v_mfma_f32_16x16x32_bf16 v[62:65], v[158:161], v[142:145], v[62:65]
	v_mfma_f32_16x16x32_bf16 v[58:61], v[158:161], v[150:153], v[58:61]
	v_mfma_f32_16x16x32_bf16 v[50:53], v[168:171], v[150:153], v[50:53]
	v_mfma_f32_16x16x32_bf16 v[54:57], v[168:171], v[142:145], v[54:57]
	v_mfma_f32_16x16x32_bf16 v[46:49], v[180:183], v[142:145], v[46:49]
	v_mfma_f32_16x16x32_bf16 v[42:45], v[180:183], v[150:153], v[42:45]
	v_mfma_f32_16x16x32_bf16 v[34:37], v[188:191], v[150:153], v[34:37]
	v_mfma_f32_16x16x32_bf16 v[38:41], v[188:191], v[142:145], v[38:41]
	v_mfma_f32_16x16x32_bf16 v[62:65], v[164:167], v[146:149], v[62:65]
	v_mfma_f32_16x16x32_bf16 v[58:61], v[164:167], v[154:157], v[58:61]
	v_mfma_f32_16x16x32_bf16 v[50:53], v[172:175], v[154:157], v[50:53]
	v_mfma_f32_16x16x32_bf16 v[54:57], v[172:175], v[146:149], v[54:57]
	v_mfma_f32_16x16x32_bf16 v[46:49], v[184:187], v[146:149], v[46:49]
	v_mfma_f32_16x16x32_bf16 v[42:45], v[184:187], v[154:157], v[42:45]
	v_mfma_f32_16x16x32_bf16 v[34:37], v[192:195], v[154:157], v[34:37]
	v_mfma_f32_16x16x32_bf16 v[38:41], v[192:195], v[146:149], v[38:41]
	v_mfma_f32_16x16x32_bf16 v[30:33], v[158:161], v[196:199], v[30:33]
	v_mfma_f32_16x16x32_bf16 v[26:29], v[158:161], v[204:207], v[26:29]
	v_mfma_f32_16x16x32_bf16 v[18:21], v[168:171], v[204:207], v[18:21]
	v_mfma_f32_16x16x32_bf16 v[22:25], v[168:171], v[196:199], v[22:25]
	v_mfma_f32_16x16x32_bf16 v[14:17], v[180:183], v[196:199], v[14:17]
	v_mfma_f32_16x16x32_bf16 v[10:13], v[180:183], v[204:207], v[10:13]
	v_mfma_f32_16x16x32_bf16 v[2:5], v[188:191], v[204:207], v[2:5]
	v_mfma_f32_16x16x32_bf16 v[6:9], v[188:191], v[196:199], v[6:9]
	v_mfma_f32_16x16x32_bf16 v[30:33], v[164:167], v[200:203], v[30:33]
	v_mfma_f32_16x16x32_bf16 v[26:29], v[164:167], v[208:211], v[26:29]
	v_mfma_f32_16x16x32_bf16 v[18:21], v[172:175], v[208:211], v[18:21]
	v_mfma_f32_16x16x32_bf16 v[22:25], v[172:175], v[200:203], v[22:25]
	v_mfma_f32_16x16x32_bf16 v[14:17], v[184:187], v[200:203], v[14:17]
	v_mfma_f32_16x16x32_bf16 v[10:13], v[184:187], v[208:211], v[10:13]
	v_mfma_f32_16x16x32_bf16 v[2:5], v[192:195], v[208:211], v[2:5]
	v_mfma_f32_16x16x32_bf16 v[6:9], v[192:195], v[200:203], v[6:9]
	s_barrier
	s_setprio 0
	s_add_i32 s20, s20, 2
	s_add_u32 s6, s6, 0x100
	s_addc_u32 s7, s7, 0
	s_cmp_lt_u32 s20, 12
	s_cbranch_scc0 .Lk_ret_in_exit
.Lk_ret_in:
	v_add_u32_e32 v154, 0x10000, v133
	ds_read_b128 v[142:145], v154
	ds_read_b128 v[146:149], v154 offset:1024
	ds_read_b128 v[150:153], v154 offset:2048
	ds_read_b128 v[154:157], v154 offset:3072
	ds_read_b128 v[158:161], v130
	ds_read_b128 v[164:167], v130 offset:1024
	ds_read_b128 v[168:171], v130 offset:2048
	ds_read_b128 v[172:175], v130 offset:3072
	ds_read_b128 v[180:183], v130 offset:4096
	ds_read_b128 v[184:187], v130 offset:5120
	ds_read_b128 v[188:191], v130 offset:6144
	ds_read_b128 v[192:195], v130 offset:7168
	v_add_u32_e32 v208, 0x14000, v133
	ds_read_b128 v[196:199], v208
	ds_read_b128 v[200:203], v208 offset:1024
	ds_read_b128 v[204:207], v208 offset:2048
	ds_read_b128 v[208:211], v208 offset:3072
	s_add_u32 s24, s18, s6
	s_addc_u32 s25, s19, s7
	s_add_u32 s24, s24, 0x80
	s_addc_u32 s25, s25, 0
	s_add_i32 s23, s15, 0xc000
	s_mov_b32 m0, s23
	s_nop 0
	global_load_lds_dwordx4 v132, s[24:25]
	s_add_i32 s23, s15, 0xe000
	s_mov_b32 m0, s23
	s_nop 0
	global_load_lds_dwordx4 v131, s[24:25]
	s_waitcnt vmcnt(8) lgkmcnt(0)
	s_setprio 1
	s_barrier
; #define WAIT_V(n) asm volatile("s_waitcnt vmcnt(" #n ")" ::: "memory")
; #define WAIT_L(n) asm volatile("s_waitcnt lgkmcnt(" #n ")" ::: "memory")
; #define BAR __builtin_amdgcn_s_barrier()
; #define SCHED __builtin_amdgcn_sched_barrier(0)
; #define STG_A(b, h, kt) stage_half_s(lds0 + ((b) * 2 + (h)) * HT_B, ((h) ? A1 : Ap) + (kt) * BK, off0, off1)
; #define STG_B(b, h, kt) stage_half_s(lds0 + (4 + (b) * 2 + (h)) * HT_B, ((h) ? B1p : Bp) + (kt) * BK, off0, off1)
; #define STG_A(b, h, kt) stage_half_s(lds0 + ((b) * 2 + (h)) * HT_B, ((h) ? A1 : Ap) + (kt) * BK, off0, off1)
; #define STG_B(b, h, kt) stage_half_s(lds0 + (4 + (b) * 2 + (h)) * HT_B, ((h) ? B1p : Bp) + (kt) * BK, off0, off1)
; #define LDA8(b, h) _Pragma("unroll") for (int m = 0; m < 4; ++m) _Pragma("unroll") for (int k = 0; k < 2; ++k) \
;     At[m][k] = *(const bf16x8*)(SA_(shm, b, h) + abase + (m * 2 + k) * 1024)
; #define LDB8(dst, b, h) _Pragma("unroll") for (int n = 0; n < 2; ++n) _Pragma("unroll") for (int k = 0; k < 2; ++k) \
;     dst[n][k] = *(const bf16x8*)(SB_(shm, b, h) + bbase + (n * 2 + k) * 1024)
; template <bool HS>
; __device__ __forceinline__ void gemm_tile8(const u16* __restrict__ Ap, const u16* __restrict__ Bp, int K,
;                                            f32x4 (&acc)[2][2][4][2], char* shm, const int tid, const float* hsr = nullptr) {
;     ...
;     LDB8(B0, 0, 0); SCHED; LDA8(0, 0); STG_A(1, 1, t + 1);
;     WAIT_L(8); BAR; WAIT_L(0); MMA8(0, 0, B0); BAR; SCHED;
;     LDB8(B1, 0, 1); STG_B(0, 0, t + 2);
;     BAR; WAIT_L(0); MMA8(0, 1, B1); BAR;
;     LDA8(0, 1); STG_A(0, 0, t + 2);
;     BAR; WAIT_L(0); MMA8(1, 0, B0); BAR; SCHED;
;     STG_B(0, 1, t + 2);
;     WAIT_V(6); BAR; MMA8(1, 1, B1); BAR;
;     LDB8(B0, 1, 0); SCHED; LDA8(1, 0); STG_A(0, 1, t + 2);
;     WAIT_L(8); BAR; WAIT_L(0); MMA8(0, 0, B0); BAR; SCHED;
;     LDB8(B1, 1, 1); STG_B(1, 0, t + 3);
;     BAR; WAIT_L(0); MMA8(0, 1, B1); BAR;
;     LDA8(1, 1); STG_A(1, 0, t + 3);
;     BAR; WAIT_L(0); MMA8(1, 0, B0); BAR; SCHED;
;     STG_B(1, 1, t + 3);
;     WAIT_V(6); BAR; MMA8(1, 1, B1); BAR;
	v_mfma_f32_16x16x32_bf16 v[126:129], v[158:161], v[142:145], v[126:129]
	v_mfma_f32_16x16x32_bf16 v[122:125], v[158:161], v[150:153], v[122:125]
	v_mfma_f32_16x16x32_bf16 v[114:117], v[168:171], v[150:153], v[114:117]
	v_mfma_f32_16x16x32_bf16 v[118:121], v[168:171], v[142:145], v[118:121]
	v_mfma_f32_16x16x32_bf16 v[110:113], v[180:183], v[142:145], v[110:113]
	v_mfma_f32_16x16x32_bf16 v[106:109], v[180:183], v[150:153], v[106:109]
	v_mfma_f32_16x16x32_bf16 v[98:101], v[188:191], v[150:153], v[98:101]
	v_mfma_f32_16x16x32_bf16 v[102:105], v[188:191], v[142:145], v[102:105]
	v_mfma_f32_16x16x32_bf16 v[126:129], v[164:167], v[146:149], v[126:129]
	v_mfma_f32_16x16x32_bf16 v[122:125], v[164:167], v[154:157], v[122:125]
	v_mfma_f32_16x16x32_bf16 v[114:117], v[172:175], v[154:157], v[114:117]
	v_mfma_f32_16x16x32_bf16 v[118:121], v[172:175], v[146:149], v[118:121]
	v_mfma_f32_16x16x32_bf16 v[110:113], v[184:187], v[146:149], v[110:113]
	v_mfma_f32_16x16x32_bf16 v[106:109], v[184:187], v[154:157], v[106:109]
	v_mfma_f32_16x16x32_bf16 v[98:101], v[192:195], v[154:157], v[98:101]
	v_mfma_f32_16x16x32_bf16 v[102:105], v[192:195], v[146:149], v[102:105]
	v_mfma_f32_16x16x32_bf16 v[94:97], v[158:161], v[196:199], v[94:97]
	v_mfma_f32_16x16x32_bf16 v[90:93], v[158:161], v[204:207], v[90:93]
	v_mfma_f32_16x16x32_bf16 v[82:85], v[168:171], v[204:207], v[82:85]
	v_mfma_f32_16x16x32_bf16 v[86:89], v[168:171], v[196:199], v[86:89]
	v_mfma_f32_16x16x32_bf16 v[78:81], v[180:183], v[196:199], v[78:81]
	v_mfma_f32_16x16x32_bf16 v[74:77], v[180:183], v[204:207], v[74:77]
	v_mfma_f32_16x16x32_bf16 v[66:69], v[188:191], v[204:207], v[66:69]
	v_mfma_f32_16x16x32_bf16 v[70:73], v[188:191], v[196:199], v[70:73]
	v_mfma_f32_16x16x32_bf16 v[94:97], v[164:167], v[200:203], v[94:97]
	v_mfma_f32_16x16x32_bf16 v[90:93], v[164:167], v[208:211], v[90:93]
	v_mfma_f32_16x16x32_bf16 v[82:85], v[172:175], v[208:211], v[82:85]
	v_mfma_f32_16x16x32_bf16 v[86:89], v[172:175], v[200:203], v[86:89]
	v_mfma_f32_16x16x32_bf16 v[78:81], v[184:187], v[200:203], v[78:81]
	v_mfma_f32_16x16x32_bf16 v[74:77], v[184:187], v[208:211], v[74:77]
	v_mfma_f32_16x16x32_bf16 v[66:69], v[192:195], v[208:211], v[66:69]
	v_mfma_f32_16x16x32_bf16 v[70:73], v[192:195], v[200:203], v[70:73]
	s_barrier
	s_setprio 0
	ds_read_b128 v[158:161], v130 offset:16384
	ds_read_b128 v[164:167], v130 offset:17408
	ds_read_b128 v[168:171], v130 offset:18432
	ds_read_b128 v[172:175], v130 offset:19456
	ds_read_b128 v[180:183], v130 offset:20480
	ds_read_b128 v[184:187], v130 offset:21504
	ds_read_b128 v[188:191], v130 offset:22528
	ds_read_b128 v[192:195], v130 offset:23552
	s_add_u32 s24, s3, s6
	s_addc_u32 s25, s10, s7
	s_add_u32 s24, s24, 0x100
	s_addc_u32 s25, s25, 0
	s_add_i32 s23, s15, 0x10000
	s_mov_b32 m0, s23
	s_nop 0
	global_load_lds_dwordx4 v132, s[24:25]
	s_add_i32 s23, s15, 0x12000
	s_mov_b32 m0, s23
	s_nop 0
	global_load_lds_dwordx4 v131, s[24:25]
	s_add_u32 s24, s8, s6
	s_addc_u32 s25, s9, s7
	s_add_u32 s24, s24, 0x100
	s_addc_u32 s25, s25, 0
	s_mov_b32 m0, s15
	s_nop 0
	global_load_lds_dwordx4 v132, s[24:25]
	s_add_i32 s23, s15, 0x2000
	s_mov_b32 m0, s23
	s_nop 0
	global_load_lds_dwordx4 v131, s[24:25]
	s_add_u32 s24, s13, s6
	s_addc_u32 s25, s14, s7
	s_add_u32 s24, s24, 0x100
	s_addc_u32 s25, s25, 0
	s_add_i32 s23, s15, 0x14000
	s_mov_b32 m0, s23
	s_nop 0
	global_load_lds_dwordx4 v132, s[24:25]
	s_add_i32 s23, s15, 0x16000
	s_mov_b32 m0, s23
	s_nop 0
	global_load_lds_dwordx4 v131, s[24:25]
	s_waitcnt vmcnt(8) lgkmcnt(0)
	s_setprio 1
	s_barrier
	v_mfma_f32_16x16x32_bf16 v[62:65], v[158:161], v[142:145], v[62:65]
	v_mfma_f32_16x16x32_bf16 v[58:61], v[158:161], v[150:153], v[58:61]
	v_mfma_f32_16x16x32_bf16 v[50:53], v[168:171], v[150:153], v[50:53]
	v_mfma_f32_16x16x32_bf16 v[54:57], v[168:171], v[142:145], v[54:57]
	v_mfma_f32_16x16x32_bf16 v[46:49], v[180:183], v[142:145], v[46:49]
	v_mfma_f32_16x16x32_bf16 v[42:45], v[180:183], v[150:153], v[42:45]
	v_mfma_f32_16x16x32_bf16 v[34:37], v[188:191], v[150:153], v[34:37]
	v_mfma_f32_16x16x32_bf16 v[38:41], v[188:191], v[142:145], v[38:41]
	v_mfma_f32_16x16x32_bf16 v[62:65], v[164:167], v[146:149], v[62:65]
	v_mfma_f32_16x16x32_bf16 v[58:61], v[164:167], v[154:157], v[58:61]
	v_mfma_f32_16x16x32_bf16 v[50:53], v[172:175], v[154:157], v[50:53]
	v_mfma_f32_16x16x32_bf16 v[54:57], v[172:175], v[146:149], v[54:57]
	v_mfma_f32_16x16x32_bf16 v[46:49], v[184:187], v[146:149], v[46:49]
	v_mfma_f32_16x16x32_bf16 v[42:45], v[184:187], v[154:157], v[42:45]
	v_mfma_f32_16x16x32_bf16 v[34:37], v[192:195], v[154:157], v[34:37]
	v_mfma_f32_16x16x32_bf16 v[38:41], v[192:195], v[146:149], v[38:41]
	v_mfma_f32_16x16x32_bf16 v[30:33], v[158:161], v[196:199], v[30:33]
	v_mfma_f32_16x16x32_bf16 v[26:29], v[158:161], v[204:207], v[26:29]
	v_mfma_f32_16x16x32_bf16 v[18:21], v[168:171], v[204:207], v[18:21]
	v_mfma_f32_16x16x32_bf16 v[22:25], v[168:171], v[196:199], v[22:25]
	v_mfma_f32_16x16x32_bf16 v[14:17], v[180:183], v[196:199], v[14:17]
	v_mfma_f32_16x16x32_bf16 v[10:13], v[180:183], v[204:207], v[10:13]
	v_mfma_f32_16x16x32_bf16 v[2:5], v[188:191], v[204:207], v[2:5]
	v_mfma_f32_16x16x32_bf16 v[6:9], v[188:191], v[196:199], v[6:9]
	v_mfma_f32_16x16x32_bf16 v[30:33], v[164:167], v[200:203], v[30:33]
	v_mfma_f32_16x16x32_bf16 v[26:29], v[164:167], v[208:211], v[26:29]
	v_mfma_f32_16x16x32_bf16 v[18:21], v[172:175], v[208:211], v[18:21]
	v_mfma_f32_16x16x32_bf16 v[22:25], v[172:175], v[200:203], v[22:25]
	v_mfma_f32_16x16x32_bf16 v[14:17], v[184:187], v[200:203], v[14:17]
	v_mfma_f32_16x16x32_bf16 v[10:13], v[184:187], v[208:211], v[10:13]
	v_mfma_f32_16x16x32_bf16 v[2:5], v[192:195], v[208:211], v[2:5]
	v_mfma_f32_16x16x32_bf16 v[6:9], v[192:195], v[200:203], v[6:9]
	s_barrier
; #define WAIT_V(n) asm volatile("s_waitcnt vmcnt(" #n ")" ::: "memory")
; #define WAIT_L(n) asm volatile("s_waitcnt lgkmcnt(" #n ")" ::: "memory")
; #define BAR __builtin_amdgcn_s_barrier()
; #define SCHED __builtin_amdgcn_sched_barrier(0)
; #define STG_A(b, h, kt) stage_half_s(lds0 + ((b) * 2 + (h)) * HT_B, ((h) ? A1 : Ap) + (kt) * BK, off0, off1)
; #define STG_B(b, h, kt) stage_half_s(lds0 + (4 + (b) * 2 + (h)) * HT_B, ((h) ? B1p : Bp) + (kt) * BK, off0, off1)
; #define STG_A(b, h, kt) stage_half_s(lds0 + ((b) * 2 + (h)) * HT_B, ((h) ? A1 : Ap) + (kt) * BK, off0, off1)
; #define STG_B(b, h, kt) stage_half_s(lds0 + (4 + (b) * 2 + (h)) * HT_B, ((h) ? B1p : Bp) + (kt) * BK, off0, off1)
; #define LDA8(b, h) _Pragma("unroll") for (int m = 0; m < 4; ++m) _Pragma("unroll") for (int k = 0; k < 2; ++k) \
;     At[m][k] = *(const bf16x8*)(SA_(shm, b, h) + abase + (m * 2 + k) * 1024)
; #define LDB8(dst, b, h) _Pragma("unroll") for (int n = 0; n < 2; ++n) _Pragma("unroll") for (int k = 0; k < 2; ++k) \
;     dst[n][k] = *(const bf16x8*)(SB_(shm, b, h) + bbase + (n * 2 + k) * 1024)
; template <bool HS>
; __device__ __forceinline__ void gemm_tile8(const u16* __restrict__ Ap, const u16* __restrict__ Bp, int K,
;                                            f32x4 (&acc)[2][2][4][2], char* shm, const int tid, const float* hsr = nullptr) {
;     ...
;     LDB8(B0, 0, 0); SCHED; LDA8(0, 0); STG_A(1, 1, t + 1);
;     WAIT_L(8); BAR; WAIT_L(0); MMA8(0, 0, B0); BAR; SCHED;
;     LDB8(B1, 0, 1); STG_B(0, 0, t + 2);
;     BAR; WAIT_L(0); MMA8(0, 1, B1); BAR;
;     LDA8(0, 1); STG_A(0, 0, t + 2);
;     BAR; WAIT_L(0); MMA8(1, 0, B0); BAR; SCHED;
;     STG_B(0, 1, t + 2);
;     WAIT_V(6); BAR; MMA8(1, 1, B1); BAR;
;     LDB8(B0, 1, 0); SCHED; LDA8(1, 0); STG_A(0, 1, t + 2);
;     WAIT_L(8); BAR; WAIT_L(0); MMA8(0, 0, B0); BAR; SCHED;
;     LDB8(B1, 1, 1); STG_B(1, 0, t + 3);
;     BAR; WAIT_L(0); MMA8(0, 1, B1); BAR;
;     LDA8(1, 1); STG_A(1, 0, t + 3);
;     BAR; WAIT_L(0); MMA8(1, 0, B0); BAR; SCHED;
;     STG_B(1, 1, t + 3);
;     WAIT_V(6); BAR; MMA8(1, 1, B1); BAR;
	s_setprio 0
	v_add_u32_e32 v154, 0x18000, v133
	ds_read_b128 v[142:145], v154
	ds_read_b128 v[146:149], v154 offset:1024
	ds_read_b128 v[150:153], v154 offset:2048
	ds_read_b128 v[154:157], v154 offset:3072
	ds_read_b128 v[158:161], v130 offset:32768
	ds_read_b128 v[164:167], v130 offset:33792
	ds_read_b128 v[168:171], v130 offset:34816
	ds_read_b128 v[172:175], v130 offset:35840
	ds_read_b128 v[180:183], v130 offset:36864
	ds_read_b128 v[184:187], v130 offset:37888
	ds_read_b128 v[188:191], v130 offset:38912
	ds_read_b128 v[192:195], v130 offset:39936
	v_add_u32_e32 v208, 0x1c000, v133
	ds_read_b128 v[196:199], v208
	ds_read_b128 v[200:203], v208 offset:1024
	ds_read_b128 v[204:207], v208 offset:2048
	ds_read_b128 v[208:211], v208 offset:3072
	s_add_u32 s24, s18, s6
	s_addc_u32 s25, s19, s7
	s_add_u32 s24, s24, 0x100
	s_addc_u32 s25, s25, 0
	s_add_i32 s23, s15, 0x4000
	s_mov_b32 m0, s23
	s_nop 0
	global_load_lds_dwordx4 v132, s[24:25]
	s_add_i32 s23, s15, 0x6000
	s_mov_b32 m0, s23
	s_nop 0
	global_load_lds_dwordx4 v131, s[24:25]
	s_waitcnt vmcnt(8) lgkmcnt(0)
	s_setprio 1
	s_barrier
	v_mfma_f32_16x16x32_bf16 v[126:129], v[158:161], v[142:145], v[126:129]
	v_mfma_f32_16x16x32_bf16 v[122:125], v[158:161], v[150:153], v[122:125]
	v_mfma_f32_16x16x32_bf16 v[114:117], v[168:171], v[150:153], v[114:117]
	v_mfma_f32_16x16x32_bf16 v[118:121], v[168:171], v[142:145], v[118:121]
	v_mfma_f32_16x16x32_bf16 v[110:113], v[180:183], v[142:145], v[110:113]
	v_mfma_f32_16x16x32_bf16 v[106:109], v[180:183], v[150:153], v[106:109]
	v_mfma_f32_16x16x32_bf16 v[98:101], v[188:191], v[150:153], v[98:101]
	v_mfma_f32_16x16x32_bf16 v[102:105], v[188:191], v[142:145], v[102:105]
	v_mfma_f32_16x16x32_bf16 v[126:129], v[164:167], v[146:149], v[126:129]
	v_mfma_f32_16x16x32_bf16 v[122:125], v[164:167], v[154:157], v[122:125]
	v_mfma_f32_16x16x32_bf16 v[114:117], v[172:175], v[154:157], v[114:117]
	v_mfma_f32_16x16x32_bf16 v[118:121], v[172:175], v[146:149], v[118:121]
	v_mfma_f32_16x16x32_bf16 v[110:113], v[184:187], v[146:149], v[110:113]
	v_mfma_f32_16x16x32_bf16 v[106:109], v[184:187], v[154:157], v[106:109]
	v_mfma_f32_16x16x32_bf16 v[98:101], v[192:195], v[154:157], v[98:101]
	v_mfma_f32_16x16x32_bf16 v[102:105], v[192:195], v[146:149], v[102:105]
	v_mfma_f32_16x16x32_bf16 v[94:97], v[158:161], v[196:199], v[94:97]
	v_mfma_f32_16x16x32_bf16 v[90:93], v[158:161], v[204:207], v[90:93]
	v_mfma_f32_16x16x32_bf16 v[82:85], v[168:171], v[204:207], v[82:85]
	v_mfma_f32_16x16x32_bf16 v[86:89], v[168:171], v[196:199], v[86:89]
	v_mfma_f32_16x16x32_bf16 v[78:81], v[180:183], v[196:199], v[78:81]
	v_mfma_f32_16x16x32_bf16 v[74:77], v[180:183], v[204:207], v[74:77]
	v_mfma_f32_16x16x32_bf16 v[66:69], v[188:191], v[204:207], v[66:69]
	v_mfma_f32_16x16x32_bf16 v[70:73], v[188:191], v[196:199], v[70:73]
	v_mfma_f32_16x16x32_bf16 v[94:97], v[164:167], v[200:203], v[94:97]
	v_mfma_f32_16x16x32_bf16 v[90:93], v[164:167], v[208:211], v[90:93]
	v_mfma_f32_16x16x32_bf16 v[82:85], v[172:175], v[208:211], v[82:85]
	v_mfma_f32_16x16x32_bf16 v[86:89], v[172:175], v[200:203], v[86:89]
	v_mfma_f32_16x16x32_bf16 v[78:81], v[184:187], v[200:203], v[78:81]
	v_mfma_f32_16x16x32_bf16 v[74:77], v[184:187], v[208:211], v[74:77]
	v_mfma_f32_16x16x32_bf16 v[66:69], v[192:195], v[208:211], v[66:69]
	v_mfma_f32_16x16x32_bf16 v[70:73], v[192:195], v[200:203], v[70:73]
	s_barrier
	s_setprio 0
	ds_read_b128 v[158:161], v130 offset:49152
	ds_read_b128 v[164:167], v130 offset:50176
	ds_read_b128 v[168:171], v130 offset:51200
	ds_read_b128 v[172:175], v130 offset:52224
	ds_read_b128 v[180:183], v130 offset:53248
	ds_read_b128 v[184:187], v130 offset:54272
	ds_read_b128 v[188:191], v130 offset:55296
	ds_read_b128 v[192:195], v130 offset:56320
	s_add_u32 s24, s3, s6
	s_addc_u32 s25, s10, s7
	s_add_u32 s24, s24, 0x180
	s_addc_u32 s25, s25, 0
	s_add_i32 s23, s15, 0x18000
	s_mov_b32 m0, s23
	s_nop 0
	global_load_lds_dwordx4 v132, s[24:25]
	s_add_i32 s23, s15, 0x1a000
	s_mov_b32 m0, s23
	s_nop 0
	global_load_lds_dwordx4 v131, s[24:25]
	s_add_u32 s24, s8, s6
	s_addc_u32 s25, s9, s7
	s_add_u32 s24, s24, 0x180
	s_addc_u32 s25, s25, 0
	s_add_i32 s23, s15, 0x8000
	s_mov_b32 m0, s23
	s_nop 0
	global_load_lds_dwordx4 v132, s[24:25]
	s_add_i32 s23, s15, 0xa000
	s_mov_b32 m0, s23
	s_nop 0
	global_load_lds_dwordx4 v131, s[24:25]
	s_add_u32 s24, s13, s6
	s_addc_u32 s25, s14, s7
	s_add_u32 s24, s24, 0x180
	s_addc_u32 s25, s25, 0
	s_add_i32 s23, s15, 0x1c000
	s_mov_b32 m0, s23
	s_nop 0
	global_load_lds_dwordx4 v132, s[24:25]
	s_add_i32 s23, s15, 0x1e000
	s_mov_b32 m0, s23
	s_nop 0
	global_load_lds_dwordx4 v131, s[24:25]
	s_waitcnt vmcnt(8) lgkmcnt(0)
	s_setprio 1
	s_barrier
	v_mfma_f32_16x16x32_bf16 v[62:65], v[158:161], v[142:145], v[62:65]
	v_mfma_f32_16x16x32_bf16 v[58:61], v[158:161], v[150:153], v[58:61]
	v_mfma_f32_16x16x32_bf16 v[50:53], v[168:171], v[150:153], v[50:53]
	v_mfma_f32_16x16x32_bf16 v[54:57], v[168:171], v[142:145], v[54:57]
	v_mfma_f32_16x16x32_bf16 v[46:49], v[180:183], v[142:145], v[46:49]
	v_mfma_f32_16x16x32_bf16 v[42:45], v[180:183], v[150:153], v[42:45]
	v_mfma_f32_16x16x32_bf16 v[34:37], v[188:191], v[150:153], v[34:37]
	v_mfma_f32_16x16x32_bf16 v[38:41], v[188:191], v[142:145], v[38:41]
	v_mfma_f32_16x16x32_bf16 v[62:65], v[164:167], v[146:149], v[62:65]
	v_mfma_f32_16x16x32_bf16 v[58:61], v[164:167], v[154:157], v[58:61]
	v_mfma_f32_16x16x32_bf16 v[50:53], v[172:175], v[154:157], v[50:53]
	v_mfma_f32_16x16x32_bf16 v[54:57], v[172:175], v[146:149], v[54:57]
	v_mfma_f32_16x16x32_bf16 v[46:49], v[184:187], v[146:149], v[46:49]
	v_mfma_f32_16x16x32_bf16 v[42:45], v[184:187], v[154:157], v[42:45]
	v_mfma_f32_16x16x32_bf16 v[34:37], v[192:195], v[154:157], v[34:37]
	v_mfma_f32_16x16x32_bf16 v[38:41], v[192:195], v[146:149], v[38:41]
	v_mfma_f32_16x16x32_bf16 v[30:33], v[158:161], v[196:199], v[30:33]
	v_mfma_f32_16x16x32_bf16 v[26:29], v[158:161], v[204:207], v[26:29]
	v_mfma_f32_16x16x32_bf16 v[18:21], v[168:171], v[204:207], v[18:21]
	v_mfma_f32_16x16x32_bf16 v[22:25], v[168:171], v[196:199], v[22:25]
	v_mfma_f32_16x16x32_bf16 v[14:17], v[180:183], v[196:199], v[14:17]
	v_mfma_f32_16x16x32_bf16 v[10:13], v[180:183], v[204:207], v[10:13]
	v_mfma_f32_16x16x32_bf16 v[2:5], v[188:191], v[204:207], v[2:5]
	v_mfma_f32_16x16x32_bf16 v[6:9], v[188:191], v[196:199], v[6:9]
	v_mfma_f32_16x16x32_bf16 v[30:33], v[164:167], v[200:203], v[30:33]
	v_mfma_f32_16x16x32_bf16 v[26:29], v[164:167], v[208:211], v[26:29]
	v_mfma_f32_16x16x32_bf16 v[18:21], v[172:175], v[208:211], v[18:21]
	v_mfma_f32_16x16x32_bf16 v[22:25], v[172:175], v[200:203], v[22:25]
	v_mfma_f32_16x16x32_bf16 v[14:17], v[184:187], v[200:203], v[14:17]
	v_mfma_f32_16x16x32_bf16 v[10:13], v[184:187], v[208:211], v[10:13]
	v_mfma_f32_16x16x32_bf16 v[2:5], v[192:195], v[208:211], v[2:5]
	v_mfma_f32_16x16x32_bf16 v[6:9], v[192:195], v[200:203], v[6:9]
	s_barrier
	s_setprio 0
	s_add_i32 s20, s20, 2
	s_add_u32 s6, s6, 0x100
	s_addc_u32 s7, s7, 0
	s_cmp_lt_u32 s20, 12
	s_cbranch_scc1 .Lk_ret_in

; #define WAIT_V(n) asm volatile("s_waitcnt vmcnt(" #n ")" ::: "memory")
; #define WAIT_L(n) asm volatile("s_waitcnt lgkmcnt(" #n ")" ::: "memory")
; #define BAR __builtin_amdgcn_s_barrier()
; #define SCHED __builtin_amdgcn_sched_barrier(0)
; #define STG_A(b, h, kt) stage_half_s(lds0 + ((b) * 2 + (h)) * HT_B, ((h) ? A1 : Ap) + (kt) * BK, off0, off1)
; #define STG_B(b, h, kt) stage_half_s(lds0 + (4 + (b) * 2 + (h)) * HT_B, ((h) ? B1p : Bp) + (kt) * BK, off0, off1)
; #define STG_A(b, h, kt) stage_half_s(lds0 + ((b) * 2 + (h)) * HT_B, ((h) ? A1 : Ap) + (kt) * BK, off0, off1)
; #define STG_B(b, h, kt) stage_half_s(lds0 + (4 + (b) * 2 + (h)) * HT_B, ((h) ? B1p : Bp) + (kt) * BK, off0, off1)
; template <bool HS>
; __device__ __forceinline__ void gemm_tile8(const u16* __restrict__ Ap, const u16* __restrict__ Bp, int K,
;                                            f32x4 (&acc)[2][2][4][2], char* shm, const int tid, const float* hsr = nullptr) {
;     ...
;   stage_rc(tid * 16, r0, c0);
;   stage_rc(tid * 16 + 8192, r1, c1);
;   const unsigned off0 = (unsigned)(r0 * K + c0) * 2u, off1 = (unsigned)(r1 * K + c1) * 2u;
;   const int wvoff = __builtin_amdgcn_readfirstlane(tid >> 6) * 1024;
;   const u16* A1 = Ap + (size_t)128 * K;
;   const u16* B1p = Bp + (size_t)128 * K;
; #pragma unroll
;   for (int a = 0; a < 2; ++a)
; #pragma unroll
;     for (int b = 0; b < 2; ++b)
; #pragma unroll
;       for (int m = 0; m < 4; ++m)
; #pragma unroll
;         for (int n = 0; n < 2; ++n) acc[a][b][m][n] = f32x4{0.f, 0.f, 0.f, 0.f};
;   const int abase = lds_byte(wr * 64 + fr, fq * 8), bbase = lds_byte(wc * 32 + fr, fq * 8);
;   bf16x8 At[4][2], B0[2][2], B1[2][2];
;   const unsigned lds0 = (unsigned)(size_t)(__attribute__((address_space(3))) char*)shm + (unsigned)wvoff;
;     ...
;   const int nt = K / BK;
;   WAIT_V(0);
;   if (wr == 1) BAR;
;   BAR;
;   BAR;
;     ...
;     LDB8(B0, 0, 0); SCHED; LDA8(0, 0); STG_A(1, 1, t + 1);
;     WAIT_L(8); BAR; WAIT_L(0); MMA8(0, 0, B0); BAR; SCHED;
;     LDB8(B1, 0, 1); STG_B(0, 0, t + 2);
;     BAR; WAIT_L(0); MMA8(0, 1, B1); BAR;
;     LDA8(0, 1); STG_A(0, 0, t + 2);
;     BAR; WAIT_L(0); MMA8(1, 0, B0); BAR; SCHED;
;     STG_B(0, 1, t + 2);
;     WAIT_V(6); BAR; MMA8(1, 1, B1); BAR;
.LBB0_650:
	s_or_b64 exec, exec, s[0:1]
	v_bfe_i32 v6, v0, 27, 1
	v_lshlrev_b32_e32 v4, 4, v0
	v_lshrrev_b32_e32 v6, 22, v6
	v_add_u32_e32 v6, v4, v6
	v_and_b32_e32 v6, 0xfffffc00, v6
	v_ashrrev_i32_e32 v5, 31, v0
	v_sub_u32_e32 v6, v4, v6
	v_lshrrev_b32_e32 v5, 26, v5
	v_lshrrev_b32_e32 v7, 4, v6
	v_add_u32_e32 v5, v0, v5
	v_bitop3_b32 v7, v7, v6, 32 bitop3:0x6c
	v_ashrrev_i32_e32 v6, 31, v6
	v_ashrrev_i32_e32 v5, 6, v5
	v_lshrrev_b32_e32 v6, 26, v6
	v_lshlrev_b32_e32 v8, 3, v5
	v_add_u32_e32 v6, v7, v6
	v_and_b32_e32 v8, 0xfffff0, v8
	v_ashrrev_i32_e32 v6, 6, v6
	v_add_u32_e32 v8, v6, v8
	v_mul_i32_i24_e32 v6, 64, v6
	v_add_u32_e32 v4, 0x2000, v4
	v_sub_u32_e32 v6, v7, v6
	v_ashrrev_i32_e32 v7, 31, v4
	v_lshrrev_b32_e32 v7, 22, v7
	v_add_u32_e32 v7, v4, v7
	v_ashrrev_i32_e32 v7, 10, v7
	v_mul_i32_i24_e32 v9, 0x400, v7
	v_sub_u32_e32 v4, v4, v9
	v_lshrrev_b32_e32 v9, 4, v4
	s_ashr_i32 s5, s4, 31
	s_mul_i32 s1, s4, 0x1600
	v_bitop3_b32 v4, v9, v4, 32 bitop3:0x6c
	s_mul_hi_i32 s0, s4, 0x1600
	s_add_u32 s3, s90, s1
	v_ashrrev_i32_e32 v10, 31, v4
	s_addc_u32 s8, s91, s0
	s_mul_i32 s0, s10, 0x160000
	v_lshrrev_b32_e32 v10, 26, v10
	s_ashr_i32 s1, s0, 31
	v_lshlrev_b32_e32 v9, 3, v7
	v_add_u32_e32 v10, v4, v10
	v_lshl_add_u64 v[130:131], v[146:147], 0, s[0:1]
	v_and_b32_e32 v9, 0xfffff0, v9
	v_lshrrev_b32_e32 v11, 6, v10
	v_and_b32_e32 v10, 0xc0, v10
	s_movk_i32 s0, 0xb00
	v_lshlrev_b32_e32 v5, 5, v5
	v_add_u32_e32 v9, v11, v9
	v_sub_u32_e32 v4, v4, v10
	v_mul_lo_u32 v8, v8, s0
	v_lshlrev_b32_e32 v7, 5, v7
	v_ashrrev_i16_sdwa v4, v178, sext(v4) dst_sel:DWORD dst_unused:UNUSED_PAD src0_sel:DWORD src1_sel:BYTE_0
	v_and_or_b32 v5, v5, 32, v8
	v_mul_lo_u32 v8, v9, s0
	v_ashrrev_i16_sdwa v6, v178, sext(v6) dst_sel:DWORD dst_unused:UNUSED_PAD src0_sel:DWORD src1_sel:BYTE_0
	v_bfe_i32 v4, v4, 0, 16
	v_and_or_b32 v7, v7, 32, v8
	v_bfe_i32 v6, v6, 0, 16
	s_add_u32 s9, s3, 0xb0000
	v_and_b32_e32 v8, 15, v0
	v_add_lshl_u32 v135, v7, v4, 1
	v_lshlrev_b32_e32 v7, 2, v0
	s_addc_u32 s11, s8, 0
	v_add_lshl_u32 v136, v5, v6, 1
	s_lshl_b32 s12, s12, 10
	s_mov_b64 s[0:1], 0xb0000
	v_and_b32_e32 v4, 48, v0
	v_lshlrev_b32_e32 v5, 6, v8
	v_and_b32_e32 v7, 32, v7
	v_lshl_add_u64 v[132:133], v[130:131], 0, s[0:1]
	v_or_b32_e32 v6, v5, v4
	v_lshlrev_b32_e32 v3, 13, v3
	v_bitop3_b32 v4, v5, v7, v4 bitop3:0x36
	v_lshlrev_b32_e32 v2, 12, v2
	s_movk_i32 s0, 0x3000
	s_add_i32 s13, s12, 0
	v_bitop3_b32 v3, v6, v3, v7 bitop3:0xde
	v_and_or_b32 v137, v2, s0, v4
	s_add_u32 s14, s3, 0xb0100
	v_mov_b32_e32 v2, 0
	s_addc_u32 s15, s8, 0
	s_mov_b32 s16, -2
	s_mov_b64 s[0:1], 0
	v_add_u32_e32 v134, 0, v3
	s_waitcnt lgkmcnt(0)
	v_readfirstlane_b32 s22, v130
	v_readfirstlane_b32 s23, v131
	v_readfirstlane_b32 s18, v132
	v_readfirstlane_b32 s19, v133
	s_barrier
	s_barrier
	v_add_u32_e32 v164, 0x10000, v137
	ds_read_b128 v[138:141], v164
	ds_read_b128 v[142:145], v164 offset:1024
	ds_read_b128 v[156:159], v164 offset:2048
	ds_read_b128 v[164:167], v164 offset:3072
	ds_read_b128 v[168:171], v134
	ds_read_b128 v[172:175], v134 offset:1024
	ds_read_b128 v[180:183], v134 offset:2048
	ds_read_b128 v[184:187], v134 offset:3072
	ds_read_b128 v[188:191], v134 offset:4096
	ds_read_b128 v[192:195], v134 offset:5120
	ds_read_b128 v[196:199], v134 offset:6144
	ds_read_b128 v[200:203], v134 offset:7168
	v_add_u32_e32 v220, 0x14000, v137
	ds_read_b128 v[204:207], v220
	ds_read_b128 v[208:211], v220 offset:1024
	ds_read_b128 v[212:215], v220 offset:2048
	ds_read_b128 v[220:223], v220 offset:3072
	s_add_u32 s20, s9, s0
	s_addc_u32 s21, s11, s1
	s_add_u32 s20, s20, 0x80
	s_addc_u32 s21, s21, 0
	s_add_i32 s17, s13, 0xc000
	s_mov_b32 m0, s17
	s_nop 0
	global_load_lds_dwordx4 v136, s[20:21]
	s_add_i32 s17, s13, 0xe000
	s_mov_b32 m0, s17
	s_nop 0
	global_load_lds_dwordx4 v135, s[20:21]
	s_waitcnt vmcnt(8) lgkmcnt(0)
	s_setprio 1
	s_barrier
	v_mfma_f32_16x16x32_bf16 v[126:129], v[168:171], v[138:141], 0
	v_mfma_f32_16x16x32_bf16 v[122:125], v[168:171], v[156:159], 0
	v_mfma_f32_16x16x32_bf16 v[114:117], v[180:183], v[156:159], 0
	v_mfma_f32_16x16x32_bf16 v[118:121], v[180:183], v[138:141], 0
	v_mfma_f32_16x16x32_bf16 v[110:113], v[188:191], v[138:141], 0
	v_mfma_f32_16x16x32_bf16 v[106:109], v[188:191], v[156:159], 0
	v_mfma_f32_16x16x32_bf16 v[98:101], v[196:199], v[156:159], 0
	v_mfma_f32_16x16x32_bf16 v[102:105], v[196:199], v[138:141], 0
	v_mfma_f32_16x16x32_bf16 v[126:129], v[172:175], v[142:145], v[126:129]
	v_mfma_f32_16x16x32_bf16 v[122:125], v[172:175], v[164:167], v[122:125]
	v_mfma_f32_16x16x32_bf16 v[114:117], v[184:187], v[164:167], v[114:117]
	v_mfma_f32_16x16x32_bf16 v[118:121], v[184:187], v[142:145], v[118:121]
	v_mfma_f32_16x16x32_bf16 v[110:113], v[192:195], v[142:145], v[110:113]
	v_mfma_f32_16x16x32_bf16 v[106:109], v[192:195], v[164:167], v[106:109]
	v_mfma_f32_16x16x32_bf16 v[98:101], v[200:203], v[164:167], v[98:101]
	v_mfma_f32_16x16x32_bf16 v[102:105], v[200:203], v[142:145], v[102:105]
	v_mfma_f32_16x16x32_bf16 v[94:97], v[168:171], v[204:207], 0
	v_mfma_f32_16x16x32_bf16 v[90:93], v[168:171], v[212:215], 0
	v_mfma_f32_16x16x32_bf16 v[82:85], v[180:183], v[212:215], 0
	v_mfma_f32_16x16x32_bf16 v[86:89], v[180:183], v[204:207], 0
	v_mfma_f32_16x16x32_bf16 v[78:81], v[188:191], v[204:207], 0
	v_mfma_f32_16x16x32_bf16 v[74:77], v[188:191], v[212:215], 0
	v_mfma_f32_16x16x32_bf16 v[66:69], v[196:199], v[212:215], 0
	v_mfma_f32_16x16x32_bf16 v[70:73], v[196:199], v[204:207], 0
	v_mfma_f32_16x16x32_bf16 v[94:97], v[172:175], v[208:211], v[94:97]
	v_mfma_f32_16x16x32_bf16 v[90:93], v[172:175], v[220:223], v[90:93]
	v_mfma_f32_16x16x32_bf16 v[82:85], v[184:187], v[220:223], v[82:85]
	v_mfma_f32_16x16x32_bf16 v[86:89], v[184:187], v[208:211], v[86:89]
	v_mfma_f32_16x16x32_bf16 v[78:81], v[192:195], v[208:211], v[78:81]
	v_mfma_f32_16x16x32_bf16 v[74:77], v[192:195], v[220:223], v[74:77]
	v_mfma_f32_16x16x32_bf16 v[66:69], v[200:203], v[220:223], v[66:69]
	v_mfma_f32_16x16x32_bf16 v[70:73], v[200:203], v[208:211], v[70:73]
	s_barrier
; #define WAIT_V(n) asm volatile("s_waitcnt vmcnt(" #n ")" ::: "memory")
; #define WAIT_L(n) asm volatile("s_waitcnt lgkmcnt(" #n ")" ::: "memory")
; #define BAR __builtin_amdgcn_s_barrier()
; #define SCHED __builtin_amdgcn_sched_barrier(0)
; #define STG_A(b, h, kt) stage_half_s(lds0 + ((b) * 2 + (h)) * HT_B, ((h) ? A1 : Ap) + (kt) * BK, off0, off1)
; #define STG_B(b, h, kt) stage_half_s(lds0 + (4 + (b) * 2 + (h)) * HT_B, ((h) ? B1p : Bp) + (kt) * BK, off0, off1)
; #define STG_A(b, h, kt) stage_half_s(lds0 + ((b) * 2 + (h)) * HT_B, ((h) ? A1 : Ap) + (kt) * BK, off0, off1)
; #define STG_B(b, h, kt) stage_half_s(lds0 + (4 + (b) * 2 + (h)) * HT_B, ((h) ? B1p : Bp) + (kt) * BK, off0, off1)
; #define LDA8(b, h) _Pragma("unroll") for (int m = 0; m < 4; ++m) _Pragma("unroll") for (int k = 0; k < 2; ++k) \
;     At[m][k] = *(const bf16x8*)(SA_(shm, b, h) + abase + (m * 2 + k) * 1024)
; #define LDB8(dst, b, h) _Pragma("unroll") for (int n = 0; n < 2; ++n) _Pragma("unroll") for (int k = 0; k < 2; ++k) \
;     dst[n][k] = *(const bf16x8*)(SB_(shm, b, h) + bbase + (n * 2 + k) * 1024)
; template <bool HS>
; __device__ __forceinline__ void gemm_tile8(const u16* __restrict__ Ap, const u16* __restrict__ Bp, int K,
;                                            f32x4 (&acc)[2][2][4][2], char* shm, const int tid, const float* hsr = nullptr) {
;     ...
;     LDB8(B0, 0, 0); SCHED; LDA8(0, 0); STG_A(1, 1, t + 1);
;     WAIT_L(8); BAR; WAIT_L(0); MMA8(0, 0, B0); BAR; SCHED;
;     LDB8(B1, 0, 1); STG_B(0, 0, t + 2);
;     BAR; WAIT_L(0); MMA8(0, 1, B1); BAR;
;     LDA8(0, 1); STG_A(0, 0, t + 2);
;     BAR; WAIT_L(0); MMA8(1, 0, B0); BAR; SCHED;
;     STG_B(0, 1, t + 2);
;     WAIT_V(6); BAR; MMA8(1, 1, B1); BAR;
;     LDB8(B0, 1, 0); SCHED; LDA8(1, 0); STG_A(0, 1, t + 2);
;     WAIT_L(8); BAR; WAIT_L(0); MMA8(0, 0, B0); BAR; SCHED;
;     LDB8(B1, 1, 1); STG_B(1, 0, t + 3);
;     BAR; WAIT_L(0); MMA8(0, 1, B1); BAR;
;     LDA8(1, 1); STG_A(1, 0, t + 3);
;     BAR; WAIT_L(0); MMA8(1, 0, B0); BAR; SCHED;
;     STG_B(1, 1, t + 3);
;     WAIT_V(6); BAR; MMA8(1, 1, B1); BAR;
	s_setprio 0
	ds_read_b128 v[168:171], v134 offset:16384
	ds_read_b128 v[172:175], v134 offset:17408
	ds_read_b128 v[180:183], v134 offset:18432
	ds_read_b128 v[184:187], v134 offset:19456
	ds_read_b128 v[188:191], v134 offset:20480
	ds_read_b128 v[192:195], v134 offset:21504
	ds_read_b128 v[196:199], v134 offset:22528
	ds_read_b128 v[200:203], v134 offset:23552
	s_add_u32 s20, s22, s0
	s_addc_u32 s21, s23, s1
	s_add_u32 s20, s20, 0x100
	s_addc_u32 s21, s21, 0
	s_add_i32 s17, s13, 0x10000
	s_mov_b32 m0, s17
	s_nop 0
	global_load_lds_dwordx4 v136, s[20:21]
	s_add_i32 s17, s13, 0x12000
	s_mov_b32 m0, s17
	s_nop 0
	global_load_lds_dwordx4 v135, s[20:21]
	s_add_u32 s20, s3, s0
	s_addc_u32 s21, s8, s1
	s_add_u32 s20, s20, 0x100
	s_addc_u32 s21, s21, 0
	s_mov_b32 m0, s13
	s_nop 0
	global_load_lds_dwordx4 v136, s[20:21]
	s_add_i32 s17, s13, 0x2000
	s_mov_b32 m0, s17
	s_nop 0
	global_load_lds_dwordx4 v135, s[20:21]
	s_add_u32 s20, s18, s0
	s_addc_u32 s21, s19, s1
	s_add_u32 s20, s20, 0x100
	s_addc_u32 s21, s21, 0
	s_add_i32 s17, s13, 0x14000
	s_mov_b32 m0, s17
	s_nop 0
	global_load_lds_dwordx4 v136, s[20:21]
	s_add_i32 s17, s13, 0x16000
	s_mov_b32 m0, s17
	s_nop 0
	global_load_lds_dwordx4 v135, s[20:21]
	s_waitcnt vmcnt(8) lgkmcnt(0)
	s_setprio 1
	s_barrier
	v_mfma_f32_16x16x32_bf16 v[62:65], v[168:171], v[138:141], 0
	v_mfma_f32_16x16x32_bf16 v[58:61], v[168:171], v[156:159], 0
	v_mfma_f32_16x16x32_bf16 v[50:53], v[180:183], v[156:159], 0
	v_mfma_f32_16x16x32_bf16 v[54:57], v[180:183], v[138:141], 0
	v_mfma_f32_16x16x32_bf16 v[46:49], v[188:191], v[138:141], 0
	v_mfma_f32_16x16x32_bf16 v[42:45], v[188:191], v[156:159], 0
	v_mfma_f32_16x16x32_bf16 v[34:37], v[196:199], v[156:159], 0
	v_mfma_f32_16x16x32_bf16 v[38:41], v[196:199], v[138:141], 0
	v_mfma_f32_16x16x32_bf16 v[62:65], v[172:175], v[142:145], v[62:65]
	v_mfma_f32_16x16x32_bf16 v[58:61], v[172:175], v[164:167], v[58:61]
	v_mfma_f32_16x16x32_bf16 v[50:53], v[184:187], v[164:167], v[50:53]
	v_mfma_f32_16x16x32_bf16 v[54:57], v[184:187], v[142:145], v[54:57]
	v_mfma_f32_16x16x32_bf16 v[46:49], v[192:195], v[142:145], v[46:49]
	v_mfma_f32_16x16x32_bf16 v[42:45], v[192:195], v[164:167], v[42:45]
	v_mfma_f32_16x16x32_bf16 v[34:37], v[200:203], v[164:167], v[34:37]
	v_mfma_f32_16x16x32_bf16 v[38:41], v[200:203], v[142:145], v[38:41]
	v_mfma_f32_16x16x32_bf16 v[30:33], v[168:171], v[204:207], 0
	v_mfma_f32_16x16x32_bf16 v[26:29], v[168:171], v[212:215], 0
	v_mfma_f32_16x16x32_bf16 v[18:21], v[180:183], v[212:215], 0
	v_mfma_f32_16x16x32_bf16 v[22:25], v[180:183], v[204:207], 0
	v_mfma_f32_16x16x32_bf16 v[14:17], v[188:191], v[204:207], 0
	v_mfma_f32_16x16x32_bf16 v[10:13], v[188:191], v[212:215], 0
	v_mfma_f32_16x16x32_bf16 v[2:5], v[196:199], v[212:215], 0
	v_mfma_f32_16x16x32_bf16 v[6:9], v[196:199], v[204:207], 0
	v_mfma_f32_16x16x32_bf16 v[30:33], v[172:175], v[208:211], v[30:33]
	v_mfma_f32_16x16x32_bf16 v[26:29], v[172:175], v[220:223], v[26:29]
	v_mfma_f32_16x16x32_bf16 v[18:21], v[184:187], v[220:223], v[18:21]
	v_mfma_f32_16x16x32_bf16 v[22:25], v[184:187], v[208:211], v[22:25]
	v_mfma_f32_16x16x32_bf16 v[14:17], v[192:195], v[208:211], v[14:17]
	v_mfma_f32_16x16x32_bf16 v[10:13], v[192:195], v[220:223], v[10:13]
	v_mfma_f32_16x16x32_bf16 v[2:5], v[200:203], v[220:223], v[2:5]
	v_mfma_f32_16x16x32_bf16 v[6:9], v[200:203], v[208:211], v[6:9]
	s_barrier
	s_setprio 0
	v_add_u32_e32 v164, 0x18000, v137
	ds_read_b128 v[138:141], v164
	ds_read_b128 v[142:145], v164 offset:1024
	ds_read_b128 v[156:159], v164 offset:2048
	ds_read_b128 v[164:167], v164 offset:3072
	ds_read_b128 v[168:171], v134 offset:32768
	ds_read_b128 v[172:175], v134 offset:33792
	ds_read_b128 v[180:183], v134 offset:34816
	ds_read_b128 v[184:187], v134 offset:35840
	ds_read_b128 v[188:191], v134 offset:36864
	ds_read_b128 v[192:195], v134 offset:37888
	ds_read_b128 v[196:199], v134 offset:38912
	ds_read_b128 v[200:203], v134 offset:39936
	v_add_u32_e32 v220, 0x1c000, v137
	ds_read_b128 v[204:207], v220
	ds_read_b128 v[208:211], v220 offset:1024
	ds_read_b128 v[212:215], v220 offset:2048
	ds_read_b128 v[220:223], v220 offset:3072
	s_add_u32 s20, s9, s0
	s_addc_u32 s21, s11, s1
	s_add_u32 s20, s20, 0x100
	s_addc_u32 s21, s21, 0
	s_add_i32 s17, s13, 0x4000
	s_mov_b32 m0, s17
	s_nop 0
	global_load_lds_dwordx4 v136, s[20:21]
	s_add_i32 s17, s13, 0x6000
	s_mov_b32 m0, s17
	s_nop 0
	global_load_lds_dwordx4 v135, s[20:21]
	s_waitcnt vmcnt(8) lgkmcnt(0)
	s_setprio 1
	s_barrier
	v_mfma_f32_16x16x32_bf16 v[126:129], v[168:171], v[138:141], v[126:129]
	v_mfma_f32_16x16x32_bf16 v[122:125], v[168:171], v[156:159], v[122:125]
	v_mfma_f32_16x16x32_bf16 v[114:117], v[180:183], v[156:159], v[114:117]
	v_mfma_f32_16x16x32_bf16 v[118:121], v[180:183], v[138:141], v[118:121]
	v_mfma_f32_16x16x32_bf16 v[110:113], v[188:191], v[138:141], v[110:113]
	v_mfma_f32_16x16x32_bf16 v[106:109], v[188:191], v[156:159], v[106:109]
	v_mfma_f32_16x16x32_bf16 v[98:101], v[196:199], v[156:159], v[98:101]
	v_mfma_f32_16x16x32_bf16 v[102:105], v[196:199], v[138:141], v[102:105]
	v_mfma_f32_16x16x32_bf16 v[126:129], v[172:175], v[142:145], v[126:129]
	v_mfma_f32_16x16x32_bf16 v[122:125], v[172:175], v[164:167], v[122:125]
	v_mfma_f32_16x16x32_bf16 v[114:117], v[184:187], v[164:167], v[114:117]
	v_mfma_f32_16x16x32_bf16 v[118:121], v[184:187], v[142:145], v[118:121]
	v_mfma_f32_16x16x32_bf16 v[110:113], v[192:195], v[142:145], v[110:113]
	v_mfma_f32_16x16x32_bf16 v[106:109], v[192:195], v[164:167], v[106:109]
	v_mfma_f32_16x16x32_bf16 v[98:101], v[200:203], v[164:167], v[98:101]
	v_mfma_f32_16x16x32_bf16 v[102:105], v[200:203], v[142:145], v[102:105]
	v_mfma_f32_16x16x32_bf16 v[94:97], v[168:171], v[204:207], v[94:97]
	v_mfma_f32_16x16x32_bf16 v[90:93], v[168:171], v[212:215], v[90:93]
	v_mfma_f32_16x16x32_bf16 v[82:85], v[180:183], v[212:215], v[82:85]
	v_mfma_f32_16x16x32_bf16 v[86:89], v[180:183], v[204:207], v[86:89]
	v_mfma_f32_16x16x32_bf16 v[78:81], v[188:191], v[204:207], v[78:81]
	v_mfma_f32_16x16x32_bf16 v[74:77], v[188:191], v[212:215], v[74:77]
	v_mfma_f32_16x16x32_bf16 v[66:69], v[196:199], v[212:215], v[66:69]
	v_mfma_f32_16x16x32_bf16 v[70:73], v[196:199], v[204:207], v[70:73]
	v_mfma_f32_16x16x32_bf16 v[94:97], v[172:175], v[208:211], v[94:97]
	v_mfma_f32_16x16x32_bf16 v[90:93], v[172:175], v[220:223], v[90:93]
	v_mfma_f32_16x16x32_bf16 v[82:85], v[184:187], v[220:223], v[82:85]
	v_mfma_f32_16x16x32_bf16 v[86:89], v[184:187], v[208:211], v[86:89]
	v_mfma_f32_16x16x32_bf16 v[78:81], v[192:195], v[208:211], v[78:81]
	v_mfma_f32_16x16x32_bf16 v[74:77], v[192:195], v[220:223], v[74:77]
	v_mfma_f32_16x16x32_bf16 v[66:69], v[200:203], v[220:223], v[66:69]
	v_mfma_f32_16x16x32_bf16 v[70:73], v[200:203], v[208:211], v[70:73]
	s_barrier
; #define WAIT_V(n) asm volatile("s_waitcnt vmcnt(" #n ")" ::: "memory")
; #define WAIT_L(n) asm volatile("s_waitcnt lgkmcnt(" #n ")" ::: "memory")
; #define BAR __builtin_amdgcn_s_barrier()
; #define SCHED __builtin_amdgcn_sched_barrier(0)
; #define STG_A(b, h, kt) stage_half_s(lds0 + ((b) * 2 + (h)) * HT_B, ((h) ? A1 : Ap) + (kt) * BK, off0, off1)
; #define STG_B(b, h, kt) stage_half_s(lds0 + (4 + (b) * 2 + (h)) * HT_B, ((h) ? B1p : Bp) + (kt) * BK, off0, off1)
; #define STG_A(b, h, kt) stage_half_s(lds0 + ((b) * 2 + (h)) * HT_B, ((h) ? A1 : Ap) + (kt) * BK, off0, off1)
; #define STG_B(b, h, kt) stage_half_s(lds0 + (4 + (b) * 2 + (h)) * HT_B, ((h) ? B1p : Bp) + (kt) * BK, off0, off1)
; #define LDA8(b, h) _Pragma("unroll") for (int m = 0; m < 4; ++m) _Pragma("unroll") for (int k = 0; k < 2; ++k) \
;     At[m][k] = *(const bf16x8*)(SA_(shm, b, h) + abase + (m * 2 + k) * 1024)
; #define LDB8(dst, b, h) _Pragma("unroll") for (int n = 0; n < 2; ++n) _Pragma("unroll") for (int k = 0; k < 2; ++k) \
;     dst[n][k] = *(const bf16x8*)(SB_(shm, b, h) + bbase + (n * 2 + k) * 1024)
; template <bool HS>
; __device__ __forceinline__ void gemm_tile8(const u16* __restrict__ Ap, const u16* __restrict__ Bp, int K,
;                                            f32x4 (&acc)[2][2][4][2], char* shm, const int tid, const float* hsr = nullptr) {
;     ...
;     LDB8(B0, 0, 0); SCHED; LDA8(0, 0); STG_A(1, 1, t + 1);
;     WAIT_L(8); BAR; WAIT_L(0); MMA8(0, 0, B0); BAR; SCHED;
;     LDB8(B1, 0, 1); STG_B(0, 0, t + 2);
;     BAR; WAIT_L(0); MMA8(0, 1, B1); BAR;
;     LDA8(0, 1); STG_A(0, 0, t + 2);
;     BAR; WAIT_L(0); MMA8(1, 0, B0); BAR; SCHED;
;     STG_B(0, 1, t + 2);
;     WAIT_V(6); BAR; MMA8(1, 1, B1); BAR;
;     LDB8(B0, 1, 0); SCHED; LDA8(1, 0); STG_A(0, 1, t + 2);
;     WAIT_L(8); BAR; WAIT_L(0); MMA8(0, 0, B0); BAR; SCHED;
;     LDB8(B1, 1, 1); STG_B(1, 0, t + 3);
;     BAR; WAIT_L(0); MMA8(0, 1, B1); BAR;
;     LDA8(1, 1); STG_A(1, 0, t + 3);
;     BAR; WAIT_L(0); MMA8(1, 0, B0); BAR; SCHED;
;     STG_B(1, 1, t + 3);
;     WAIT_V(6); BAR; MMA8(1, 1, B1); BAR;
	s_setprio 0
	ds_read_b128 v[168:171], v134 offset:49152
	ds_read_b128 v[172:175], v134 offset:50176
	ds_read_b128 v[180:183], v134 offset:51200
	ds_read_b128 v[184:187], v134 offset:52224
	ds_read_b128 v[188:191], v134 offset:53248
	ds_read_b128 v[192:195], v134 offset:54272
	ds_read_b128 v[196:199], v134 offset:55296
	ds_read_b128 v[200:203], v134 offset:56320
	s_add_u32 s20, s22, s0
	s_addc_u32 s21, s23, s1
	s_add_u32 s20, s20, 0x180
	s_addc_u32 s21, s21, 0
	s_add_i32 s17, s13, 0x18000
	s_mov_b32 m0, s17
	s_nop 0
	global_load_lds_dwordx4 v136, s[20:21]
	s_add_i32 s17, s13, 0x1a000
	s_mov_b32 m0, s17
	s_nop 0
	global_load_lds_dwordx4 v135, s[20:21]
	s_add_u32 s20, s3, s0
	s_addc_u32 s21, s8, s1
	s_add_u32 s20, s20, 0x180
	s_addc_u32 s21, s21, 0
	s_add_i32 s17, s13, 0x8000
	s_mov_b32 m0, s17
	s_nop 0
	global_load_lds_dwordx4 v136, s[20:21]
	s_add_i32 s17, s13, 0xa000
	s_mov_b32 m0, s17
	s_nop 0
	global_load_lds_dwordx4 v135, s[20:21]
	s_add_u32 s20, s18, s0
	s_addc_u32 s21, s19, s1
	s_add_u32 s20, s20, 0x180
	s_addc_u32 s21, s21, 0
	s_add_i32 s17, s13, 0x1c000
	s_mov_b32 m0, s17
	s_nop 0
	global_load_lds_dwordx4 v136, s[20:21]
	s_add_i32 s17, s13, 0x1e000
	s_mov_b32 m0, s17
	s_nop 0
	global_load_lds_dwordx4 v135, s[20:21]
	s_waitcnt vmcnt(8) lgkmcnt(0)
	s_setprio 1
	s_barrier
	v_mfma_f32_16x16x32_bf16 v[62:65], v[168:171], v[138:141], v[62:65]
	v_mfma_f32_16x16x32_bf16 v[58:61], v[168:171], v[156:159], v[58:61]
	v_mfma_f32_16x16x32_bf16 v[50:53], v[180:183], v[156:159], v[50:53]
	v_mfma_f32_16x16x32_bf16 v[54:57], v[180:183], v[138:141], v[54:57]
	v_mfma_f32_16x16x32_bf16 v[46:49], v[188:191], v[138:141], v[46:49]
	v_mfma_f32_16x16x32_bf16 v[42:45], v[188:191], v[156:159], v[42:45]
	v_mfma_f32_16x16x32_bf16 v[34:37], v[196:199], v[156:159], v[34:37]
	v_mfma_f32_16x16x32_bf16 v[38:41], v[196:199], v[138:141], v[38:41]
	v_mfma_f32_16x16x32_bf16 v[62:65], v[172:175], v[142:145], v[62:65]
	v_mfma_f32_16x16x32_bf16 v[58:61], v[172:175], v[164:167], v[58:61]
	v_mfma_f32_16x16x32_bf16 v[50:53], v[184:187], v[164:167], v[50:53]
	v_mfma_f32_16x16x32_bf16 v[54:57], v[184:187], v[142:145], v[54:57]
	v_mfma_f32_16x16x32_bf16 v[46:49], v[192:195], v[142:145], v[46:49]
	v_mfma_f32_16x16x32_bf16 v[42:45], v[192:195], v[164:167], v[42:45]
	v_mfma_f32_16x16x32_bf16 v[34:37], v[200:203], v[164:167], v[34:37]
	v_mfma_f32_16x16x32_bf16 v[38:41], v[200:203], v[142:145], v[38:41]
	v_mfma_f32_16x16x32_bf16 v[30:33], v[168:171], v[204:207], v[30:33]
	v_mfma_f32_16x16x32_bf16 v[26:29], v[168:171], v[212:215], v[26:29]
	v_mfma_f32_16x16x32_bf16 v[18:21], v[180:183], v[212:215], v[18:21]
	v_mfma_f32_16x16x32_bf16 v[22:25], v[180:183], v[204:207], v[22:25]
	v_mfma_f32_16x16x32_bf16 v[14:17], v[188:191], v[204:207], v[14:17]
	v_mfma_f32_16x16x32_bf16 v[10:13], v[188:191], v[212:215], v[10:13]
	v_mfma_f32_16x16x32_bf16 v[2:5], v[196:199], v[212:215], v[2:5]
	v_mfma_f32_16x16x32_bf16 v[6:9], v[196:199], v[204:207], v[6:9]
	v_mfma_f32_16x16x32_bf16 v[30:33], v[172:175], v[208:211], v[30:33]
	v_mfma_f32_16x16x32_bf16 v[26:29], v[172:175], v[220:223], v[26:29]
	v_mfma_f32_16x16x32_bf16 v[18:21], v[184:187], v[220:223], v[18:21]
	v_mfma_f32_16x16x32_bf16 v[22:25], v[184:187], v[208:211], v[22:25]
	v_mfma_f32_16x16x32_bf16 v[14:17], v[192:195], v[208:211], v[14:17]
	v_mfma_f32_16x16x32_bf16 v[10:13], v[192:195], v[220:223], v[10:13]
	v_mfma_f32_16x16x32_bf16 v[2:5], v[200:203], v[220:223], v[2:5]
	v_mfma_f32_16x16x32_bf16 v[6:9], v[200:203], v[208:211], v[6:9]
	s_barrier
	s_setprio 0
	s_add_i32 s16, s16, 2
	s_add_u32 s0, s0, 0x100
	s_addc_u32 s1, s1, 0
	s_cmp_lt_u32 s16, 40
	s_cbranch_scc0 .Lk_ffn_out_exit
.Lk_ffn_out:
	v_add_u32_e32 v164, 0x10000, v137
	ds_read_b128 v[138:141], v164
	ds_read_b128 v[142:145], v164 offset:1024
	ds_read_b128 v[156:159], v164 offset:2048
	ds_read_b128 v[164:167], v164 offset:3072
	ds_read_b128 v[168:171], v134
	ds_read_b128 v[172:175], v134 offset:1024
	ds_read_b128 v[180:183], v134 offset:2048
	ds_read_b128 v[184:187], v134 offset:3072
	ds_read_b128 v[188:191], v134 offset:4096
	ds_read_b128 v[192:195], v134 offset:5120
	ds_read_b128 v[196:199], v134 offset:6144
	ds_read_b128 v[200:203], v134 offset:7168
	v_add_u32_e32 v220, 0x14000, v137
	ds_read_b128 v[204:207], v220
	ds_read_b128 v[208:211], v220 offset:1024
	ds_read_b128 v[212:215], v220 offset:2048
	ds_read_b128 v[220:223], v220 offset:3072
	s_add_u32 s20, s9, s0
	s_addc_u32 s21, s11, s1
	s_add_u32 s20, s20, 0x80
	s_addc_u32 s21, s21, 0
	s_add_i32 s17, s13, 0xc000
	s_mov_b32 m0, s17
	s_nop 0
	global_load_lds_dwordx4 v136, s[20:21]
	s_add_i32 s17, s13, 0xe000
	s_mov_b32 m0, s17
	s_nop 0
	global_load_lds_dwordx4 v135, s[20:21]
	s_waitcnt vmcnt(8) lgkmcnt(0)
	s_setprio 1
	s_barrier
; #define WAIT_V(n) asm volatile("s_waitcnt vmcnt(" #n ")" ::: "memory")
; #define WAIT_L(n) asm volatile("s_waitcnt lgkmcnt(" #n ")" ::: "memory")
; #define BAR __builtin_amdgcn_s_barrier()
; #define SCHED __builtin_amdgcn_sched_barrier(0)
; #define STG_A(b, h, kt) stage_half_s(lds0 + ((b) * 2 + (h)) * HT_B, ((h) ? A1 : Ap) + (kt) * BK, off0, off1)
; #define STG_B(b, h, kt) stage_half_s(lds0 + (4 + (b) * 2 + (h)) * HT_B, ((h) ? B1p : Bp) + (kt) * BK, off0, off1)
; #define STG_A(b, h, kt) stage_half_s(lds0 + ((b) * 2 + (h)) * HT_B, ((h) ? A1 : Ap) + (kt) * BK, off0, off1)
; #define STG_B(b, h, kt) stage_half_s(lds0 + (4 + (b) * 2 + (h)) * HT_B, ((h) ? B1p : Bp) + (kt) * BK, off0, off1)
; #define LDA8(b, h) _Pragma("unroll") for (int m = 0; m < 4; ++m) _Pragma("unroll") for (int k = 0; k < 2; ++k) \
;     At[m][k] = *(const bf16x8*)(SA_(shm, b, h) + abase + (m * 2 + k) * 1024)
; #define LDB8(dst, b, h) _Pragma("unroll") for (int n = 0; n < 2; ++n) _Pragma("unroll") for (int k = 0; k < 2; ++k) \
;     dst[n][k] = *(const bf16x8*)(SB_(shm, b, h) + bbase + (n * 2 + k) * 1024)
; template <bool HS>
; __device__ __forceinline__ void gemm_tile8(const u16* __restrict__ Ap, const u16* __restrict__ Bp, int K,
;                                            f32x4 (&acc)[2][2][4][2], char* shm, const int tid, const float* hsr = nullptr) {
;     ...
;     LDB8(B0, 0, 0); SCHED; LDA8(0, 0); STG_A(1, 1, t + 1);
;     WAIT_L(8); BAR; WAIT_L(0); MMA8(0, 0, B0); BAR; SCHED;
;     LDB8(B1, 0, 1); STG_B(0, 0, t + 2);
;     BAR; WAIT_L(0); MMA8(0, 1, B1); BAR;
;     LDA8(0, 1); STG_A(0, 0, t + 2);
;     BAR; WAIT_L(0); MMA8(1, 0, B0); BAR; SCHED;
;     STG_B(0, 1, t + 2);
;     WAIT_V(6); BAR; MMA8(1, 1, B1); BAR;
;     LDB8(B0, 1, 0); SCHED; LDA8(1, 0); STG_A(0, 1, t + 2);
;     WAIT_L(8); BAR; WAIT_L(0); MMA8(0, 0, B0); BAR; SCHED;
;     LDB8(B1, 1, 1); STG_B(1, 0, t + 3);
;     BAR; WAIT_L(0); MMA8(0, 1, B1); BAR;
;     LDA8(1, 1); STG_A(1, 0, t + 3);
;     BAR; WAIT_L(0); MMA8(1, 0, B0); BAR; SCHED;
;     STG_B(1, 1, t + 3);
;     WAIT_V(6); BAR; MMA8(1, 1, B1); BAR;
	v_mfma_f32_16x16x32_bf16 v[126:129], v[168:171], v[138:141], v[126:129]
	v_mfma_f32_16x16x32_bf16 v[122:125], v[168:171], v[156:159], v[122:125]
	v_mfma_f32_16x16x32_bf16 v[114:117], v[180:183], v[156:159], v[114:117]
	v_mfma_f32_16x16x32_bf16 v[118:121], v[180:183], v[138:141], v[118:121]
	v_mfma_f32_16x16x32_bf16 v[110:113], v[188:191], v[138:141], v[110:113]
	v_mfma_f32_16x16x32_bf16 v[106:109], v[188:191], v[156:159], v[106:109]
	v_mfma_f32_16x16x32_bf16 v[98:101], v[196:199], v[156:159], v[98:101]
	v_mfma_f32_16x16x32_bf16 v[102:105], v[196:199], v[138:141], v[102:105]
	v_mfma_f32_16x16x32_bf16 v[126:129], v[172:175], v[142:145], v[126:129]
	v_mfma_f32_16x16x32_bf16 v[122:125], v[172:175], v[164:167], v[122:125]
	v_mfma_f32_16x16x32_bf16 v[114:117], v[184:187], v[164:167], v[114:117]
	v_mfma_f32_16x16x32_bf16 v[118:121], v[184:187], v[142:145], v[118:121]
	v_mfma_f32_16x16x32_bf16 v[110:113], v[192:195], v[142:145], v[110:113]
	v_mfma_f32_16x16x32_bf16 v[106:109], v[192:195], v[164:167], v[106:109]
	v_mfma_f32_16x16x32_bf16 v[98:101], v[200:203], v[164:167], v[98:101]
	v_mfma_f32_16x16x32_bf16 v[102:105], v[200:203], v[142:145], v[102:105]
	v_mfma_f32_16x16x32_bf16 v[94:97], v[168:171], v[204:207], v[94:97]
	v_mfma_f32_16x16x32_bf16 v[90:93], v[168:171], v[212:215], v[90:93]
	v_mfma_f32_16x16x32_bf16 v[82:85], v[180:183], v[212:215], v[82:85]
	v_mfma_f32_16x16x32_bf16 v[86:89], v[180:183], v[204:207], v[86:89]
	v_mfma_f32_16x16x32_bf16 v[78:81], v[188:191], v[204:207], v[78:81]
	v_mfma_f32_16x16x32_bf16 v[74:77], v[188:191], v[212:215], v[74:77]
	v_mfma_f32_16x16x32_bf16 v[66:69], v[196:199], v[212:215], v[66:69]
	v_mfma_f32_16x16x32_bf16 v[70:73], v[196:199], v[204:207], v[70:73]
	v_mfma_f32_16x16x32_bf16 v[94:97], v[172:175], v[208:211], v[94:97]
	v_mfma_f32_16x16x32_bf16 v[90:93], v[172:175], v[220:223], v[90:93]
	v_mfma_f32_16x16x32_bf16 v[82:85], v[184:187], v[220:223], v[82:85]
	v_mfma_f32_16x16x32_bf16 v[86:89], v[184:187], v[208:211], v[86:89]
	v_mfma_f32_16x16x32_bf16 v[78:81], v[192:195], v[208:211], v[78:81]
	v_mfma_f32_16x16x32_bf16 v[74:77], v[192:195], v[220:223], v[74:77]
	v_mfma_f32_16x16x32_bf16 v[66:69], v[200:203], v[220:223], v[66:69]
	v_mfma_f32_16x16x32_bf16 v[70:73], v[200:203], v[208:211], v[70:73]
	s_barrier
	s_setprio 0
	ds_read_b128 v[168:171], v134 offset:16384
	ds_read_b128 v[172:175], v134 offset:17408
	ds_read_b128 v[180:183], v134 offset:18432
	ds_read_b128 v[184:187], v134 offset:19456
	ds_read_b128 v[188:191], v134 offset:20480
	ds_read_b128 v[192:195], v134 offset:21504
	ds_read_b128 v[196:199], v134 offset:22528
	ds_read_b128 v[200:203], v134 offset:23552
	s_add_u32 s20, s22, s0
	s_addc_u32 s21, s23, s1
	s_add_u32 s20, s20, 0x100
	s_addc_u32 s21, s21, 0
	s_add_i32 s17, s13, 0x10000
	s_mov_b32 m0, s17
	s_nop 0
	global_load_lds_dwordx4 v136, s[20:21]
	s_add_i32 s17, s13, 0x12000
	s_mov_b32 m0, s17
	s_nop 0
	global_load_lds_dwordx4 v135, s[20:21]
	s_add_u32 s20, s3, s0
	s_addc_u32 s21, s8, s1
	s_add_u32 s20, s20, 0x100
	s_addc_u32 s21, s21, 0
	s_mov_b32 m0, s13
	s_nop 0
	global_load_lds_dwordx4 v136, s[20:21]
	s_add_i32 s17, s13, 0x2000
	s_mov_b32 m0, s17
	s_nop 0
	global_load_lds_dwordx4 v135, s[20:21]
	s_add_u32 s20, s18, s0
	s_addc_u32 s21, s19, s1
	s_add_u32 s20, s20, 0x100
	s_addc_u32 s21, s21, 0
	s_add_i32 s17, s13, 0x14000
	s_mov_b32 m0, s17
	s_nop 0
	global_load_lds_dwordx4 v136, s[20:21]
	s_add_i32 s17, s13, 0x16000
	s_mov_b32 m0, s17
	s_nop 0
	global_load_lds_dwordx4 v135, s[20:21]
	s_waitcnt vmcnt(8) lgkmcnt(0)
	s_setprio 1
	s_barrier
	v_mfma_f32_16x16x32_bf16 v[62:65], v[168:171], v[138:141], v[62:65]
	v_mfma_f32_16x16x32_bf16 v[58:61], v[168:171], v[156:159], v[58:61]
	v_mfma_f32_16x16x32_bf16 v[50:53], v[180:183], v[156:159], v[50:53]
	v_mfma_f32_16x16x32_bf16 v[54:57], v[180:183], v[138:141], v[54:57]
	v_mfma_f32_16x16x32_bf16 v[46:49], v[188:191], v[138:141], v[46:49]
	v_mfma_f32_16x16x32_bf16 v[42:45], v[188:191], v[156:159], v[42:45]
	v_mfma_f32_16x16x32_bf16 v[34:37], v[196:199], v[156:159], v[34:37]
	v_mfma_f32_16x16x32_bf16 v[38:41], v[196:199], v[138:141], v[38:41]
	v_mfma_f32_16x16x32_bf16 v[62:65], v[172:175], v[142:145], v[62:65]
	v_mfma_f32_16x16x32_bf16 v[58:61], v[172:175], v[164:167], v[58:61]
	v_mfma_f32_16x16x32_bf16 v[50:53], v[184:187], v[164:167], v[50:53]
	v_mfma_f32_16x16x32_bf16 v[54:57], v[184:187], v[142:145], v[54:57]
	v_mfma_f32_16x16x32_bf16 v[46:49], v[192:195], v[142:145], v[46:49]
	v_mfma_f32_16x16x32_bf16 v[42:45], v[192:195], v[164:167], v[42:45]
	v_mfma_f32_16x16x32_bf16 v[34:37], v[200:203], v[164:167], v[34:37]
	v_mfma_f32_16x16x32_bf16 v[38:41], v[200:203], v[142:145], v[38:41]
	v_mfma_f32_16x16x32_bf16 v[30:33], v[168:171], v[204:207], v[30:33]
	v_mfma_f32_16x16x32_bf16 v[26:29], v[168:171], v[212:215], v[26:29]
	v_mfma_f32_16x16x32_bf16 v[18:21], v[180:183], v[212:215], v[18:21]
	v_mfma_f32_16x16x32_bf16 v[22:25], v[180:183], v[204:207], v[22:25]
	v_mfma_f32_16x16x32_bf16 v[14:17], v[188:191], v[204:207], v[14:17]
	v_mfma_f32_16x16x32_bf16 v[10:13], v[188:191], v[212:215], v[10:13]
	v_mfma_f32_16x16x32_bf16 v[2:5], v[196:199], v[212:215], v[2:5]
	v_mfma_f32_16x16x32_bf16 v[6:9], v[196:199], v[204:207], v[6:9]
	v_mfma_f32_16x16x32_bf16 v[30:33], v[172:175], v[208:211], v[30:33]
	v_mfma_f32_16x16x32_bf16 v[26:29], v[172:175], v[220:223], v[26:29]
	v_mfma_f32_16x16x32_bf16 v[18:21], v[184:187], v[220:223], v[18:21]
	v_mfma_f32_16x16x32_bf16 v[22:25], v[184:187], v[208:211], v[22:25]
	v_mfma_f32_16x16x32_bf16 v[14:17], v[192:195], v[208:211], v[14:17]
	v_mfma_f32_16x16x32_bf16 v[10:13], v[192:195], v[220:223], v[10:13]
	v_mfma_f32_16x16x32_bf16 v[2:5], v[200:203], v[220:223], v[2:5]
	v_mfma_f32_16x16x32_bf16 v[6:9], v[200:203], v[208:211], v[6:9]
	s_barrier
; #define WAIT_V(n) asm volatile("s_waitcnt vmcnt(" #n ")" ::: "memory")
; #define WAIT_L(n) asm volatile("s_waitcnt lgkmcnt(" #n ")" ::: "memory")
; #define BAR __builtin_amdgcn_s_barrier()
; #define SCHED __builtin_amdgcn_sched_barrier(0)
; #define STG_A(b, h, kt) stage_half_s(lds0 + ((b) * 2 + (h)) * HT_B, ((h) ? A1 : Ap) + (kt) * BK, off0, off1)
; #define STG_B(b, h, kt) stage_half_s(lds0 + (4 + (b) * 2 + (h)) * HT_B, ((h) ? B1p : Bp) + (kt) * BK, off0, off1)
; #define STG_A(b, h, kt) stage_half_s(lds0 + ((b) * 2 + (h)) * HT_B, ((h) ? A1 : Ap) + (kt) * BK, off0, off1)
; #define STG_B(b, h, kt) stage_half_s(lds0 + (4 + (b) * 2 + (h)) * HT_B, ((h) ? B1p : Bp) + (kt) * BK, off0, off1)
; #define LDA8(b, h) _Pragma("unroll") for (int m = 0; m < 4; ++m) _Pragma("unroll") for (int k = 0; k < 2; ++k) \
;     At[m][k] = *(const bf16x8*)(SA_(shm, b, h) + abase + (m * 2 + k) * 1024)
; #define LDB8(dst, b, h) _Pragma("unroll") for (int n = 0; n < 2; ++n) _Pragma("unroll") for (int k = 0; k < 2; ++k) \
;     dst[n][k] = *(const bf16x8*)(SB_(shm, b, h) + bbase + (n * 2 + k) * 1024)
; template <bool HS>
; __device__ __forceinline__ void gemm_tile8(const u16* __restrict__ Ap, const u16* __restrict__ Bp, int K,
;                                            f32x4 (&acc)[2][2][4][2], char* shm, const int tid, const float* hsr = nullptr) {
;     ...
;     LDB8(B0, 0, 0); SCHED; LDA8(0, 0); STG_A(1, 1, t + 1);
;     WAIT_L(8); BAR; WAIT_L(0); MMA8(0, 0, B0); BAR; SCHED;
;     LDB8(B1, 0, 1); STG_B(0, 0, t + 2);
;     BAR; WAIT_L(0); MMA8(0, 1, B1); BAR;
;     LDA8(0, 1); STG_A(0, 0, t + 2);
;     BAR; WAIT_L(0); MMA8(1, 0, B0); BAR; SCHED;
;     STG_B(0, 1, t + 2);
;     WAIT_V(6); BAR; MMA8(1, 1, B1); BAR;
;     LDB8(B0, 1, 0); SCHED; LDA8(1, 0); STG_A(0, 1, t + 2);
;     WAIT_L(8); BAR; WAIT_L(0); MMA8(0, 0, B0); BAR; SCHED;
;     LDB8(B1, 1, 1); STG_B(1, 0, t + 3);
;     BAR; WAIT_L(0); MMA8(0, 1, B1); BAR;
;     LDA8(1, 1); STG_A(1, 0, t + 3);
;     BAR; WAIT_L(0); MMA8(1, 0, B0); BAR; SCHED;
;     STG_B(1, 1, t + 3);
;     WAIT_V(6); BAR; MMA8(1, 1, B1); BAR;
	s_setprio 0
	v_add_u32_e32 v164, 0x18000, v137
	ds_read_b128 v[138:141], v164
	ds_read_b128 v[142:145], v164 offset:1024
	ds_read_b128 v[156:159], v164 offset:2048
	ds_read_b128 v[164:167], v164 offset:3072
	ds_read_b128 v[168:171], v134 offset:32768
	ds_read_b128 v[172:175], v134 offset:33792
	ds_read_b128 v[180:183], v134 offset:34816
	ds_read_b128 v[184:187], v134 offset:35840
	ds_read_b128 v[188:191], v134 offset:36864
	ds_read_b128 v[192:195], v134 offset:37888
	ds_read_b128 v[196:199], v134 offset:38912
	ds_read_b128 v[200:203], v134 offset:39936
	v_add_u32_e32 v220, 0x1c000, v137
	ds_read_b128 v[204:207], v220
	ds_read_b128 v[208:211], v220 offset:1024
	ds_read_b128 v[212:215], v220 offset:2048
	ds_read_b128 v[220:223], v220 offset:3072
	s_add_u32 s20, s9, s0
	s_addc_u32 s21, s11, s1
	s_add_u32 s20, s20, 0x100
	s_addc_u32 s21, s21, 0
	s_add_i32 s17, s13, 0x4000
	s_mov_b32 m0, s17
	s_nop 0
	global_load_lds_dwordx4 v136, s[20:21]
	s_add_i32 s17, s13, 0x6000
	s_mov_b32 m0, s17
	s_nop 0
	global_load_lds_dwordx4 v135, s[20:21]
	s_waitcnt vmcnt(8) lgkmcnt(0)
	s_setprio 1
	s_barrier
	v_mfma_f32_16x16x32_bf16 v[126:129], v[168:171], v[138:141], v[126:129]
	v_mfma_f32_16x16x32_bf16 v[122:125], v[168:171], v[156:159], v[122:125]
	v_mfma_f32_16x16x32_bf16 v[114:117], v[180:183], v[156:159], v[114:117]
	v_mfma_f32_16x16x32_bf16 v[118:121], v[180:183], v[138:141], v[118:121]
	v_mfma_f32_16x16x32_bf16 v[110:113], v[188:191], v[138:141], v[110:113]
	v_mfma_f32_16x16x32_bf16 v[106:109], v[188:191], v[156:159], v[106:109]
	v_mfma_f32_16x16x32_bf16 v[98:101], v[196:199], v[156:159], v[98:101]
	v_mfma_f32_16x16x32_bf16 v[102:105], v[196:199], v[138:141], v[102:105]
	v_mfma_f32_16x16x32_bf16 v[126:129], v[172:175], v[142:145], v[126:129]
	v_mfma_f32_16x16x32_bf16 v[122:125], v[172:175], v[164:167], v[122:125]
	v_mfma_f32_16x16x32_bf16 v[114:117], v[184:187], v[164:167], v[114:117]
	v_mfma_f32_16x16x32_bf16 v[118:121], v[184:187], v[142:145], v[118:121]
	v_mfma_f32_16x16x32_bf16 v[110:113], v[192:195], v[142:145], v[110:113]
	v_mfma_f32_16x16x32_bf16 v[106:109], v[192:195], v[164:167], v[106:109]
	v_mfma_f32_16x16x32_bf16 v[98:101], v[200:203], v[164:167], v[98:101]
	v_mfma_f32_16x16x32_bf16 v[102:105], v[200:203], v[142:145], v[102:105]
	v_mfma_f32_16x16x32_bf16 v[94:97], v[168:171], v[204:207], v[94:97]
	v_mfma_f32_16x16x32_bf16 v[90:93], v[168:171], v[212:215], v[90:93]
	v_mfma_f32_16x16x32_bf16 v[82:85], v[180:183], v[212:215], v[82:85]
	v_mfma_f32_16x16x32_bf16 v[86:89], v[180:183], v[204:207], v[86:89]
	v_mfma_f32_16x16x32_bf16 v[78:81], v[188:191], v[204:207], v[78:81]
	v_mfma_f32_16x16x32_bf16 v[74:77], v[188:191], v[212:215], v[74:77]
	v_mfma_f32_16x16x32_bf16 v[66:69], v[196:199], v[212:215], v[66:69]
	v_mfma_f32_16x16x32_bf16 v[70:73], v[196:199], v[204:207], v[70:73]
	v_mfma_f32_16x16x32_bf16 v[94:97], v[172:175], v[208:211], v[94:97]
	v_mfma_f32_16x16x32_bf16 v[90:93], v[172:175], v[220:223], v[90:93]
	v_mfma_f32_16x16x32_bf16 v[82:85], v[184:187], v[220:223], v[82:85]
	v_mfma_f32_16x16x32_bf16 v[86:89], v[184:187], v[208:211], v[86:89]
	v_mfma_f32_16x16x32_bf16 v[78:81], v[192:195], v[208:211], v[78:81]
	v_mfma_f32_16x16x32_bf16 v[74:77], v[192:195], v[220:223], v[74:77]
	v_mfma_f32_16x16x32_bf16 v[66:69], v[200:203], v[220:223], v[66:69]
	v_mfma_f32_16x16x32_bf16 v[70:73], v[200:203], v[208:211], v[70:73]
	s_barrier
	s_setprio 0
	ds_read_b128 v[168:171], v134 offset:49152
	ds_read_b128 v[172:175], v134 offset:50176
	ds_read_b128 v[180:183], v134 offset:51200
	ds_read_b128 v[184:187], v134 offset:52224
	ds_read_b128 v[188:191], v134 offset:53248
	ds_read_b128 v[192:195], v134 offset:54272
	ds_read_b128 v[196:199], v134 offset:55296
	ds_read_b128 v[200:203], v134 offset:56320
	s_add_u32 s20, s22, s0
	s_addc_u32 s21, s23, s1
	s_add_u32 s20, s20, 0x180
	s_addc_u32 s21, s21, 0
	s_add_i32 s17, s13, 0x18000
	s_mov_b32 m0, s17
	s_nop 0
	global_load_lds_dwordx4 v136, s[20:21]
	s_add_i32 s17, s13, 0x1a000
	s_mov_b32 m0, s17
	s_nop 0
	global_load_lds_dwordx4 v135, s[20:21]
	s_add_u32 s20, s3, s0
	s_addc_u32 s21, s8, s1
	s_add_u32 s20, s20, 0x180
	s_addc_u32 s21, s21, 0
	s_add_i32 s17, s13, 0x8000
	s_mov_b32 m0, s17
	s_nop 0
	global_load_lds_dwordx4 v136, s[20:21]
	s_add_i32 s17, s13, 0xa000
	s_mov_b32 m0, s17
	s_nop 0
	global_load_lds_dwordx4 v135, s[20:21]
	s_add_u32 s20, s18, s0
	s_addc_u32 s21, s19, s1
	s_add_u32 s20, s20, 0x180
	s_addc_u32 s21, s21, 0
	s_add_i32 s17, s13, 0x1c000
	s_mov_b32 m0, s17
	s_nop 0
	global_load_lds_dwordx4 v136, s[20:21]
	s_add_i32 s17, s13, 0x1e000
	s_mov_b32 m0, s17
	s_nop 0
	global_load_lds_dwordx4 v135, s[20:21]
	s_waitcnt vmcnt(8) lgkmcnt(0)
	s_setprio 1
	s_barrier
	v_mfma_f32_16x16x32_bf16 v[62:65], v[168:171], v[138:141], v[62:65]
	v_mfma_f32_16x16x32_bf16 v[58:61], v[168:171], v[156:159], v[58:61]
	v_mfma_f32_16x16x32_bf16 v[50:53], v[180:183], v[156:159], v[50:53]
	v_mfma_f32_16x16x32_bf16 v[54:57], v[180:183], v[138:141], v[54:57]
	v_mfma_f32_16x16x32_bf16 v[46:49], v[188:191], v[138:141], v[46:49]
	v_mfma_f32_16x16x32_bf16 v[42:45], v[188:191], v[156:159], v[42:45]
	v_mfma_f32_16x16x32_bf16 v[34:37], v[196:199], v[156:159], v[34:37]
	v_mfma_f32_16x16x32_bf16 v[38:41], v[196:199], v[138:141], v[38:41]
	v_mfma_f32_16x16x32_bf16 v[62:65], v[172:175], v[142:145], v[62:65]
	v_mfma_f32_16x16x32_bf16 v[58:61], v[172:175], v[164:167], v[58:61]
	v_mfma_f32_16x16x32_bf16 v[50:53], v[184:187], v[164:167], v[50:53]
	v_mfma_f32_16x16x32_bf16 v[54:57], v[184:187], v[142:145], v[54:57]
	v_mfma_f32_16x16x32_bf16 v[46:49], v[192:195], v[142:145], v[46:49]
	v_mfma_f32_16x16x32_bf16 v[42:45], v[192:195], v[164:167], v[42:45]
	v_mfma_f32_16x16x32_bf16 v[34:37], v[200:203], v[164:167], v[34:37]
	v_mfma_f32_16x16x32_bf16 v[38:41], v[200:203], v[142:145], v[38:41]
	v_mfma_f32_16x16x32_bf16 v[30:33], v[168:171], v[204:207], v[30:33]
	v_mfma_f32_16x16x32_bf16 v[26:29], v[168:171], v[212:215], v[26:29]
	v_mfma_f32_16x16x32_bf16 v[18:21], v[180:183], v[212:215], v[18:21]
	v_mfma_f32_16x16x32_bf16 v[22:25], v[180:183], v[204:207], v[22:25]
	v_mfma_f32_16x16x32_bf16 v[14:17], v[188:191], v[204:207], v[14:17]
	v_mfma_f32_16x16x32_bf16 v[10:13], v[188:191], v[212:215], v[10:13]
	v_mfma_f32_16x16x32_bf16 v[2:5], v[196:199], v[212:215], v[2:5]
	v_mfma_f32_16x16x32_bf16 v[6:9], v[196:199], v[204:207], v[6:9]
	v_mfma_f32_16x16x32_bf16 v[30:33], v[172:175], v[208:211], v[30:33]
	v_mfma_f32_16x16x32_bf16 v[26:29], v[172:175], v[220:223], v[26:29]
	v_mfma_f32_16x16x32_bf16 v[18:21], v[184:187], v[220:223], v[18:21]
	v_mfma_f32_16x16x32_bf16 v[22:25], v[184:187], v[208:211], v[22:25]
	v_mfma_f32_16x16x32_bf16 v[14:17], v[192:195], v[208:211], v[14:17]
	v_mfma_f32_16x16x32_bf16 v[10:13], v[192:195], v[220:223], v[10:13]
	v_mfma_f32_16x16x32_bf16 v[2:5], v[200:203], v[220:223], v[2:5]
	v_mfma_f32_16x16x32_bf16 v[6:9], v[200:203], v[208:211], v[6:9]
	s_barrier
	s_setprio 0
	s_add_i32 s16, s16, 2
	s_add_u32 s0, s0, 0x100
	s_addc_u32 s1, s1, 0
	s_cmp_lt_u32 s16, 40
	s_cbranch_scc1 .Lk_ffn_out

; #define WAIT_V(n) asm volatile("s_waitcnt vmcnt(" #n ")" ::: "memory")
; #define WAIT_L(n) asm volatile("s_waitcnt lgkmcnt(" #n ")" ::: "memory")
; #define BAR __builtin_amdgcn_s_barrier()
; #define SCHED __builtin_amdgcn_sched_barrier(0)
; #define STG_A(b, h, kt) stage_half_s(lds0 + ((b) * 2 + (h)) * HT_B, ((h) ? A1 : Ap) + (kt) * BK, off0, off1)
; #define STG_B(b, h, kt) stage_half_s(lds0 + (4 + (b) * 2 + (h)) * HT_B, ((h) ? B1p : Bp) + (kt) * BK, off0, off1)
; #define STG_A(b, h, kt) stage_half_s(lds0 + ((b) * 2 + (h)) * HT_B, ((h) ? A1 : Ap) + (kt) * BK, off0, off1)
; #define STG_B(b, h, kt) stage_half_s(lds0 + (4 + (b) * 2 + (h)) * HT_B, ((h) ? B1p : Bp) + (kt) * BK, off0, off1)
; #define LDA8(b, h) _Pragma("unroll") for (int m = 0; m < 4; ++m) _Pragma("unroll") for (int k = 0; k < 2; ++k) \
;     At[m][k] = *(const bf16x8*)(SA_(shm, b, h) + abase + (m * 2 + k) * 1024)
; #define LDB8(dst, b, h) _Pragma("unroll") for (int n = 0; n < 2; ++n) _Pragma("unroll") for (int k = 0; k < 2; ++k) \
;     dst[n][k] = *(const bf16x8*)(SB_(shm, b, h) + bbase + (n * 2 + k) * 1024)
; template <bool HS>
; __device__ __forceinline__ void gemm_tile8(const u16* __restrict__ Ap, const u16* __restrict__ Bp, int K,
;                                            f32x4 (&acc)[2][2][4][2], char* shm, const int tid, const float* hsr = nullptr) {
;     ...
;     LDB8(B0, 0, 0); SCHED; LDA8(0, 0); STG_A(1, 1, t + 1);
;     WAIT_L(8); BAR; WAIT_L(0); MMA8(0, 0, B0); BAR; SCHED;
;     LDB8(B1, 0, 1); STG_B(0, 0, t + 2);
;     BAR; WAIT_L(0); MMA8(0, 1, B1); BAR;
;     LDA8(0, 1); STG_A(0, 0, t + 2);
;     BAR; WAIT_L(0); MMA8(1, 0, B0); BAR; SCHED;
;     STG_B(0, 1, t + 2);
;     WAIT_V(6); BAR; MMA8(1, 1, B1); BAR;
;     LDB8(B0, 1, 0); SCHED; LDA8(1, 0); STG_A(0, 1, t + 2);
;     WAIT_L(8); BAR; WAIT_L(0); MMA8(0, 0, B0); BAR; SCHED;
;     LDB8(B1, 1, 1); STG_B(1, 0, t + 3);
;     BAR; WAIT_L(0); MMA8(0, 1, B1); BAR;
;     LDA8(1, 1); STG_A(1, 0, t + 3);
;     BAR; WAIT_L(0); MMA8(1, 0, B0); BAR; SCHED;
;     STG_B(1, 1, t + 3);
;     WAIT_V(6); BAR; MMA8(1, 1, B1); BAR;
.Lffn_in_kinit:
	v_readfirstlane_b32 s20, v130
	v_readfirstlane_b32 s21, v131
	v_readfirstlane_b32 s22, v132
	v_readfirstlane_b32 s23, v133
	s_mov_b32 s16, s5
	s_mov_b32 s17, s6
	s_mov_b32 s18, s12
	s_mov_b32 s19, s13
	s_barrier
	s_barrier
	ds_read_b128 v[146:149], v244
	ds_read_b128 v[150:153], v244 offset:1024
	ds_read_b128 v[154:157], v244 offset:2048
	ds_read_b128 v[158:161], v244 offset:3072
	ds_read_b128 v[162:165], v142
	ds_read_b128 v[166:169], v142 offset:1024
	ds_read_b128 v[170:173], v142 offset:2048
	ds_read_b128 v[174:177], v142 offset:3072
	ds_read_b128 v[180:183], v142 offset:4096
	ds_read_b128 v[184:187], v142 offset:5120
	ds_read_b128 v[188:191], v142 offset:6144
	ds_read_b128 v[192:195], v142 offset:7168
	ds_read_b128 v[196:199], v245
	ds_read_b128 v[200:203], v245 offset:1024
	ds_read_b128 v[204:207], v245 offset:2048
	ds_read_b128 v[208:211], v245 offset:3072
	s_add_u32 s0, s18, 0x80
	s_addc_u32 s1, s19, 0
	s_add_i32 s3, s7, 0xc000
	s_mov_b32 m0, s3
	s_nop 0
	global_load_lds_dwordx4 v144, s[0:1]
	s_add_i32 s3, s7, 0xe000
	s_mov_b32 m0, s3
	s_nop 0
	global_load_lds_dwordx4 v143, s[0:1]
	s_waitcnt vmcnt(8) lgkmcnt(0)
	s_setprio 1
	s_barrier
	v_mfma_f32_16x16x32_bf16 v[126:129], v[162:165], v[146:149], 0
	v_mfma_f32_16x16x32_bf16 v[122:125], v[162:165], v[154:157], 0
	v_mfma_f32_16x16x32_bf16 v[114:117], v[170:173], v[154:157], 0
	v_mfma_f32_16x16x32_bf16 v[118:121], v[170:173], v[146:149], 0
	v_mfma_f32_16x16x32_bf16 v[110:113], v[180:183], v[146:149], 0
	v_mfma_f32_16x16x32_bf16 v[106:109], v[180:183], v[154:157], 0
	v_mfma_f32_16x16x32_bf16 v[98:101], v[188:191], v[154:157], 0
	v_mfma_f32_16x16x32_bf16 v[102:105], v[188:191], v[146:149], 0
	v_mfma_f32_16x16x32_bf16 v[126:129], v[166:169], v[150:153], v[126:129]
	v_mfma_f32_16x16x32_bf16 v[122:125], v[166:169], v[158:161], v[122:125]
	v_mfma_f32_16x16x32_bf16 v[114:117], v[174:177], v[158:161], v[114:117]
	v_mfma_f32_16x16x32_bf16 v[118:121], v[174:177], v[150:153], v[118:121]
	v_mfma_f32_16x16x32_bf16 v[110:113], v[184:187], v[150:153], v[110:113]
	v_mfma_f32_16x16x32_bf16 v[106:109], v[184:187], v[158:161], v[106:109]
	v_mfma_f32_16x16x32_bf16 v[98:101], v[192:195], v[158:161], v[98:101]
	v_mfma_f32_16x16x32_bf16 v[102:105], v[192:195], v[150:153], v[102:105]
	v_mfma_f32_16x16x32_bf16 v[94:97], v[162:165], v[196:199], 0
	v_mfma_f32_16x16x32_bf16 v[90:93], v[162:165], v[204:207], 0
	v_mfma_f32_16x16x32_bf16 v[82:85], v[170:173], v[204:207], 0
	v_mfma_f32_16x16x32_bf16 v[86:89], v[170:173], v[196:199], 0
	v_mfma_f32_16x16x32_bf16 v[78:81], v[180:183], v[196:199], 0
	v_mfma_f32_16x16x32_bf16 v[74:77], v[180:183], v[204:207], 0
	v_mfma_f32_16x16x32_bf16 v[66:69], v[188:191], v[204:207], 0
	v_mfma_f32_16x16x32_bf16 v[70:73], v[188:191], v[196:199], 0
	v_mfma_f32_16x16x32_bf16 v[94:97], v[166:169], v[200:203], v[94:97]
	v_mfma_f32_16x16x32_bf16 v[90:93], v[166:169], v[208:211], v[90:93]
	v_mfma_f32_16x16x32_bf16 v[82:85], v[174:177], v[208:211], v[82:85]
	v_mfma_f32_16x16x32_bf16 v[86:89], v[174:177], v[200:203], v[86:89]
	v_mfma_f32_16x16x32_bf16 v[78:81], v[184:187], v[200:203], v[78:81]
	v_mfma_f32_16x16x32_bf16 v[74:77], v[184:187], v[208:211], v[74:77]
	v_mfma_f32_16x16x32_bf16 v[66:69], v[192:195], v[208:211], v[66:69]
	v_mfma_f32_16x16x32_bf16 v[70:73], v[192:195], v[200:203], v[70:73]
	s_barrier
	s_setprio 0
	ds_read_b128 v[162:165], v142 offset:16384
	ds_read_b128 v[166:169], v142 offset:17408
	ds_read_b128 v[170:173], v142 offset:18432
	ds_read_b128 v[174:177], v142 offset:19456
	ds_read_b128 v[180:183], v142 offset:20480
	ds_read_b128 v[184:187], v142 offset:21504
	ds_read_b128 v[188:191], v142 offset:22528
	ds_read_b128 v[192:195], v142 offset:23552
	s_add_u32 s0, s20, 0x100
	s_addc_u32 s1, s21, 0
	s_add_i32 s3, s7, 0x10000
	s_mov_b32 m0, s3
	s_nop 0
	global_load_lds_dwordx4 v144, s[0:1]
	s_add_i32 s3, s7, 0x12000
	s_mov_b32 m0, s3
	s_nop 0
	global_load_lds_dwordx4 v143, s[0:1]
	s_add_u32 s0, s16, 0x100
	s_addc_u32 s1, s17, 0
	s_mov_b32 m0, s7
	s_nop 0
	global_load_lds_dwordx4 v144, s[0:1]
	s_add_i32 s3, s7, 0x2000
	s_mov_b32 m0, s3
	s_nop 0
	global_load_lds_dwordx4 v143, s[0:1]
	s_add_u32 s0, s22, 0x100
	s_addc_u32 s1, s23, 0
	s_add_i32 s3, s7, 0x14000
	s_mov_b32 m0, s3
	s_nop 0
	global_load_lds_dwordx4 v144, s[0:1]
	s_add_i32 s3, s7, 0x16000
	s_mov_b32 m0, s3
	s_nop 0
	global_load_lds_dwordx4 v143, s[0:1]
	s_waitcnt vmcnt(8) lgkmcnt(0)
	s_setprio 1
	s_barrier
	v_mfma_f32_16x16x32_bf16 v[62:65], v[162:165], v[146:149], 0
	v_mfma_f32_16x16x32_bf16 v[58:61], v[162:165], v[154:157], 0
	v_mfma_f32_16x16x32_bf16 v[50:53], v[170:173], v[154:157], 0
	v_mfma_f32_16x16x32_bf16 v[54:57], v[170:173], v[146:149], 0
	v_mfma_f32_16x16x32_bf16 v[46:49], v[180:183], v[146:149], 0
	v_mfma_f32_16x16x32_bf16 v[42:45], v[180:183], v[154:157], 0
	v_mfma_f32_16x16x32_bf16 v[34:37], v[188:191], v[154:157], 0
	v_mfma_f32_16x16x32_bf16 v[38:41], v[188:191], v[146:149], 0
	v_mfma_f32_16x16x32_bf16 v[62:65], v[166:169], v[150:153], v[62:65]
	v_mfma_f32_16x16x32_bf16 v[58:61], v[166:169], v[158:161], v[58:61]
	v_mfma_f32_16x16x32_bf16 v[50:53], v[174:177], v[158:161], v[50:53]
	v_mfma_f32_16x16x32_bf16 v[54:57], v[174:177], v[150:153], v[54:57]
	v_mfma_f32_16x16x32_bf16 v[46:49], v[184:187], v[150:153], v[46:49]
	v_mfma_f32_16x16x32_bf16 v[42:45], v[184:187], v[158:161], v[42:45]
	v_mfma_f32_16x16x32_bf16 v[34:37], v[192:195], v[158:161], v[34:37]
	v_mfma_f32_16x16x32_bf16 v[38:41], v[192:195], v[150:153], v[38:41]
	v_mfma_f32_16x16x32_bf16 v[30:33], v[162:165], v[196:199], 0
	v_mfma_f32_16x16x32_bf16 v[26:29], v[162:165], v[204:207], 0
	v_mfma_f32_16x16x32_bf16 v[18:21], v[170:173], v[204:207], 0
	v_mfma_f32_16x16x32_bf16 v[22:25], v[170:173], v[196:199], 0
	v_mfma_f32_16x16x32_bf16 v[14:17], v[180:183], v[196:199], 0
	v_mfma_f32_16x16x32_bf16 v[10:13], v[180:183], v[204:207], 0
	v_mfma_f32_16x16x32_bf16 v[2:5], v[188:191], v[204:207], 0
	v_mfma_f32_16x16x32_bf16 v[6:9], v[188:191], v[196:199], 0
	v_mfma_f32_16x16x32_bf16 v[30:33], v[166:169], v[200:203], v[30:33]
	v_mfma_f32_16x16x32_bf16 v[26:29], v[166:169], v[208:211], v[26:29]
	v_mfma_f32_16x16x32_bf16 v[18:21], v[174:177], v[208:211], v[18:21]
	v_mfma_f32_16x16x32_bf16 v[22:25], v[174:177], v[200:203], v[22:25]
	v_mfma_f32_16x16x32_bf16 v[14:17], v[184:187], v[200:203], v[14:17]
	v_mfma_f32_16x16x32_bf16 v[10:13], v[184:187], v[208:211], v[10:13]
	v_mfma_f32_16x16x32_bf16 v[2:5], v[192:195], v[208:211], v[2:5]
	v_mfma_f32_16x16x32_bf16 v[6:9], v[192:195], v[200:203], v[6:9]
	s_barrier
; #define WAIT_V(n) asm volatile("s_waitcnt vmcnt(" #n ")" ::: "memory")
; #define WAIT_L(n) asm volatile("s_waitcnt lgkmcnt(" #n ")" ::: "memory")
; #define BAR __builtin_amdgcn_s_barrier()
; #define SCHED __builtin_amdgcn_sched_barrier(0)
; #define STG_A(b, h, kt) stage_half_s(lds0 + ((b) * 2 + (h)) * HT_B, ((h) ? A1 : Ap) + (kt) * BK, off0, off1)
; #define STG_B(b, h, kt) stage_half_s(lds0 + (4 + (b) * 2 + (h)) * HT_B, ((h) ? B1p : Bp) + (kt) * BK, off0, off1)
; #define STG_A(b, h, kt) stage_half_s(lds0 + ((b) * 2 + (h)) * HT_B, ((h) ? A1 : Ap) + (kt) * BK, off0, off1)
; #define STG_B(b, h, kt) stage_half_s(lds0 + (4 + (b) * 2 + (h)) * HT_B, ((h) ? B1p : Bp) + (kt) * BK, off0, off1)
; #define LDA8(b, h) _Pragma("unroll") for (int m = 0; m < 4; ++m) _Pragma("unroll") for (int k = 0; k < 2; ++k) \
;     At[m][k] = *(const bf16x8*)(SA_(shm, b, h) + abase + (m * 2 + k) * 1024)
; #define LDB8(dst, b, h) _Pragma("unroll") for (int n = 0; n < 2; ++n) _Pragma("unroll") for (int k = 0; k < 2; ++k) \
;     dst[n][k] = *(const bf16x8*)(SB_(shm, b, h) + bbase + (n * 2 + k) * 1024)
; template <bool HS>
; __device__ __forceinline__ void gemm_tile8(const u16* __restrict__ Ap, const u16* __restrict__ Bp, int K,
;                                            f32x4 (&acc)[2][2][4][2], char* shm, const int tid, const float* hsr = nullptr) {
;     ...
;     LDB8(B0, 0, 0); SCHED; LDA8(0, 0); STG_A(1, 1, t + 1);
;     WAIT_L(8); BAR; WAIT_L(0); MMA8(0, 0, B0); BAR; SCHED;
;     LDB8(B1, 0, 1); STG_B(0, 0, t + 2);
;     BAR; WAIT_L(0); MMA8(0, 1, B1); BAR;
;     LDA8(0, 1); STG_A(0, 0, t + 2);
;     BAR; WAIT_L(0); MMA8(1, 0, B0); BAR; SCHED;
;     STG_B(0, 1, t + 2);
;     WAIT_V(6); BAR; MMA8(1, 1, B1); BAR;
;     LDB8(B0, 1, 0); SCHED; LDA8(1, 0); STG_A(0, 1, t + 2);
;     WAIT_L(8); BAR; WAIT_L(0); MMA8(0, 0, B0); BAR; SCHED;
;     LDB8(B1, 1, 1); STG_B(1, 0, t + 3);
;     BAR; WAIT_L(0); MMA8(0, 1, B1); BAR;
;     LDA8(1, 1); STG_A(1, 0, t + 3);
;     BAR; WAIT_L(0); MMA8(1, 0, B0); BAR; SCHED;
;     STG_B(1, 1, t + 3);
;     WAIT_V(6); BAR; MMA8(1, 1, B1); BAR;
	s_setprio 0
	ds_read_b128 v[146:149], v246
	ds_read_b128 v[150:153], v246 offset:1024
	ds_read_b128 v[154:157], v246 offset:2048
	ds_read_b128 v[158:161], v246 offset:3072
	ds_read_b128 v[162:165], v142 offset:32768
	ds_read_b128 v[166:169], v142 offset:33792
	ds_read_b128 v[170:173], v142 offset:34816
	ds_read_b128 v[174:177], v142 offset:35840
	ds_read_b128 v[180:183], v142 offset:36864
	ds_read_b128 v[184:187], v142 offset:37888
	ds_read_b128 v[188:191], v142 offset:38912
	ds_read_b128 v[192:195], v142 offset:39936
	ds_read_b128 v[196:199], v247
	ds_read_b128 v[200:203], v247 offset:1024
	ds_read_b128 v[204:207], v247 offset:2048
	ds_read_b128 v[208:211], v247 offset:3072
	s_add_u32 s0, s18, 0x100
	s_addc_u32 s1, s19, 0
	s_add_i32 s3, s7, 0x4000
	s_mov_b32 m0, s3
	s_nop 0
	global_load_lds_dwordx4 v144, s[0:1]
	s_add_i32 s3, s7, 0x6000
	s_mov_b32 m0, s3
	s_nop 0
	global_load_lds_dwordx4 v143, s[0:1]
	s_waitcnt vmcnt(8) lgkmcnt(0)
	s_setprio 1
	s_barrier
	v_mfma_f32_16x16x32_bf16 v[126:129], v[162:165], v[146:149], v[126:129]
	v_mfma_f32_16x16x32_bf16 v[122:125], v[162:165], v[154:157], v[122:125]
	v_mfma_f32_16x16x32_bf16 v[114:117], v[170:173], v[154:157], v[114:117]
	v_mfma_f32_16x16x32_bf16 v[118:121], v[170:173], v[146:149], v[118:121]
	v_mfma_f32_16x16x32_bf16 v[110:113], v[180:183], v[146:149], v[110:113]
	v_mfma_f32_16x16x32_bf16 v[106:109], v[180:183], v[154:157], v[106:109]
	v_mfma_f32_16x16x32_bf16 v[98:101], v[188:191], v[154:157], v[98:101]
	v_mfma_f32_16x16x32_bf16 v[102:105], v[188:191], v[146:149], v[102:105]
	v_mfma_f32_16x16x32_bf16 v[126:129], v[166:169], v[150:153], v[126:129]
	v_mfma_f32_16x16x32_bf16 v[122:125], v[166:169], v[158:161], v[122:125]
	v_mfma_f32_16x16x32_bf16 v[114:117], v[174:177], v[158:161], v[114:117]
	v_mfma_f32_16x16x32_bf16 v[118:121], v[174:177], v[150:153], v[118:121]
	v_mfma_f32_16x16x32_bf16 v[110:113], v[184:187], v[150:153], v[110:113]
	v_mfma_f32_16x16x32_bf16 v[106:109], v[184:187], v[158:161], v[106:109]
	v_mfma_f32_16x16x32_bf16 v[98:101], v[192:195], v[158:161], v[98:101]
	v_mfma_f32_16x16x32_bf16 v[102:105], v[192:195], v[150:153], v[102:105]
	v_mfma_f32_16x16x32_bf16 v[94:97], v[162:165], v[196:199], v[94:97]
	v_mfma_f32_16x16x32_bf16 v[90:93], v[162:165], v[204:207], v[90:93]
	v_mfma_f32_16x16x32_bf16 v[82:85], v[170:173], v[204:207], v[82:85]
	v_mfma_f32_16x16x32_bf16 v[86:89], v[170:173], v[196:199], v[86:89]
	v_mfma_f32_16x16x32_bf16 v[78:81], v[180:183], v[196:199], v[78:81]
	v_mfma_f32_16x16x32_bf16 v[74:77], v[180:183], v[204:207], v[74:77]
	v_mfma_f32_16x16x32_bf16 v[66:69], v[188:191], v[204:207], v[66:69]
	v_mfma_f32_16x16x32_bf16 v[70:73], v[188:191], v[196:199], v[70:73]
	v_mfma_f32_16x16x32_bf16 v[94:97], v[166:169], v[200:203], v[94:97]
	v_mfma_f32_16x16x32_bf16 v[90:93], v[166:169], v[208:211], v[90:93]
	v_mfma_f32_16x16x32_bf16 v[82:85], v[174:177], v[208:211], v[82:85]
	v_mfma_f32_16x16x32_bf16 v[86:89], v[174:177], v[200:203], v[86:89]
	v_mfma_f32_16x16x32_bf16 v[78:81], v[184:187], v[200:203], v[78:81]
	v_mfma_f32_16x16x32_bf16 v[74:77], v[184:187], v[208:211], v[74:77]
	v_mfma_f32_16x16x32_bf16 v[66:69], v[192:195], v[208:211], v[66:69]
	v_mfma_f32_16x16x32_bf16 v[70:73], v[192:195], v[200:203], v[70:73]
	s_barrier
	s_setprio 0
	ds_read_b128 v[162:165], v142 offset:49152
	ds_read_b128 v[166:169], v142 offset:50176
	ds_read_b128 v[170:173], v142 offset:51200
	ds_read_b128 v[174:177], v142 offset:52224
	ds_read_b128 v[180:183], v142 offset:53248
	ds_read_b128 v[184:187], v142 offset:54272
	ds_read_b128 v[188:191], v142 offset:55296
	ds_read_b128 v[192:195], v142 offset:56320
	s_add_u32 s0, s20, 0x180
	s_addc_u32 s1, s21, 0
	s_add_i32 s3, s7, 0x18000
	s_mov_b32 m0, s3
	s_nop 0
	global_load_lds_dwordx4 v144, s[0:1]
	s_add_i32 s3, s7, 0x1a000
	s_mov_b32 m0, s3
	s_nop 0
	global_load_lds_dwordx4 v143, s[0:1]
	s_add_u32 s0, s16, 0x180
	s_addc_u32 s1, s17, 0
	s_add_i32 s3, s7, 0x8000
	s_mov_b32 m0, s3
	s_nop 0
	global_load_lds_dwordx4 v144, s[0:1]
	s_add_i32 s3, s7, 0xa000
	s_mov_b32 m0, s3
	s_nop 0
	global_load_lds_dwordx4 v143, s[0:1]
	s_add_u32 s0, s22, 0x180
	s_addc_u32 s1, s23, 0
	s_add_i32 s3, s7, 0x1c000
	s_mov_b32 m0, s3
	s_nop 0
	global_load_lds_dwordx4 v144, s[0:1]
	s_add_i32 s3, s7, 0x1e000
	s_mov_b32 m0, s3
	s_nop 0
	global_load_lds_dwordx4 v143, s[0:1]
	s_waitcnt vmcnt(8) lgkmcnt(0)
	s_setprio 1
	s_barrier
	v_mfma_f32_16x16x32_bf16 v[62:65], v[162:165], v[146:149], v[62:65]
	v_mfma_f32_16x16x32_bf16 v[58:61], v[162:165], v[154:157], v[58:61]
	v_mfma_f32_16x16x32_bf16 v[50:53], v[170:173], v[154:157], v[50:53]
	v_mfma_f32_16x16x32_bf16 v[54:57], v[170:173], v[146:149], v[54:57]
	v_mfma_f32_16x16x32_bf16 v[46:49], v[180:183], v[146:149], v[46:49]
	v_mfma_f32_16x16x32_bf16 v[42:45], v[180:183], v[154:157], v[42:45]
	v_mfma_f32_16x16x32_bf16 v[34:37], v[188:191], v[154:157], v[34:37]
	v_mfma_f32_16x16x32_bf16 v[38:41], v[188:191], v[146:149], v[38:41]
	v_mfma_f32_16x16x32_bf16 v[62:65], v[166:169], v[150:153], v[62:65]
	v_mfma_f32_16x16x32_bf16 v[58:61], v[166:169], v[158:161], v[58:61]
	v_mfma_f32_16x16x32_bf16 v[50:53], v[174:177], v[158:161], v[50:53]
	v_mfma_f32_16x16x32_bf16 v[54:57], v[174:177], v[150:153], v[54:57]
	v_mfma_f32_16x16x32_bf16 v[46:49], v[184:187], v[150:153], v[46:49]
	v_mfma_f32_16x16x32_bf16 v[42:45], v[184:187], v[158:161], v[42:45]
	v_mfma_f32_16x16x32_bf16 v[34:37], v[192:195], v[158:161], v[34:37]
	v_mfma_f32_16x16x32_bf16 v[38:41], v[192:195], v[150:153], v[38:41]
	v_mfma_f32_16x16x32_bf16 v[30:33], v[162:165], v[196:199], v[30:33]
	v_mfma_f32_16x16x32_bf16 v[26:29], v[162:165], v[204:207], v[26:29]
	v_mfma_f32_16x16x32_bf16 v[18:21], v[170:173], v[204:207], v[18:21]
	v_mfma_f32_16x16x32_bf16 v[22:25], v[170:173], v[196:199], v[22:25]
	v_mfma_f32_16x16x32_bf16 v[14:17], v[180:183], v[196:199], v[14:17]
	v_mfma_f32_16x16x32_bf16 v[10:13], v[180:183], v[204:207], v[10:13]
	v_mfma_f32_16x16x32_bf16 v[2:5], v[188:191], v[204:207], v[2:5]
	v_mfma_f32_16x16x32_bf16 v[6:9], v[188:191], v[196:199], v[6:9]
	v_mfma_f32_16x16x32_bf16 v[30:33], v[166:169], v[200:203], v[30:33]
	v_mfma_f32_16x16x32_bf16 v[26:29], v[166:169], v[208:211], v[26:29]
	v_mfma_f32_16x16x32_bf16 v[18:21], v[174:177], v[208:211], v[18:21]
	v_mfma_f32_16x16x32_bf16 v[22:25], v[174:177], v[200:203], v[22:25]
	v_mfma_f32_16x16x32_bf16 v[14:17], v[184:187], v[200:203], v[14:17]
	v_mfma_f32_16x16x32_bf16 v[10:13], v[184:187], v[208:211], v[10:13]
	v_mfma_f32_16x16x32_bf16 v[2:5], v[192:195], v[208:211], v[2:5]
	v_mfma_f32_16x16x32_bf16 v[6:9], v[192:195], v[200:203], v[6:9]
	s_barrier
	s_setprio 0
	s_add_u32 s16, s16, 0x100
	s_addc_u32 s17, s17, 0
	s_add_u32 s18, s18, 0x100
	s_addc_u32 s19, s19, 0
	s_add_u32 s20, s20, 0x100
	s_addc_u32 s21, s21, 0
	s_add_u32 s22, s22, 0x100
	s_addc_u32 s23, s23, 0
	s_mov_b32 s14, 6
; #define WAIT_V(n) asm volatile("s_waitcnt vmcnt(" #n ")" ::: "memory")
; #define WAIT_L(n) asm volatile("s_waitcnt lgkmcnt(" #n ")" ::: "memory")
; #define BAR __builtin_amdgcn_s_barrier()
; #define SCHED __builtin_amdgcn_sched_barrier(0)
; #define STG_A(b, h, kt) stage_half_s(lds0 + ((b) * 2 + (h)) * HT_B, ((h) ? A1 : Ap) + (kt) * BK, off0, off1)
; #define STG_B(b, h, kt) stage_half_s(lds0 + (4 + (b) * 2 + (h)) * HT_B, ((h) ? B1p : Bp) + (kt) * BK, off0, off1)
; #define STG_A(b, h, kt) stage_half_s(lds0 + ((b) * 2 + (h)) * HT_B, ((h) ? A1 : Ap) + (kt) * BK, off0, off1)
; #define STG_B(b, h, kt) stage_half_s(lds0 + (4 + (b) * 2 + (h)) * HT_B, ((h) ? B1p : Bp) + (kt) * BK, off0, off1)
; #define LDA8(b, h) _Pragma("unroll") for (int m = 0; m < 4; ++m) _Pragma("unroll") for (int k = 0; k < 2; ++k) \
;     At[m][k] = *(const bf16x8*)(SA_(shm, b, h) + abase + (m * 2 + k) * 1024)
; #define LDB8(dst, b, h) _Pragma("unroll") for (int n = 0; n < 2; ++n) _Pragma("unroll") for (int k = 0; k < 2; ++k) \
;     dst[n][k] = *(const bf16x8*)(SB_(shm, b, h) + bbase + (n * 2 + k) * 1024)
; template <bool HS>
; __device__ __forceinline__ void gemm_tile8(const u16* __restrict__ Ap, const u16* __restrict__ Bp, int K,
;                                            f32x4 (&acc)[2][2][4][2], char* shm, const int tid, const float* hsr = nullptr) {
;     ...
;     LDB8(B0, 0, 0); SCHED; LDA8(0, 0); STG_A(1, 1, t + 1);
;     WAIT_L(8); BAR; WAIT_L(0); MMA8(0, 0, B0); BAR; SCHED;
;     LDB8(B1, 0, 1); STG_B(0, 0, t + 2);
;     BAR; WAIT_L(0); MMA8(0, 1, B1); BAR;
;     LDA8(0, 1); STG_A(0, 0, t + 2);
;     BAR; WAIT_L(0); MMA8(1, 0, B0); BAR; SCHED;
;     STG_B(0, 1, t + 2);
;     WAIT_V(6); BAR; MMA8(1, 1, B1); BAR;
;     LDB8(B0, 1, 0); SCHED; LDA8(1, 0); STG_A(0, 1, t + 2);
;     WAIT_L(8); BAR; WAIT_L(0); MMA8(0, 0, B0); BAR; SCHED;
;     LDB8(B1, 1, 1); STG_B(1, 0, t + 3);
;     BAR; WAIT_L(0); MMA8(0, 1, B1); BAR;
;     LDA8(1, 1); STG_A(1, 0, t + 3);
;     BAR; WAIT_L(0); MMA8(1, 0, B0); BAR; SCHED;
;     STG_B(1, 1, t + 3);
;     WAIT_V(6); BAR; MMA8(1, 1, B1); BAR;
.Lk_ffn_in:
	ds_read_b128 v[146:149], v244
	ds_read_b128 v[150:153], v244 offset:1024
	ds_read_b128 v[154:157], v244 offset:2048
	ds_read_b128 v[158:161], v244 offset:3072
	ds_read_b128 v[162:165], v142
	ds_read_b128 v[166:169], v142 offset:1024
	ds_read_b128 v[170:173], v142 offset:2048
	ds_read_b128 v[174:177], v142 offset:3072
	ds_read_b128 v[180:183], v142 offset:4096
	ds_read_b128 v[184:187], v142 offset:5120
	ds_read_b128 v[188:191], v142 offset:6144
	ds_read_b128 v[192:195], v142 offset:7168
	ds_read_b128 v[196:199], v245
	ds_read_b128 v[200:203], v245 offset:1024
	ds_read_b128 v[204:207], v245 offset:2048
	ds_read_b128 v[208:211], v245 offset:3072
	s_add_u32 s0, s18, 0x80
	s_addc_u32 s1, s19, 0
	s_add_i32 s3, s7, 0xc000
	s_mov_b32 m0, s3
	s_nop 0
	global_load_lds_dwordx4 v144, s[0:1]
	s_add_i32 s3, s7, 0xe000
	s_mov_b32 m0, s3
	s_nop 0
	global_load_lds_dwordx4 v143, s[0:1]
	s_waitcnt vmcnt(8) lgkmcnt(0)
	s_setprio 1
	s_barrier
	v_mfma_f32_16x16x32_bf16 v[126:129], v[162:165], v[146:149], v[126:129]
	v_mfma_f32_16x16x32_bf16 v[122:125], v[162:165], v[154:157], v[122:125]
	v_mfma_f32_16x16x32_bf16 v[114:117], v[170:173], v[154:157], v[114:117]
	v_mfma_f32_16x16x32_bf16 v[118:121], v[170:173], v[146:149], v[118:121]
	v_mfma_f32_16x16x32_bf16 v[110:113], v[180:183], v[146:149], v[110:113]
	v_mfma_f32_16x16x32_bf16 v[106:109], v[180:183], v[154:157], v[106:109]
	v_mfma_f32_16x16x32_bf16 v[98:101], v[188:191], v[154:157], v[98:101]
	v_mfma_f32_16x16x32_bf16 v[102:105], v[188:191], v[146:149], v[102:105]
	v_mfma_f32_16x16x32_bf16 v[126:129], v[166:169], v[150:153], v[126:129]
	v_mfma_f32_16x16x32_bf16 v[122:125], v[166:169], v[158:161], v[122:125]
	v_mfma_f32_16x16x32_bf16 v[114:117], v[174:177], v[158:161], v[114:117]
	v_mfma_f32_16x16x32_bf16 v[118:121], v[174:177], v[150:153], v[118:121]
	v_mfma_f32_16x16x32_bf16 v[110:113], v[184:187], v[150:153], v[110:113]
	v_mfma_f32_16x16x32_bf16 v[106:109], v[184:187], v[158:161], v[106:109]
	v_mfma_f32_16x16x32_bf16 v[98:101], v[192:195], v[158:161], v[98:101]
	v_mfma_f32_16x16x32_bf16 v[102:105], v[192:195], v[150:153], v[102:105]
	v_mfma_f32_16x16x32_bf16 v[94:97], v[162:165], v[196:199], v[94:97]
	v_mfma_f32_16x16x32_bf16 v[90:93], v[162:165], v[204:207], v[90:93]
	v_mfma_f32_16x16x32_bf16 v[82:85], v[170:173], v[204:207], v[82:85]
	v_mfma_f32_16x16x32_bf16 v[86:89], v[170:173], v[196:199], v[86:89]
	v_mfma_f32_16x16x32_bf16 v[78:81], v[180:183], v[196:199], v[78:81]
	v_mfma_f32_16x16x32_bf16 v[74:77], v[180:183], v[204:207], v[74:77]
	v_mfma_f32_16x16x32_bf16 v[66:69], v[188:191], v[204:207], v[66:69]
	v_mfma_f32_16x16x32_bf16 v[70:73], v[188:191], v[196:199], v[70:73]
	v_mfma_f32_16x16x32_bf16 v[94:97], v[166:169], v[200:203], v[94:97]
	v_mfma_f32_16x16x32_bf16 v[90:93], v[166:169], v[208:211], v[90:93]
	v_mfma_f32_16x16x32_bf16 v[82:85], v[174:177], v[208:211], v[82:85]
	v_mfma_f32_16x16x32_bf16 v[86:89], v[174:177], v[200:203], v[86:89]
	v_mfma_f32_16x16x32_bf16 v[78:81], v[184:187], v[200:203], v[78:81]
	v_mfma_f32_16x16x32_bf16 v[74:77], v[184:187], v[208:211], v[74:77]
	v_mfma_f32_16x16x32_bf16 v[66:69], v[192:195], v[208:211], v[66:69]
	v_mfma_f32_16x16x32_bf16 v[70:73], v[192:195], v[200:203], v[70:73]
	s_barrier
	s_setprio 0
	ds_read_b128 v[162:165], v142 offset:16384
	ds_read_b128 v[166:169], v142 offset:17408
	ds_read_b128 v[170:173], v142 offset:18432
	ds_read_b128 v[174:177], v142 offset:19456
	ds_read_b128 v[180:183], v142 offset:20480
	ds_read_b128 v[184:187], v142 offset:21504
	ds_read_b128 v[188:191], v142 offset:22528
	ds_read_b128 v[192:195], v142 offset:23552
	s_add_u32 s0, s20, 0x100
	s_addc_u32 s1, s21, 0
	s_add_i32 s3, s7, 0x10000
	s_mov_b32 m0, s3
	s_nop 0
	global_load_lds_dwordx4 v144, s[0:1]
	s_add_i32 s3, s7, 0x12000
	s_mov_b32 m0, s3
	s_nop 0
	global_load_lds_dwordx4 v143, s[0:1]
	s_add_u32 s0, s16, 0x100
	s_addc_u32 s1, s17, 0
	s_mov_b32 m0, s7
	s_nop 0
	global_load_lds_dwordx4 v144, s[0:1]
	s_add_i32 s3, s7, 0x2000
	s_mov_b32 m0, s3
	s_nop 0
	global_load_lds_dwordx4 v143, s[0:1]
	s_add_u32 s0, s22, 0x100
	s_addc_u32 s1, s23, 0
	s_add_i32 s3, s7, 0x14000
	s_mov_b32 m0, s3
	s_nop 0
	global_load_lds_dwordx4 v144, s[0:1]
	s_add_i32 s3, s7, 0x16000
	s_mov_b32 m0, s3
	s_nop 0
	global_load_lds_dwordx4 v143, s[0:1]
	s_waitcnt vmcnt(8) lgkmcnt(0)
	s_setprio 1
	s_barrier
	v_mfma_f32_16x16x32_bf16 v[62:65], v[162:165], v[146:149], v[62:65]
	v_mfma_f32_16x16x32_bf16 v[58:61], v[162:165], v[154:157], v[58:61]
	v_mfma_f32_16x16x32_bf16 v[50:53], v[170:173], v[154:157], v[50:53]
	v_mfma_f32_16x16x32_bf16 v[54:57], v[170:173], v[146:149], v[54:57]
	v_mfma_f32_16x16x32_bf16 v[46:49], v[180:183], v[146:149], v[46:49]
	v_mfma_f32_16x16x32_bf16 v[42:45], v[180:183], v[154:157], v[42:45]
	v_mfma_f32_16x16x32_bf16 v[34:37], v[188:191], v[154:157], v[34:37]
	v_mfma_f32_16x16x32_bf16 v[38:41], v[188:191], v[146:149], v[38:41]
	v_mfma_f32_16x16x32_bf16 v[62:65], v[166:169], v[150:153], v[62:65]
	v_mfma_f32_16x16x32_bf16 v[58:61], v[166:169], v[158:161], v[58:61]
	v_mfma_f32_16x16x32_bf16 v[50:53], v[174:177], v[158:161], v[50:53]
	v_mfma_f32_16x16x32_bf16 v[54:57], v[174:177], v[150:153], v[54:57]
	v_mfma_f32_16x16x32_bf16 v[46:49], v[184:187], v[150:153], v[46:49]
	v_mfma_f32_16x16x32_bf16 v[42:45], v[184:187], v[158:161], v[42:45]
	v_mfma_f32_16x16x32_bf16 v[34:37], v[192:195], v[158:161], v[34:37]
	v_mfma_f32_16x16x32_bf16 v[38:41], v[192:195], v[150:153], v[38:41]
	v_mfma_f32_16x16x32_bf16 v[30:33], v[162:165], v[196:199], v[30:33]
	v_mfma_f32_16x16x32_bf16 v[26:29], v[162:165], v[204:207], v[26:29]
	v_mfma_f32_16x16x32_bf16 v[18:21], v[170:173], v[204:207], v[18:21]
	v_mfma_f32_16x16x32_bf16 v[22:25], v[170:173], v[196:199], v[22:25]
	v_mfma_f32_16x16x32_bf16 v[14:17], v[180:183], v[196:199], v[14:17]
	v_mfma_f32_16x16x32_bf16 v[10:13], v[180:183], v[204:207], v[10:13]
	v_mfma_f32_16x16x32_bf16 v[2:5], v[188:191], v[204:207], v[2:5]
	v_mfma_f32_16x16x32_bf16 v[6:9], v[188:191], v[196:199], v[6:9]
	v_mfma_f32_16x16x32_bf16 v[30:33], v[166:169], v[200:203], v[30:33]
	v_mfma_f32_16x16x32_bf16 v[26:29], v[166:169], v[208:211], v[26:29]
	v_mfma_f32_16x16x32_bf16 v[18:21], v[174:177], v[208:211], v[18:21]
	v_mfma_f32_16x16x32_bf16 v[22:25], v[174:177], v[200:203], v[22:25]
	v_mfma_f32_16x16x32_bf16 v[14:17], v[184:187], v[200:203], v[14:17]
	v_mfma_f32_16x16x32_bf16 v[10:13], v[184:187], v[208:211], v[10:13]
	v_mfma_f32_16x16x32_bf16 v[2:5], v[192:195], v[208:211], v[2:5]
	v_mfma_f32_16x16x32_bf16 v[6:9], v[192:195], v[200:203], v[6:9]
	s_barrier
; #define WAIT_V(n) asm volatile("s_waitcnt vmcnt(" #n ")" ::: "memory")
; #define WAIT_L(n) asm volatile("s_waitcnt lgkmcnt(" #n ")" ::: "memory")
; #define BAR __builtin_amdgcn_s_barrier()
; #define SCHED __builtin_amdgcn_sched_barrier(0)
; #define STG_A(b, h, kt) stage_half_s(lds0 + ((b) * 2 + (h)) * HT_B, ((h) ? A1 : Ap) + (kt) * BK, off0, off1)
; #define STG_B(b, h, kt) stage_half_s(lds0 + (4 + (b) * 2 + (h)) * HT_B, ((h) ? B1p : Bp) + (kt) * BK, off0, off1)
; #define STG_A(b, h, kt) stage_half_s(lds0 + ((b) * 2 + (h)) * HT_B, ((h) ? A1 : Ap) + (kt) * BK, off0, off1)
; #define STG_B(b, h, kt) stage_half_s(lds0 + (4 + (b) * 2 + (h)) * HT_B, ((h) ? B1p : Bp) + (kt) * BK, off0, off1)
; #define LDA8(b, h) _Pragma("unroll") for (int m = 0; m < 4; ++m) _Pragma("unroll") for (int k = 0; k < 2; ++k) \
;     At[m][k] = *(const bf16x8*)(SA_(shm, b, h) + abase + (m * 2 + k) * 1024)
; #define LDB8(dst, b, h) _Pragma("unroll") for (int n = 0; n < 2; ++n) _Pragma("unroll") for (int k = 0; k < 2; ++k) \
;     dst[n][k] = *(const bf16x8*)(SB_(shm, b, h) + bbase + (n * 2 + k) * 1024)
; template <bool HS>
; __device__ __forceinline__ void gemm_tile8(const u16* __restrict__ Ap, const u16* __restrict__ Bp, int K,
;                                            f32x4 (&acc)[2][2][4][2], char* shm, const int tid, const float* hsr = nullptr) {
;     ...
;     LDB8(B0, 0, 0); SCHED; LDA8(0, 0); STG_A(1, 1, t + 1);
;     WAIT_L(8); BAR; WAIT_L(0); MMA8(0, 0, B0); BAR; SCHED;
;     LDB8(B1, 0, 1); STG_B(0, 0, t + 2);
;     BAR; WAIT_L(0); MMA8(0, 1, B1); BAR;
;     LDA8(0, 1); STG_A(0, 0, t + 2);
;     BAR; WAIT_L(0); MMA8(1, 0, B0); BAR; SCHED;
;     STG_B(0, 1, t + 2);
;     WAIT_V(6); BAR; MMA8(1, 1, B1); BAR;
;     LDB8(B0, 1, 0); SCHED; LDA8(1, 0); STG_A(0, 1, t + 2);
;     WAIT_L(8); BAR; WAIT_L(0); MMA8(0, 0, B0); BAR; SCHED;
;     LDB8(B1, 1, 1); STG_B(1, 0, t + 3);
;     BAR; WAIT_L(0); MMA8(0, 1, B1); BAR;
;     LDA8(1, 1); STG_A(1, 0, t + 3);
;     BAR; WAIT_L(0); MMA8(1, 0, B0); BAR; SCHED;
;     STG_B(1, 1, t + 3);
;     WAIT_V(6); BAR; MMA8(1, 1, B1); BAR;
	s_setprio 0
	ds_read_b128 v[146:149], v246
	ds_read_b128 v[150:153], v246 offset:1024
	ds_read_b128 v[154:157], v246 offset:2048
	ds_read_b128 v[158:161], v246 offset:3072
	ds_read_b128 v[162:165], v142 offset:32768
	ds_read_b128 v[166:169], v142 offset:33792
	ds_read_b128 v[170:173], v142 offset:34816
	ds_read_b128 v[174:177], v142 offset:35840
	ds_read_b128 v[180:183], v142 offset:36864
	ds_read_b128 v[184:187], v142 offset:37888
	ds_read_b128 v[188:191], v142 offset:38912
	ds_read_b128 v[192:195], v142 offset:39936
	ds_read_b128 v[196:199], v247
	ds_read_b128 v[200:203], v247 offset:1024
	ds_read_b128 v[204:207], v247 offset:2048
	ds_read_b128 v[208:211], v247 offset:3072
	s_add_u32 s0, s18, 0x100
	s_addc_u32 s1, s19, 0
	s_add_i32 s3, s7, 0x4000
	s_mov_b32 m0, s3
	s_nop 0
	global_load_lds_dwordx4 v144, s[0:1]
	s_add_i32 s3, s7, 0x6000
	s_mov_b32 m0, s3
	s_nop 0
	global_load_lds_dwordx4 v143, s[0:1]
	s_waitcnt vmcnt(8) lgkmcnt(0)
	s_setprio 1
	s_barrier
	v_mfma_f32_16x16x32_bf16 v[126:129], v[162:165], v[146:149], v[126:129]
	v_mfma_f32_16x16x32_bf16 v[122:125], v[162:165], v[154:157], v[122:125]
	v_mfma_f32_16x16x32_bf16 v[114:117], v[170:173], v[154:157], v[114:117]
	v_mfma_f32_16x16x32_bf16 v[118:121], v[170:173], v[146:149], v[118:121]
	v_mfma_f32_16x16x32_bf16 v[110:113], v[180:183], v[146:149], v[110:113]
	v_mfma_f32_16x16x32_bf16 v[106:109], v[180:183], v[154:157], v[106:109]
	v_mfma_f32_16x16x32_bf16 v[98:101], v[188:191], v[154:157], v[98:101]
	v_mfma_f32_16x16x32_bf16 v[102:105], v[188:191], v[146:149], v[102:105]
	v_mfma_f32_16x16x32_bf16 v[126:129], v[166:169], v[150:153], v[126:129]
	v_mfma_f32_16x16x32_bf16 v[122:125], v[166:169], v[158:161], v[122:125]
	v_mfma_f32_16x16x32_bf16 v[114:117], v[174:177], v[158:161], v[114:117]
	v_mfma_f32_16x16x32_bf16 v[118:121], v[174:177], v[150:153], v[118:121]
	v_mfma_f32_16x16x32_bf16 v[110:113], v[184:187], v[150:153], v[110:113]
	v_mfma_f32_16x16x32_bf16 v[106:109], v[184:187], v[158:161], v[106:109]
	v_mfma_f32_16x16x32_bf16 v[98:101], v[192:195], v[158:161], v[98:101]
	v_mfma_f32_16x16x32_bf16 v[102:105], v[192:195], v[150:153], v[102:105]
	v_mfma_f32_16x16x32_bf16 v[94:97], v[162:165], v[196:199], v[94:97]
	v_mfma_f32_16x16x32_bf16 v[90:93], v[162:165], v[204:207], v[90:93]
	v_mfma_f32_16x16x32_bf16 v[82:85], v[170:173], v[204:207], v[82:85]
	v_mfma_f32_16x16x32_bf16 v[86:89], v[170:173], v[196:199], v[86:89]
	v_mfma_f32_16x16x32_bf16 v[78:81], v[180:183], v[196:199], v[78:81]
	v_mfma_f32_16x16x32_bf16 v[74:77], v[180:183], v[204:207], v[74:77]
	v_mfma_f32_16x16x32_bf16 v[66:69], v[188:191], v[204:207], v[66:69]
	v_mfma_f32_16x16x32_bf16 v[70:73], v[188:191], v[196:199], v[70:73]
	v_mfma_f32_16x16x32_bf16 v[94:97], v[166:169], v[200:203], v[94:97]
	v_mfma_f32_16x16x32_bf16 v[90:93], v[166:169], v[208:211], v[90:93]
	v_mfma_f32_16x16x32_bf16 v[82:85], v[174:177], v[208:211], v[82:85]
	v_mfma_f32_16x16x32_bf16 v[86:89], v[174:177], v[200:203], v[86:89]
	v_mfma_f32_16x16x32_bf16 v[78:81], v[184:187], v[200:203], v[78:81]
	v_mfma_f32_16x16x32_bf16 v[74:77], v[184:187], v[208:211], v[74:77]
	v_mfma_f32_16x16x32_bf16 v[66:69], v[192:195], v[208:211], v[66:69]
	v_mfma_f32_16x16x32_bf16 v[70:73], v[192:195], v[200:203], v[70:73]
	s_barrier
	s_setprio 0
	ds_read_b128 v[162:165], v142 offset:49152
	ds_read_b128 v[166:169], v142 offset:50176
	ds_read_b128 v[170:173], v142 offset:51200
	ds_read_b128 v[174:177], v142 offset:52224
	ds_read_b128 v[180:183], v142 offset:53248
	ds_read_b128 v[184:187], v142 offset:54272
	ds_read_b128 v[188:191], v142 offset:55296
	ds_read_b128 v[192:195], v142 offset:56320
	s_add_u32 s0, s20, 0x180
	s_addc_u32 s1, s21, 0
	s_add_i32 s3, s7, 0x18000
	s_mov_b32 m0, s3
	s_nop 0
	global_load_lds_dwordx4 v144, s[0:1]
	s_add_i32 s3, s7, 0x1a000
	s_mov_b32 m0, s3
	s_nop 0
	global_load_lds_dwordx4 v143, s[0:1]
	s_add_u32 s0, s16, 0x180
	s_addc_u32 s1, s17, 0
	s_add_i32 s3, s7, 0x8000
	s_mov_b32 m0, s3
	s_nop 0
	global_load_lds_dwordx4 v144, s[0:1]
	s_add_i32 s3, s7, 0xa000
	s_mov_b32 m0, s3
	s_nop 0
	global_load_lds_dwordx4 v143, s[0:1]
	s_add_u32 s0, s22, 0x180
	s_addc_u32 s1, s23, 0
	s_add_i32 s3, s7, 0x1c000
	s_mov_b32 m0, s3
	s_nop 0
	global_load_lds_dwordx4 v144, s[0:1]
	s_add_i32 s3, s7, 0x1e000
	s_mov_b32 m0, s3
	s_nop 0
	global_load_lds_dwordx4 v143, s[0:1]
	s_waitcnt vmcnt(8) lgkmcnt(0)
	s_setprio 1
	s_barrier
	v_mfma_f32_16x16x32_bf16 v[62:65], v[162:165], v[146:149], v[62:65]
	v_mfma_f32_16x16x32_bf16 v[58:61], v[162:165], v[154:157], v[58:61]
	v_mfma_f32_16x16x32_bf16 v[50:53], v[170:173], v[154:157], v[50:53]
	v_mfma_f32_16x16x32_bf16 v[54:57], v[170:173], v[146:149], v[54:57]
	v_mfma_f32_16x16x32_bf16 v[46:49], v[180:183], v[146:149], v[46:49]
	v_mfma_f32_16x16x32_bf16 v[42:45], v[180:183], v[154:157], v[42:45]
	v_mfma_f32_16x16x32_bf16 v[34:37], v[188:191], v[154:157], v[34:37]
	v_mfma_f32_16x16x32_bf16 v[38:41], v[188:191], v[146:149], v[38:41]
	v_mfma_f32_16x16x32_bf16 v[62:65], v[166:169], v[150:153], v[62:65]
	v_mfma_f32_16x16x32_bf16 v[58:61], v[166:169], v[158:161], v[58:61]
	v_mfma_f32_16x16x32_bf16 v[50:53], v[174:177], v[158:161], v[50:53]
	v_mfma_f32_16x16x32_bf16 v[54:57], v[174:177], v[150:153], v[54:57]
	v_mfma_f32_16x16x32_bf16 v[46:49], v[184:187], v[150:153], v[46:49]
	v_mfma_f32_16x16x32_bf16 v[42:45], v[184:187], v[158:161], v[42:45]
	v_mfma_f32_16x16x32_bf16 v[34:37], v[192:195], v[158:161], v[34:37]
	v_mfma_f32_16x16x32_bf16 v[38:41], v[192:195], v[150:153], v[38:41]
	v_mfma_f32_16x16x32_bf16 v[30:33], v[162:165], v[196:199], v[30:33]
	v_mfma_f32_16x16x32_bf16 v[26:29], v[162:165], v[204:207], v[26:29]
	v_mfma_f32_16x16x32_bf16 v[18:21], v[170:173], v[204:207], v[18:21]
	v_mfma_f32_16x16x32_bf16 v[22:25], v[170:173], v[196:199], v[22:25]
	v_mfma_f32_16x16x32_bf16 v[14:17], v[180:183], v[196:199], v[14:17]
	v_mfma_f32_16x16x32_bf16 v[10:13], v[180:183], v[204:207], v[10:13]
	v_mfma_f32_16x16x32_bf16 v[2:5], v[188:191], v[204:207], v[2:5]
	v_mfma_f32_16x16x32_bf16 v[6:9], v[188:191], v[196:199], v[6:9]
	v_mfma_f32_16x16x32_bf16 v[30:33], v[166:169], v[200:203], v[30:33]
	v_mfma_f32_16x16x32_bf16 v[26:29], v[166:169], v[208:211], v[26:29]
	v_mfma_f32_16x16x32_bf16 v[18:21], v[174:177], v[208:211], v[18:21]
	v_mfma_f32_16x16x32_bf16 v[22:25], v[174:177], v[200:203], v[22:25]
	v_mfma_f32_16x16x32_bf16 v[14:17], v[184:187], v[200:203], v[14:17]
	v_mfma_f32_16x16x32_bf16 v[10:13], v[184:187], v[208:211], v[10:13]
	v_mfma_f32_16x16x32_bf16 v[2:5], v[192:195], v[208:211], v[2:5]
	v_mfma_f32_16x16x32_bf16 v[6:9], v[192:195], v[200:203], v[6:9]
	s_barrier
; #define WAIT_V(n) asm volatile("s_waitcnt vmcnt(" #n ")" ::: "memory")
; #define WAIT_L(n) asm volatile("s_waitcnt lgkmcnt(" #n ")" ::: "memory")
; #define BAR __builtin_amdgcn_s_barrier()
; #define SCHED __builtin_amdgcn_sched_barrier(0)
; #define STG_A(b, h, kt) stage_half_s(lds0 + ((b) * 2 + (h)) * HT_B, ((h) ? A1 : Ap) + (kt) * BK, off0, off1)
; #define STG_B(b, h, kt) stage_half_s(lds0 + (4 + (b) * 2 + (h)) * HT_B, ((h) ? B1p : Bp) + (kt) * BK, off0, off1)
; #define STG_A(b, h, kt) stage_half_s(lds0 + ((b) * 2 + (h)) * HT_B, ((h) ? A1 : Ap) + (kt) * BK, off0, off1)
; #define STG_B(b, h, kt) stage_half_s(lds0 + (4 + (b) * 2 + (h)) * HT_B, ((h) ? B1p : Bp) + (kt) * BK, off0, off1)
; #define LDA8(b, h) _Pragma("unroll") for (int m = 0; m < 4; ++m) _Pragma("unroll") for (int k = 0; k < 2; ++k) \
;     At[m][k] = *(const bf16x8*)(SA_(shm, b, h) + abase + (m * 2 + k) * 1024)
; #define LDB8(dst, b, h) _Pragma("unroll") for (int n = 0; n < 2; ++n) _Pragma("unroll") for (int k = 0; k < 2; ++k) \
;     dst[n][k] = *(const bf16x8*)(SB_(shm, b, h) + bbase + (n * 2 + k) * 1024)
; template <bool HS>
; __device__ __forceinline__ void gemm_tile8(const u16* __restrict__ Ap, const u16* __restrict__ Bp, int K,
;                                            f32x4 (&acc)[2][2][4][2], char* shm, const int tid, const float* hsr = nullptr) {
;     ...
;     LDB8(B0, 0, 0); SCHED; LDA8(0, 0); STG_A(1, 1, t + 1);
;     WAIT_L(8); BAR; WAIT_L(0); MMA8(0, 0, B0); BAR; SCHED;
;     LDB8(B1, 0, 1); STG_B(0, 0, t + 2);
;     BAR; WAIT_L(0); MMA8(0, 1, B1); BAR;
;     LDA8(0, 1); STG_A(0, 0, t + 2);
;     BAR; WAIT_L(0); MMA8(1, 0, B0); BAR; SCHED;
;     STG_B(0, 1, t + 2);
;     WAIT_V(6); BAR; MMA8(1, 1, B1); BAR;
;     LDB8(B0, 1, 0); SCHED; LDA8(1, 0); STG_A(0, 1, t + 2);
;     WAIT_L(8); BAR; WAIT_L(0); MMA8(0, 0, B0); BAR; SCHED;
;     LDB8(B1, 1, 1); STG_B(1, 0, t + 3);
;     BAR; WAIT_L(0); MMA8(0, 1, B1); BAR;
;     LDA8(1, 1); STG_A(1, 0, t + 3);
;     BAR; WAIT_L(0); MMA8(1, 0, B0); BAR; SCHED;
;     STG_B(1, 1, t + 3);
;     WAIT_V(6); BAR; MMA8(1, 1, B1); BAR;
;   }
;   { LDB8(B0, 0, 0); LDA8(0, 0); STG_A(1, 1, nt - 1);
;     BAR; WAIT_L(0); MMA8(0, 0, B0); BAR;
;     LDB8(B1, 0, 1); BAR; WAIT_L(0); MMA8(0, 1, B1); BAR;
;     LDA8(0, 1); WAIT_V(4); BAR; WAIT_L(0); MMA8(1, 0, B0); MMA8(1, 1, B1); BAR; }
	s_setprio 0
	s_add_u32 s16, s16, 0x100
	s_addc_u32 s17, s17, 0
	s_add_u32 s18, s18, 0x100
	s_addc_u32 s19, s19, 0
	s_add_u32 s20, s20, 0x100
	s_addc_u32 s21, s21, 0
	s_add_u32 s22, s22, 0x100
	s_addc_u32 s23, s23, 0
	s_sub_i32 s14, s14, 1
	s_cmp_lg_u32 s14, 0
	s_cbranch_scc1 .Lk_ffn_in
	ds_read_b128 v[146:149], v244
	ds_read_b128 v[150:153], v244 offset:1024
	ds_read_b128 v[154:157], v244 offset:2048
	ds_read_b128 v[158:161], v244 offset:3072
	ds_read_b128 v[162:165], v142
	ds_read_b128 v[166:169], v142 offset:1024
	ds_read_b128 v[170:173], v142 offset:2048
	ds_read_b128 v[174:177], v142 offset:3072
	ds_read_b128 v[180:183], v142 offset:4096
	ds_read_b128 v[184:187], v142 offset:5120
	ds_read_b128 v[188:191], v142 offset:6144
	ds_read_b128 v[192:195], v142 offset:7168
	ds_read_b128 v[196:199], v245
	ds_read_b128 v[200:203], v245 offset:1024
	ds_read_b128 v[204:207], v245 offset:2048
	ds_read_b128 v[208:211], v245 offset:3072
	s_add_u32 s0, s18, 0x80
	s_addc_u32 s1, s19, 0
	s_add_i32 s3, s7, 0xc000
	s_mov_b32 m0, s3
	s_nop 0
	global_load_lds_dwordx4 v144, s[0:1]
	s_add_i32 s3, s7, 0xe000
	s_mov_b32 m0, s3
	s_nop 0
	global_load_lds_dwordx4 v143, s[0:1]
	s_waitcnt vmcnt(8) lgkmcnt(0)
	s_setprio 1
	s_barrier
	v_mfma_f32_16x16x32_bf16 v[126:129], v[162:165], v[146:149], v[126:129]
	v_mfma_f32_16x16x32_bf16 v[122:125], v[162:165], v[154:157], v[122:125]
	v_mfma_f32_16x16x32_bf16 v[114:117], v[170:173], v[154:157], v[114:117]
	v_mfma_f32_16x16x32_bf16 v[118:121], v[170:173], v[146:149], v[118:121]
	v_mfma_f32_16x16x32_bf16 v[110:113], v[180:183], v[146:149], v[110:113]
	v_mfma_f32_16x16x32_bf16 v[106:109], v[180:183], v[154:157], v[106:109]
	v_mfma_f32_16x16x32_bf16 v[98:101], v[188:191], v[154:157], v[98:101]
	v_mfma_f32_16x16x32_bf16 v[102:105], v[188:191], v[146:149], v[102:105]
	v_mfma_f32_16x16x32_bf16 v[126:129], v[166:169], v[150:153], v[126:129]
	v_mfma_f32_16x16x32_bf16 v[122:125], v[166:169], v[158:161], v[122:125]
	v_mfma_f32_16x16x32_bf16 v[114:117], v[174:177], v[158:161], v[114:117]
	v_mfma_f32_16x16x32_bf16 v[118:121], v[174:177], v[150:153], v[118:121]
	v_mfma_f32_16x16x32_bf16 v[110:113], v[184:187], v[150:153], v[110:113]
	v_mfma_f32_16x16x32_bf16 v[106:109], v[184:187], v[158:161], v[106:109]
	v_mfma_f32_16x16x32_bf16 v[98:101], v[192:195], v[158:161], v[98:101]
	v_mfma_f32_16x16x32_bf16 v[102:105], v[192:195], v[150:153], v[102:105]
	v_mfma_f32_16x16x32_bf16 v[94:97], v[162:165], v[196:199], v[94:97]
	v_mfma_f32_16x16x32_bf16 v[90:93], v[162:165], v[204:207], v[90:93]
	v_mfma_f32_16x16x32_bf16 v[82:85], v[170:173], v[204:207], v[82:85]
	v_mfma_f32_16x16x32_bf16 v[86:89], v[170:173], v[196:199], v[86:89]
	v_mfma_f32_16x16x32_bf16 v[78:81], v[180:183], v[196:199], v[78:81]
	v_mfma_f32_16x16x32_bf16 v[74:77], v[180:183], v[204:207], v[74:77]
	v_mfma_f32_16x16x32_bf16 v[66:69], v[188:191], v[204:207], v[66:69]
	v_mfma_f32_16x16x32_bf16 v[70:73], v[188:191], v[196:199], v[70:73]
	v_mfma_f32_16x16x32_bf16 v[94:97], v[166:169], v[200:203], v[94:97]
	v_mfma_f32_16x16x32_bf16 v[90:93], v[166:169], v[208:211], v[90:93]
	v_mfma_f32_16x16x32_bf16 v[82:85], v[174:177], v[208:211], v[82:85]
	v_mfma_f32_16x16x32_bf16 v[86:89], v[174:177], v[200:203], v[86:89]
	v_mfma_f32_16x16x32_bf16 v[78:81], v[184:187], v[200:203], v[78:81]
	v_mfma_f32_16x16x32_bf16 v[74:77], v[184:187], v[208:211], v[74:77]
	v_mfma_f32_16x16x32_bf16 v[66:69], v[192:195], v[208:211], v[66:69]
	v_mfma_f32_16x16x32_bf16 v[70:73], v[192:195], v[200:203], v[70:73]
	s_barrier
	s_setprio 0
	ds_read_b128 v[162:165], v142 offset:16384
	ds_read_b128 v[166:169], v142 offset:17408
	ds_read_b128 v[170:173], v142 offset:18432
	ds_read_b128 v[174:177], v142 offset:19456
	ds_read_b128 v[180:183], v142 offset:20480
	ds_read_b128 v[184:187], v142 offset:21504
	ds_read_b128 v[188:191], v142 offset:22528
	ds_read_b128 v[192:195], v142 offset:23552
	s_waitcnt vmcnt(2) lgkmcnt(0)
	s_setprio 1
	s_barrier
	v_mfma_f32_16x16x32_bf16 v[62:65], v[162:165], v[146:149], v[62:65]
	v_mfma_f32_16x16x32_bf16 v[58:61], v[162:165], v[154:157], v[58:61]
	v_mfma_f32_16x16x32_bf16 v[50:53], v[170:173], v[154:157], v[50:53]
	v_mfma_f32_16x16x32_bf16 v[54:57], v[170:173], v[146:149], v[54:57]
	v_mfma_f32_16x16x32_bf16 v[46:49], v[180:183], v[146:149], v[46:49]
	v_mfma_f32_16x16x32_bf16 v[42:45], v[180:183], v[154:157], v[42:45]
	v_mfma_f32_16x16x32_bf16 v[34:37], v[188:191], v[154:157], v[34:37]
	v_mfma_f32_16x16x32_bf16 v[38:41], v[188:191], v[146:149], v[38:41]
	v_mfma_f32_16x16x32_bf16 v[62:65], v[166:169], v[150:153], v[62:65]
	v_mfma_f32_16x16x32_bf16 v[58:61], v[166:169], v[158:161], v[58:61]
	v_mfma_f32_16x16x32_bf16 v[50:53], v[174:177], v[158:161], v[50:53]
	v_mfma_f32_16x16x32_bf16 v[54:57], v[174:177], v[150:153], v[54:57]
	v_mfma_f32_16x16x32_bf16 v[46:49], v[184:187], v[150:153], v[46:49]
	v_mfma_f32_16x16x32_bf16 v[42:45], v[184:187], v[158:161], v[42:45]
	v_mfma_f32_16x16x32_bf16 v[34:37], v[192:195], v[158:161], v[34:37]
	v_mfma_f32_16x16x32_bf16 v[38:41], v[192:195], v[150:153], v[38:41]
	v_mfma_f32_16x16x32_bf16 v[30:33], v[162:165], v[196:199], v[30:33]
	v_mfma_f32_16x16x32_bf16 v[26:29], v[162:165], v[204:207], v[26:29]
	v_mfma_f32_16x16x32_bf16 v[18:21], v[170:173], v[204:207], v[18:21]
	v_mfma_f32_16x16x32_bf16 v[22:25], v[170:173], v[196:199], v[22:25]
	v_mfma_f32_16x16x32_bf16 v[14:17], v[180:183], v[196:199], v[14:17]
	v_mfma_f32_16x16x32_bf16 v[10:13], v[180:183], v[204:207], v[10:13]
	v_mfma_f32_16x16x32_bf16 v[2:5], v[188:191], v[204:207], v[2:5]
	v_mfma_f32_16x16x32_bf16 v[6:9], v[188:191], v[196:199], v[6:9]
	v_mfma_f32_16x16x32_bf16 v[30:33], v[166:169], v[200:203], v[30:33]
	v_mfma_f32_16x16x32_bf16 v[26:29], v[166:169], v[208:211], v[26:29]
	v_mfma_f32_16x16x32_bf16 v[18:21], v[174:177], v[208:211], v[18:21]
	v_mfma_f32_16x16x32_bf16 v[22:25], v[174:177], v[200:203], v[22:25]
	v_mfma_f32_16x16x32_bf16 v[14:17], v[184:187], v[200:203], v[14:17]
	v_mfma_f32_16x16x32_bf16 v[10:13], v[184:187], v[208:211], v[10:13]
	v_mfma_f32_16x16x32_bf16 v[2:5], v[192:195], v[208:211], v[2:5]
	v_mfma_f32_16x16x32_bf16 v[6:9], v[192:195], v[200:203], v[6:9]
	s_barrier
; #define WAIT_V(n) asm volatile("s_waitcnt vmcnt(" #n ")" ::: "memory")
; #define WAIT_L(n) asm volatile("s_waitcnt lgkmcnt(" #n ")" ::: "memory")
; #define BAR __builtin_amdgcn_s_barrier()
; #define STG_A(b, h, kt) stage_half_s(lds0 + ((b) * 2 + (h)) * HT_B, ((h) ? A1 : Ap) + (kt) * BK, off0, off1)
; #define STG_A(b, h, kt) stage_half_s(lds0 + ((b) * 2 + (h)) * HT_B, ((h) ? A1 : Ap) + (kt) * BK, off0, off1)
; #define LDA8(b, h) _Pragma("unroll") for (int m = 0; m < 4; ++m) _Pragma("unroll") for (int k = 0; k < 2; ++k) \
;     At[m][k] = *(const bf16x8*)(SA_(shm, b, h) + abase + (m * 2 + k) * 1024)
; #define LDB8(dst, b, h) _Pragma("unroll") for (int n = 0; n < 2; ++n) _Pragma("unroll") for (int k = 0; k < 2; ++k) \
;     dst[n][k] = *(const bf16x8*)(SB_(shm, b, h) + bbase + (n * 2 + k) * 1024)
; #define MMA8(ai, bj, Bx) do { __builtin_amdgcn_s_setprio(1); \
;     _Pragma("unroll") for (int m = 0; m < 4; ++m) _Pragma("unroll") for (int n = 0; n < 2; ++n) _Pragma("unroll") for (int k = 0; k < 2; ++k) \
;       acc[ai][bj][m][n] = __builtin_amdgcn_mfma_f32_16x16x32_bf16(At[m][k], Bx[n][k], acc[ai][bj][m][n], 0, 0, 0); \
;     __builtin_amdgcn_s_setprio(0); } while (0)
; template <bool HS>
; __device__ __forceinline__ void gemm_tile8(const u16* __restrict__ Ap, const u16* __restrict__ Bp, int K,
;                                            f32x4 (&acc)[2][2][4][2], char* shm, const int tid, const float* hsr = nullptr) {
;     ...
;   { LDB8(B0, 0, 0); LDA8(0, 0); STG_A(1, 1, nt - 1);
;     BAR; WAIT_L(0); MMA8(0, 0, B0); BAR;
;     LDB8(B1, 0, 1); BAR; WAIT_L(0); MMA8(0, 1, B1); BAR;
;     LDA8(0, 1); WAIT_V(4); BAR; WAIT_L(0); MMA8(1, 0, B0); MMA8(1, 1, B1); BAR; }
;   { LDB8(B0, 1, 0); LDA8(1, 0); WAIT_V(2); BAR; WAIT_L(0); MMA8(0, 0, B0); BAR;
;     LDB8(B1, 1, 1); WAIT_V(0); BAR; WAIT_L(0); MMA8(0, 1, B1); BAR;
;     LDA8(1, 1); BAR; WAIT_L(0); MMA8(1, 0, B0); MMA8(1, 1, B1); BAR; }
;   if (wr == 0) BAR;
	s_setprio 0
	ds_read_b128 v[146:149], v246
	ds_read_b128 v[150:153], v246 offset:1024
	ds_read_b128 v[154:157], v246 offset:2048
	ds_read_b128 v[158:161], v246 offset:3072
	ds_read_b128 v[162:165], v142 offset:32768
	ds_read_b128 v[166:169], v142 offset:33792
	ds_read_b128 v[170:173], v142 offset:34816
	ds_read_b128 v[174:177], v142 offset:35840
	ds_read_b128 v[180:183], v142 offset:36864
	ds_read_b128 v[184:187], v142 offset:37888
	ds_read_b128 v[188:191], v142 offset:38912
	ds_read_b128 v[192:195], v142 offset:39936
	ds_read_b128 v[196:199], v247
	ds_read_b128 v[200:203], v247 offset:1024
	ds_read_b128 v[204:207], v247 offset:2048
	ds_read_b128 v[208:211], v247 offset:3072
	s_waitcnt vmcnt(0) lgkmcnt(0)
	s_setprio 1
	s_barrier
	v_mfma_f32_16x16x32_bf16 v[126:129], v[162:165], v[146:149], v[126:129]
	v_mfma_f32_16x16x32_bf16 v[122:125], v[162:165], v[154:157], v[122:125]
	v_mfma_f32_16x16x32_bf16 v[114:117], v[170:173], v[154:157], v[114:117]
	v_mfma_f32_16x16x32_bf16 v[118:121], v[170:173], v[146:149], v[118:121]
	v_mfma_f32_16x16x32_bf16 v[110:113], v[180:183], v[146:149], v[110:113]
	v_mfma_f32_16x16x32_bf16 v[106:109], v[180:183], v[154:157], v[106:109]
	v_mfma_f32_16x16x32_bf16 v[98:101], v[188:191], v[154:157], v[98:101]
	v_mfma_f32_16x16x32_bf16 v[102:105], v[188:191], v[146:149], v[102:105]
	v_mfma_f32_16x16x32_bf16 v[126:129], v[166:169], v[150:153], v[126:129]
	v_mfma_f32_16x16x32_bf16 v[122:125], v[166:169], v[158:161], v[122:125]
	v_mfma_f32_16x16x32_bf16 v[114:117], v[174:177], v[158:161], v[114:117]
	v_mfma_f32_16x16x32_bf16 v[118:121], v[174:177], v[150:153], v[118:121]
	v_mfma_f32_16x16x32_bf16 v[110:113], v[184:187], v[150:153], v[110:113]
	v_mfma_f32_16x16x32_bf16 v[106:109], v[184:187], v[158:161], v[106:109]
	v_mfma_f32_16x16x32_bf16 v[98:101], v[192:195], v[158:161], v[98:101]
	v_mfma_f32_16x16x32_bf16 v[102:105], v[192:195], v[150:153], v[102:105]
	v_mfma_f32_16x16x32_bf16 v[94:97], v[162:165], v[196:199], v[94:97]
	v_mfma_f32_16x16x32_bf16 v[90:93], v[162:165], v[204:207], v[90:93]
	v_mfma_f32_16x16x32_bf16 v[82:85], v[170:173], v[204:207], v[82:85]
	v_mfma_f32_16x16x32_bf16 v[86:89], v[170:173], v[196:199], v[86:89]
	v_mfma_f32_16x16x32_bf16 v[78:81], v[180:183], v[196:199], v[78:81]
	v_mfma_f32_16x16x32_bf16 v[74:77], v[180:183], v[204:207], v[74:77]
	v_mfma_f32_16x16x32_bf16 v[66:69], v[188:191], v[204:207], v[66:69]
	v_mfma_f32_16x16x32_bf16 v[70:73], v[188:191], v[196:199], v[70:73]
	v_mfma_f32_16x16x32_bf16 v[94:97], v[166:169], v[200:203], v[94:97]
	v_mfma_f32_16x16x32_bf16 v[90:93], v[166:169], v[208:211], v[90:93]
	v_mfma_f32_16x16x32_bf16 v[82:85], v[174:177], v[208:211], v[82:85]
	v_mfma_f32_16x16x32_bf16 v[86:89], v[174:177], v[200:203], v[86:89]
	v_mfma_f32_16x16x32_bf16 v[78:81], v[184:187], v[200:203], v[78:81]
	v_mfma_f32_16x16x32_bf16 v[74:77], v[184:187], v[208:211], v[74:77]
	v_mfma_f32_16x16x32_bf16 v[66:69], v[192:195], v[208:211], v[66:69]
	v_mfma_f32_16x16x32_bf16 v[70:73], v[192:195], v[200:203], v[70:73]
	s_barrier
	s_setprio 0
	ds_read_b128 v[162:165], v142 offset:49152
	ds_read_b128 v[166:169], v142 offset:50176
	ds_read_b128 v[170:173], v142 offset:51200
	ds_read_b128 v[174:177], v142 offset:52224
	ds_read_b128 v[180:183], v142 offset:53248
	ds_read_b128 v[184:187], v142 offset:54272
	ds_read_b128 v[188:191], v142 offset:55296
	ds_read_b128 v[192:195], v142 offset:56320
	s_waitcnt lgkmcnt(0)
	s_setprio 1
	s_barrier
	v_mfma_f32_16x16x32_bf16 v[62:65], v[162:165], v[146:149], v[62:65]
	v_mfma_f32_16x16x32_bf16 v[58:61], v[162:165], v[154:157], v[58:61]
	v_mfma_f32_16x16x32_bf16 v[50:53], v[170:173], v[154:157], v[50:53]
	v_mfma_f32_16x16x32_bf16 v[54:57], v[170:173], v[146:149], v[54:57]
	v_mfma_f32_16x16x32_bf16 v[46:49], v[180:183], v[146:149], v[46:49]
	v_mfma_f32_16x16x32_bf16 v[42:45], v[180:183], v[154:157], v[42:45]
	v_mfma_f32_16x16x32_bf16 v[34:37], v[188:191], v[154:157], v[34:37]
	v_mfma_f32_16x16x32_bf16 v[38:41], v[188:191], v[146:149], v[38:41]
	v_mfma_f32_16x16x32_bf16 v[62:65], v[166:169], v[150:153], v[62:65]
	v_mfma_f32_16x16x32_bf16 v[58:61], v[166:169], v[158:161], v[58:61]
	v_mfma_f32_16x16x32_bf16 v[50:53], v[174:177], v[158:161], v[50:53]
	v_mfma_f32_16x16x32_bf16 v[54:57], v[174:177], v[150:153], v[54:57]
	v_mfma_f32_16x16x32_bf16 v[46:49], v[184:187], v[150:153], v[46:49]
	v_mfma_f32_16x16x32_bf16 v[42:45], v[184:187], v[158:161], v[42:45]
	v_mfma_f32_16x16x32_bf16 v[34:37], v[192:195], v[158:161], v[34:37]
	v_mfma_f32_16x16x32_bf16 v[38:41], v[192:195], v[150:153], v[38:41]
	v_mfma_f32_16x16x32_bf16 v[30:33], v[162:165], v[196:199], v[30:33]
	v_mfma_f32_16x16x32_bf16 v[26:29], v[162:165], v[204:207], v[26:29]
	v_mfma_f32_16x16x32_bf16 v[18:21], v[170:173], v[204:207], v[18:21]
	v_mfma_f32_16x16x32_bf16 v[22:25], v[170:173], v[196:199], v[22:25]
	v_mfma_f32_16x16x32_bf16 v[14:17], v[180:183], v[196:199], v[14:17]
	v_mfma_f32_16x16x32_bf16 v[10:13], v[180:183], v[204:207], v[10:13]
	v_mfma_f32_16x16x32_bf16 v[2:5], v[188:191], v[204:207], v[2:5]
	v_mfma_f32_16x16x32_bf16 v[6:9], v[188:191], v[196:199], v[6:9]
	v_mfma_f32_16x16x32_bf16 v[30:33], v[166:169], v[200:203], v[30:33]
	v_mfma_f32_16x16x32_bf16 v[26:29], v[166:169], v[208:211], v[26:29]
	v_mfma_f32_16x16x32_bf16 v[18:21], v[174:177], v[208:211], v[18:21]
	v_mfma_f32_16x16x32_bf16 v[22:25], v[174:177], v[200:203], v[22:25]
	v_mfma_f32_16x16x32_bf16 v[14:17], v[184:187], v[200:203], v[14:17]
	v_mfma_f32_16x16x32_bf16 v[10:13], v[184:187], v[208:211], v[10:13]
	v_mfma_f32_16x16x32_bf16 v[2:5], v[192:195], v[208:211], v[2:5]
	v_mfma_f32_16x16x32_bf16 v[6:9], v[192:195], v[200:203], v[6:9]
	s_setprio 0
	s_movk_i32 s0, 0x100
	v_cmp_gt_u32_e32 vcc, s0, v0
	s_barrier
	s_and_saveexec_b64 s[0:1], vcc
	s_cbranch_execz .LBB0_862
	s_barrier
